# P8 load balance: the last 512 tokens are processed one per block by its four waves (2 heads + 32 experts each, partial rows reduced through LDS) instead of as a fifth token on 512 waves
# speedup vs baseline: 1.0099x; 1.0060x over previous
.LBB0_917:
	s_or_b64 exec, exec, s[6:7]
	v_lshrrev_b32_e32 v3, 6, v204
	v_lshl_add_u32 v4, s2, 2, v3
	s_mov_b32 s89, s2
	s_load_dword s88, s[0:1], 0x120
	s_waitcnt lgkmcnt(0)
	s_cmp_eq_u32 s88, 0x200
	s_mov_b32 s87, 0x2200
	s_cselect_b32 s87, 0x2000, s87
	s_cselect_b32 s85, 1, 0
	s_mov_b32 s2, s87
	s_sub_u32 s87, s87, 1
	v_cmp_gt_i32_e32 vcc, s2, v4
	s_and_saveexec_b64 s[2:3], vcc
	s_cbranch_execz .LBB0_930
	v_and_b32_e32 v6, 32, v204
	s_add_u32 s74, s94, 0x1cb18000
	v_cmp_eq_u32_e64 s[8:9], 0, v6
	v_lshlrev_b32_e32 v6, 5, v0
	v_mov_b32_e32 v7, 0
	s_addc_u32 s75, s95, 0
	v_lshl_add_u64 v[8:9], s[94:95], 0, v[6:7]
	s_mov_b64 s[10:11], 0x13288000
	v_and_b32_e32 v6, 2, v204
	v_and_b32_e32 v10, 1, v204
	s_add_u32 s76, s94, 0x1cb08000
	v_lshl_add_u64 v[8:9], v[8:9], 0, s[10:11]
	v_cmp_ne_u32_e32 vcc, 0, v6
	v_cmp_eq_u32_e64 s[10:11], 0, v10
	v_and_b32_e32 v10, 4, v204
	s_addc_u32 s77, s95, 0
	s_xor_b64 s[12:13], vcc, s[10:11]
	v_cmp_ne_u32_e32 vcc, 0, v10
	v_cmp_eq_u32_e64 s[14:15], 0, v6
	v_and_b32_e32 v6, 8, v204
	v_lshlrev_b32_e32 v5, 10, v3
	v_and_b32_e32 v3, 16, v204
	s_xor_b64 s[16:17], vcc, s[14:15]
	s_xor_b64 s[18:19], vcc, s[10:11]
	v_cmp_ne_u32_e32 vcc, 0, v6
	v_cmp_eq_u32_e64 s[20:21], 0, v10
	v_cmp_eq_u32_e64 s[6:7], 0, v3
	s_xor_b64 s[22:23], vcc, s[20:21]
	s_xor_b64 s[24:25], vcc, s[14:15]
	s_xor_b64 s[26:27], vcc, s[10:11]
	v_cmp_ne_u32_e32 vcc, 0, v3
	v_mbcnt_lo_u32_b32 v3, -1, 0
	v_mbcnt_hi_u32_b32 v3, -1, v3
	s_load_dword s33, s[0:1], 0x120
	v_and_b32_e32 v166, 64, v3
	v_cndmask_b32_e64 v2, v2, 0, s[4:5]
	v_cmp_eq_u32_e64 s[28:29], 0, v6
	v_or_b32_e32 v2, v166, v2
	v_lshlrev_b32_e32 v6, 3, v0
	v_lshlrev_b32_e32 v167, 2, v2
	v_cndmask_b32_e64 v1, v1, 0, s[4:5]
	v_lshl_add_u64 v[2:3], s[94:95], 0, v[6:7]
	s_mov_b64 s[60:61], 0x8000
	v_lshlrev_b32_e32 v6, 6, v0
	v_cmp_lt_u32_e64 s[40:41], 31, v0
	v_or_b32_e32 v1, v166, v1
	v_lshl_add_u64 v[10:11], v[2:3], 0, s[60:61]
	s_mov_b64 s[60:61], 0x4008000
	v_lshl_add_u64 v[14:15], s[92:93], 0, v[6:7]
	v_lshlrev_b32_e32 v6, 2, v0
	v_add_u32_e32 v169, 32, v5
	s_movk_i32 s78, 0x7f
	v_xor_b32_e32 v164, 0x7f, v0
	v_xor_b32_e32 v165, 63, v0
	s_xor_b64 s[30:31], vcc, s[28:29]
	s_xor_b64 s[34:35], vcc, s[20:21]
	s_xor_b64 s[36:37], vcc, s[14:15]
	s_xor_b64 s[38:39], vcc, s[10:11]
	s_xor_b64 s[42:43], s[40:41], s[6:7]
	s_xor_b64 s[44:45], s[40:41], s[28:29]
	s_xor_b64 s[46:47], s[40:41], s[20:21]
	s_xor_b64 s[48:49], s[40:41], s[14:15]
	s_xor_b64 s[50:51], s[40:41], s[10:11]
	v_cmp_gt_u32_e64 s[52:53], 32, v0
	v_lshlrev_b32_e32 v168, 2, v1
	v_cmp_gt_u32_e64 s[54:55], 16, v0
	v_lshl_add_u64 v[12:13], v[2:3], 0, s[60:61]
	s_waitcnt lgkmcnt(0)
	s_lshl_b32 s79, s33, 2
	v_add_u32_e32 v170, v169, v6
	v_lshl_add_u64 v[16:17], s[94:95], 0, v[6:7]
	v_add_u32_e32 v6, 16, v169
	s_mov_b64 s[60:61], 0
	s_mov_b64 s[62:63], 0x1000
	s_movk_i32 s80, 0x1000
	v_mov_b32_e32 v171, 0x358637bd
	s_mov_b32 s81, 0x800000
	s_mov_b32 s82, 0xc0e00000
	s_mov_b32 s83, 0x3e6d3388
	v_mov_b32_e32 v172, 0xbf3a00e3
	s_mov_b32 s84, s87
	v_bfrev_b32_e32 v173, 1
	v_mov_b32_e32 v174, 0x40e00000
	s_branch .LBB0_920

.LBB0_930:
	s_or_b64 exec, exec, s[2:3]
	s_cmp_eq_u32 s85, 1
	s_cbranch_scc0 .Lpb_skip
	s_add_u32 s90, s89, 0x2000
	v_mov_b32_e32 v4, s90
	v_lshrrev_b32_e32 v0, 6, v204
	s_nop 0
	v_readfirstlane_b32 s91, v0
	s_lshl_b32 s88, s91, 11
	s_add_u32 s87, s88, 0x800
	v_mov_b32_e32 v92, 0x7fffffff
	v_cndmask_b32_e64 v100, v173, v92, s[12:13]
	v_cndmask_b32_e64 v101, v173, v92, s[16:17]
	v_cndmask_b32_e64 v102, v173, v92, s[18:19]
	v_cndmask_b32_e64 v103, v173, v92, s[22:23]
	v_cndmask_b32_e64 v104, v173, v92, s[24:25]
	v_cndmask_b32_e64 v105, v173, v92, s[26:27]
	v_cndmask_b32_e64 v106, v173, v92, s[30:31]
	v_cndmask_b32_e64 v107, v173, v92, s[34:35]
	v_cndmask_b32_e64 v108, v173, v92, s[36:37]
	v_cndmask_b32_e64 v109, v173, v92, s[38:39]
	v_cndmask_b32_e64 v110, v173, v92, s[42:43]
	v_cndmask_b32_e64 v111, v173, v92, s[44:45]
	v_cndmask_b32_e64 v112, v173, v92, s[46:47]
	v_cndmask_b32_e64 v113, v173, v92, s[48:49]
	v_cndmask_b32_e64 v114, v173, v92, s[50:51]
	v_cndmask_b32_e64 v115, v92, v173, s[40:41]
	v_cndmask_b32_e64 v116, v173, v92, s[40:41]
	v_cndmask_b32_e64 v117, v173, v92, s[6:7]
	v_cndmask_b32_e64 v118, v92, v173, s[6:7]
	v_cndmask_b32_e64 v119, v173, v92, s[28:29]
	v_cndmask_b32_e64 v120, v92, v173, s[28:29]
	v_cndmask_b32_e64 v121, v173, v92, s[20:21]
	v_cndmask_b32_e64 v122, v92, v173, s[20:21]
	v_cndmask_b32_e64 v123, v173, v92, s[14:15]
	v_cndmask_b32_e64 v124, v92, v173, s[14:15]
	v_cndmask_b32_e64 v125, v173, v92, s[10:11]
	v_cndmask_b32_e64 v126, v92, v173, s[10:11]
	v_cndmask_b32_e64 v127, v173, v92, s[52:53]
	v_ashrrev_i32_e32 v5, 31, v4
	v_lshlrev_b64 v[0:1], 13, v[4:5]
	v_lshl_add_u64 v[18:19], v[14:15], 0, v[0:1]
	global_load_dwordx4 v[24:27], v[18:19], off offset:16
	global_load_dwordx4 v[28:31], v[18:19], off
	global_load_dwordx4 v[32:35], v[18:19], off offset:48
	global_load_dwordx4 v[60:63], v[18:19], off offset:32
	v_lshlrev_b64 v[2:3], 12, v[4:5]
	v_add_co_u32_e32 v20, vcc, s80, v18
	v_lshl_add_u64 v[2:3], v[8:9], 0, v[2:3]
	s_nop 0
	v_addc_co_u32_e32 v21, vcc, 0, v19, vcc
	global_load_dwordx4 v[36:39], v[2:3], off
	global_load_dwordx4 v[64:67], v[2:3], off offset:16
	global_load_dwordx4 v[68:71], v[2:3], off offset:2048
	v_lshl_add_u64 v[22:23], v[18:19], 0, s[62:63]
	global_load_dwordx4 v[72:75], v[20:21], off
	global_load_dwordx4 v[76:79], v[22:23], off offset:16
	global_load_dwordx4 v[80:83], v[22:23], off offset:32
	global_load_dwordx4 v[84:87], v[22:23], off offset:48
	global_load_dwordx4 v[88:91], v[2:3], off offset:2064
	v_lshl_add_u64 v[0:1], v[16:17], 0, v[0:1]
	s_mov_b32 s64, s88
	s_mov_b32 s65, 0
	s_waitcnt vmcnt(11)
	v_mul_f32_e32 v40, v25, v25
	s_waitcnt vmcnt(10)
	v_mul_f32_e32 v5, v29, v29
	v_fmac_f32_e32 v5, v28, v28
	s_waitcnt vmcnt(8)
	v_mul_f32_e32 v42, v61, v61
	v_fmac_f32_e32 v40, v24, v24
	v_mul_f32_e32 v44, v33, v33
	v_fmac_f32_e32 v42, v60, v60
	v_fmac_f32_e32 v5, v30, v30
	v_fmac_f32_e32 v40, v26, v26
	s_waitcnt vmcnt(3)
	v_mov_b32_e32 v3, v76
	v_mov_b32_e32 v76, v73
	v_fmac_f32_e32 v44, v32, v32
	v_mov_b32_e32 v2, v72
	v_fmac_f32_e32 v42, v62, v62
	v_pk_mul_f32 v[60:61], v[76:77], v[76:77]
	v_fmac_f32_e32 v5, v31, v31
	v_fmac_f32_e32 v40, v27, v27
	v_mov_b32_e32 v24, v74
	v_mov_b32_e32 v25, v78
	s_waitcnt vmcnt(1)
	v_mov_b32_e32 v29, v84
	v_mov_b32_e32 v84, v81
	v_fmac_f32_e32 v44, v34, v34
	v_fmac_f32_e32 v42, v63, v63
	v_pk_fma_f32 v[2:3], v[2:3], v[2:3], v[60:61]
	v_add_f32_e32 v5, v5, v40
	v_lshlrev_b32_e32 v50, 16, v64
	v_and_b32_e32 v49, 0xffff0000, v64
	v_lshlrev_b32_e32 v48, 16, v65
	v_and_b32_e32 v47, 0xffff0000, v65
	v_mov_b32_e32 v78, v75
	v_mov_b32_e32 v28, v80
	v_pk_mul_f32 v[64:65], v[84:85], v[84:85]
	v_fmac_f32_e32 v44, v35, v35
	v_pk_fma_f32 v[2:3], v[24:25], v[24:25], v[2:3]
	v_add_f32_e32 v5, v5, v42
	v_mov_b32_e32 v32, v82
	v_mov_b32_e32 v33, v86
	v_pk_fma_f32 v[26:27], v[28:29], v[28:29], v[64:65]
	v_pk_fma_f32 v[2:3], v[78:79], v[78:79], v[2:3]
	v_add_f32_e32 v5, v5, v44
	v_mov_b32_e32 v86, v83
	v_pk_fma_f32 v[24:25], v[32:33], v[32:33], v[26:27]
	v_add_f32_e32 v2, v5, v2
	v_pk_fma_f32 v[24:25], v[86:87], v[86:87], v[24:25]
	v_add_f32_e32 v2, v2, v3
	v_add_f32_e32 v2, v2, v24
	v_add_f32_e32 v2, v2, v25
	v_mov_b32_e32 v3, v2
	v_mov_b32_e32 v5, v2
	s_nop 1
	v_permlane32_swap_b32_e32 v3, v5
	v_cndmask_b32_e64 v3, v3, v5, s[8:9]
	v_add_f32_e32 v2, v2, v3
	v_mov_b32_e32 v3, v2
	v_mov_b32_e32 v5, v2
	s_nop 1
	v_permlane16_swap_b32_e32 v3, v5
	v_cndmask_b32_e64 v3, v3, v5, s[6:7]
	v_add_f32_e32 v2, v2, v3
	v_lshlrev_b32_e32 v58, 16, v36
	v_and_b32_e32 v57, 0xffff0000, v36
	v_add_f32_dpp v2, v2, v2 row_ror:8 row_mask:0xf bank_mask:0xf bound_ctrl:1
	v_lshlrev_b32_e32 v56, 16, v37
	v_and_b32_e32 v55, 0xffff0000, v37
	v_mov_b32_dpp v3, v2 row_half_mirror row_mask:0xf bank_mask:0xf bound_ctrl:1
	v_max3_f32 v36, |v58|, 0, |v57|
	v_lshlrev_b32_e32 v54, 16, v38
	v_add_f32_dpp v2, v3, v2 quad_perm:[3,2,1,0] row_mask:0xf bank_mask:0xf bound_ctrl:1
	v_and_b32_e32 v53, 0xffff0000, v38
	v_max3_f32 v30, v36, |v56|, |v55|
	v_add_f32_dpp v2, v2, v2 quad_perm:[2,3,0,1] row_mask:0xf bank_mask:0xf bound_ctrl:1
	v_lshlrev_b32_e32 v52, 16, v39
	v_and_b32_e32 v51, 0xffff0000, v39
	v_max3_f32 v28, v30, |v54|, |v53|
	v_add_f32_dpp v2, v2, v2 quad_perm:[1,0,3,2] row_mask:0xf bank_mask:0xf bound_ctrl:1
	v_max3_f32 v26, v28, |v52|, |v51|
	v_fmamk_f32 v2, v2, 0x3a000000, v171
	v_max3_f32 v26, v26, |v50|, |v49|
	v_mul_f32_e32 v3, 0x4b800000, v2
	v_cmp_gt_f32_e32 vcc, s81, v2
	v_lshlrev_b32_e32 v46, 16, v66
	v_and_b32_e32 v45, 0xffff0000, v66
	v_cndmask_b32_e32 v2, v2, v3, vcc
	v_max3_f32 v3, v26, |v48|, |v47|
	v_lshlrev_b32_e32 v43, 16, v67
	v_and_b32_e32 v41, 0xffff0000, v67
	v_max3_f32 v3, v3, |v46|, |v45|
	v_lshlrev_b32_e32 v39, 16, v68
	v_and_b32_e32 v37, 0xffff0000, v68
	v_max3_f32 v3, v3, |v43|, |v41|
	v_lshlrev_b32_e32 v44, 16, v69
	v_and_b32_e32 v42, 0xffff0000, v69
	v_max3_f32 v3, v3, |v39|, |v37|
	v_lshlrev_b32_e32 v40, 16, v70
	v_and_b32_e32 v38, 0xffff0000, v70
	v_max3_f32 v3, v3, |v44|, |v42|
	v_lshlrev_b32_e32 v36, 16, v71
	v_and_b32_e32 v35, 0xffff0000, v71
	v_max3_f32 v3, v3, |v40|, |v38|
	s_waitcnt vmcnt(0)
	v_lshlrev_b32_e32 v34, 16, v88
	v_and_b32_e32 v33, 0xffff0000, v88
	v_max3_f32 v3, v3, |v36|, |v35|
	v_lshlrev_b32_e32 v32, 16, v89
	v_and_b32_e32 v31, 0xffff0000, v89
	v_max3_f32 v3, v3, |v34|, |v33|
	v_lshlrev_b32_e32 v30, 16, v90
	v_and_b32_e32 v29, 0xffff0000, v90
	v_max3_f32 v3, v3, |v32|, |v31|
	v_lshlrev_b32_e32 v25, 16, v91
	v_and_b32_e32 v5, 0xffff0000, v91
	v_max3_f32 v3, v3, |v30|, |v29|
	v_max3_f32 v3, v3, |v25|, |v5|
	v_mov_b32_e32 v26, v3
	v_mov_b32_e32 v27, v3
	s_nop 1
	v_permlane32_swap_b32_e32 v26, v27
	v_cndmask_b32_e64 v26, v26, v27, s[8:9]
	v_max_f32_e32 v26, v26, v26
	v_max_f32_e32 v3, v3, v26
	v_mov_b32_e32 v26, v3
	v_mov_b32_e32 v27, v3
	s_nop 1
	v_permlane16_swap_b32_e32 v26, v27
	v_cndmask_b32_e64 v26, v26, v27, s[6:7]
	v_max_f32_e32 v26, v26, v26
	v_max_f32_e32 v3, v3, v26
	v_rsq_f32_e32 v2, v2
	v_mov_b32_e32 v28, v170
	s_lshr_b32 s96, s88, 4
	v_add_u32_e32 v28, s96, v28
	v_mov_b32_dpp v26, v3 row_ror:8 row_mask:0xf bank_mask:0xf bound_ctrl:1
	v_max_f32_e32 v26, v26, v26
	v_max_f32_e32 v3, v3, v26
	v_mul_f32_e32 v24, 0x45800000, v2
	v_cndmask_b32_e32 v24, v2, v24, vcc
	v_mov_b32_dpp v26, v3 row_half_mirror row_mask:0xf bank_mask:0xf bound_ctrl:1
	s_nop 1
	v_mov_b32_dpp v26, v26 quad_perm:[3,2,1,0] row_mask:0xf bank_mask:0xf bound_ctrl:1
	v_max_f32_e32 v26, v26, v26
	v_max_f32_e32 v3, v3, v26
	s_nop 1
	v_mov_b32_dpp v26, v3 quad_perm:[2,3,0,1] row_mask:0xf bank_mask:0xf bound_ctrl:1
	v_max_f32_e32 v26, v26, v26
	v_max_f32_e32 v26, v3, v26
	s_nop 1
	v_mov_b32_dpp v27, v26 quad_perm:[1,0,3,2] row_mask:0xf bank_mask:0xf bound_ctrl:1
	s_branch .Lpb_922
.Lpb_921:
	s_or_b64 exec, exec, s[66:67]
	s_add_u32 s64, s64, 0x800
	s_addc_u32 s65, s65, 0
	s_cmp_eq_u32 s64, s87
	v_add_u32_e32 v28, 0x80, v28
	s_cbranch_scc1 .Lpb_926

.Lpb_926:
	s_waitcnt lgkmcnt(0)
	v_and_b32_e32 v0, 63, v204
	v_lshlrev_b32_e32 v1, 12, v4
	v_lshl_add_u32 v1, v0, 5, v1
	v_add_u32_e32 v1, 0x13288000, v1
	global_load_dwordx4 v[64:67], v1, s[94:95]
	global_load_dwordx4 v[68:71], v1, s[94:95] offset:16
	global_load_dwordx4 v[72:75], v1, s[94:95] offset:2048
	global_load_dwordx4 v[76:79], v1, s[94:95] offset:2064
	ds_read_b32 v80, v170
	ds_read_b32 v81, v170 offset:256
	ds_read_b32 v82, v170 offset:512
	ds_read_b32 v83, v170 offset:768
	v_lshlrev_b32_e32 v28, 3, v0
	v_add_u32_e32 v29, 0x4008000, v28
	v_add_u32_e32 v28, 0x8000, v28
	s_waitcnt lgkmcnt(0)
	v_lshlrev_b32_e32 v2, 2, v80
	v_lshlrev_b32_e32 v3, 2, v81
	global_load_dword v84, v2, s[74:75]
	global_load_dword v85, v3, s[74:75]
	global_load_dword v86, v2, s[76:77]
	global_load_dword v87, v3, s[76:77]
	v_mov_b32_e32 v32, 0
	v_mov_b32_e32 v33, 0
	v_mov_b32_e32 v34, 0
	v_mov_b32_e32 v35, 0
	v_mov_b32_e32 v36, 0
	v_mov_b32_e32 v37, 0
	v_mov_b32_e32 v38, 0
	v_mov_b32_e32 v39, 0
	v_mov_b32_e32 v40, 0
	v_mov_b32_e32 v41, 0
	v_mov_b32_e32 v42, 0
	v_mov_b32_e32 v43, 0
	v_mov_b32_e32 v44, 0
	v_mov_b32_e32 v45, 0
	v_mov_b32_e32 v46, 0
	v_mov_b32_e32 v47, 0
	v_mov_b32_e32 v48, 0
	v_mov_b32_e32 v49, 0
	v_mov_b32_e32 v50, 0
	v_mov_b32_e32 v51, 0
	v_mov_b32_e32 v52, 0
	v_mov_b32_e32 v53, 0
	v_mov_b32_e32 v54, 0
	v_mov_b32_e32 v55, 0
	v_mov_b32_e32 v56, 0
	v_mov_b32_e32 v57, 0
	v_mov_b32_e32 v58, 0
	v_mov_b32_e32 v59, 0
	v_mov_b32_e32 v60, 0
	v_mov_b32_e32 v61, 0
	v_mov_b32_e32 v62, 0
	v_mov_b32_e32 v63, 0
	v_lshlrev_b32_e32 v2, 2, v0
	v_sub_u32_e32 v25, v170, v2
	v_add_u32_e32 v5, 0x1000, v170
	v_lshrrev_b32_e32 v2, 4, v0
	v_lshrrev_b32_e32 v3, 5, v0
	v_and_b32_e32 v2, 1, v2
	v_lshl_or_b32 v2, v2, 1, v3
	v_add_u32_e32 v3, 0x1000, v25
	v_lshl_add_u32 v26, v2, 2, v3
	v_add_u32_e32 v27, 16, v26
	s_lshr_b32 s96, s88, 4
	v_add_u32_e32 v25, s96, v25
	v_add_u32_e32 v26, s96, v26
	v_add_u32_e32 v27, s96, v27
	s_waitcnt vmcnt(4)
	v_lshlrev_b32_e32 v128, 16, v64
	v_and_b32_e32 v129, 0xffff0000, v64
	v_lshlrev_b32_e32 v130, 16, v65
	v_and_b32_e32 v131, 0xffff0000, v65
	v_lshlrev_b32_e32 v132, 16, v66
	v_and_b32_e32 v133, 0xffff0000, v66
	v_lshlrev_b32_e32 v134, 16, v67
	v_and_b32_e32 v135, 0xffff0000, v67
	v_lshlrev_b32_e32 v136, 16, v68
	v_and_b32_e32 v137, 0xffff0000, v68
	v_lshlrev_b32_e32 v138, 16, v69
	v_and_b32_e32 v139, 0xffff0000, v69
	v_lshlrev_b32_e32 v140, 16, v70
	v_and_b32_e32 v141, 0xffff0000, v70
	v_lshlrev_b32_e32 v142, 16, v71
	v_and_b32_e32 v143, 0xffff0000, v71
	v_lshlrev_b32_e32 v144, 16, v72
	v_and_b32_e32 v145, 0xffff0000, v72
	v_lshlrev_b32_e32 v146, 16, v73
	v_and_b32_e32 v147, 0xffff0000, v73
	v_lshlrev_b32_e32 v148, 16, v74
	v_and_b32_e32 v149, 0xffff0000, v74
	v_lshlrev_b32_e32 v150, 16, v75
	v_and_b32_e32 v151, 0xffff0000, v75
	v_lshlrev_b32_e32 v152, 16, v76
	v_and_b32_e32 v153, 0xffff0000, v76
	v_lshlrev_b32_e32 v154, 16, v77
	v_and_b32_e32 v155, 0xffff0000, v77
	v_lshlrev_b32_e32 v156, 16, v78
	v_and_b32_e32 v157, 0xffff0000, v78
	v_lshlrev_b32_e32 v158, 16, v79
	v_and_b32_e32 v159, 0xffff0000, v79
	v_max3_f32 v6, |v128|, |v129|, |v130|
	v_max3_f32 v6, v6, |v131|, |v132|
	v_max3_f32 v6, v6, |v133|, |v134|
	v_max3_f32 v6, v6, |v135|, |v136|
	v_max3_f32 v6, v6, |v137|, |v138|
	v_max3_f32 v6, v6, |v139|, |v140|
	v_max3_f32 v6, v6, |v141|, |v142|
	v_max3_f32 v6, v6, |v143|, |v144|
	v_max3_f32 v6, v6, |v145|, |v146|
	v_max3_f32 v6, v6, |v147|, |v148|
	v_max3_f32 v6, v6, |v149|, |v150|
	v_max3_f32 v6, v6, |v151|, |v152|
	v_max3_f32 v6, v6, |v153|, |v154|
	v_max3_f32 v6, v6, |v155|, |v156|
	v_max3_f32 v6, v6, |v157|, |v158|
	v_max_f32_e64 v6, v6, |v159|
	v_mov_b32_e32 v2, v6
	v_mov_b32_e32 v3, v6
	s_nop 1
	v_permlane32_swap_b32_e32 v2, v3
	v_max_f32_e32 v6, v2, v3
	v_mov_b32_e32 v2, v6
	v_mov_b32_e32 v3, v6
	s_nop 1
	v_permlane16_swap_b32_e32 v2, v3
	v_max_f32_e32 v6, v2, v3
	s_nop 1
	v_max_f32_dpp v6, v6, v6 row_ror:8 row_mask:0xf bank_mask:0xf
	s_nop 1
	v_max_f32_dpp v6, v6, v6 row_ror:4 row_mask:0xf bank_mask:0xf
	s_nop 1
	v_max_f32_dpp v6, v6, v6 row_ror:2 row_mask:0xf bank_mask:0xf
	s_nop 1
	v_max_f32_dpp v6, v6, v6 row_ror:1 row_mask:0xf bank_mask:0xf
	v_mul_f32_e32 v7, 0x3e124925, v6
	v_cmp_lt_f32_e32 vcc, 0, v6
	s_nop 1
	v_cndmask_b32_e32 v7, 1.0, v7, vcc
	v_mul_f32_e32 v10, 0x3d924925, v7
	v_rcp_f32_e32 v11, v7
	v_rcp_f32_e32 v12, v10
	s_mov_b32 s33, 0xc0e00000
	v_mov_b32_e32 v13, 0x40e00000
	v_mul_f32_e32 v21, v128, v11
	v_rndne_f32_e32 v21, v21
	v_med3_f32 v21, v21, s33, v13
	v_fma_f32 v22, -v7, v21, v128
	v_mul_f32_e32 v22, v22, v12
	v_rndne_f32_e32 v22, v22
	v_med3_f32 v22, v22, s33, v13
	v_cvt_i32_f32_e32 v21, v21
	v_cvt_i32_f32_e32 v22, v22
	v_and_b32_e32 v208, 15, v21
	v_and_b32_e32 v212, 15, v22
	v_mul_f32_e32 v23, v129, v11
	v_rndne_f32_e32 v23, v23
	v_med3_f32 v23, v23, s33, v13
	v_fma_f32 v30, -v7, v23, v129
	v_mul_f32_e32 v30, v30, v12
	v_rndne_f32_e32 v30, v30
	v_med3_f32 v30, v30, s33, v13
	v_cvt_i32_f32_e32 v23, v23
	v_cvt_i32_f32_e32 v30, v30
	v_and_b32_e32 v23, 15, v23
	v_and_b32_e32 v30, 15, v30
	v_lshl_or_b32 v208, v23, 4, v208
	v_lshl_or_b32 v212, v30, 4, v212
	v_mul_f32_e32 v21, v130, v11
	v_rndne_f32_e32 v21, v21
	v_med3_f32 v21, v21, s33, v13
	v_fma_f32 v22, -v7, v21, v130
	v_mul_f32_e32 v22, v22, v12
	v_rndne_f32_e32 v22, v22
	v_med3_f32 v22, v22, s33, v13
	v_cvt_i32_f32_e32 v21, v21
	v_cvt_i32_f32_e32 v22, v22
	v_and_b32_e32 v21, 15, v21
	v_and_b32_e32 v22, 15, v22
	v_lshl_or_b32 v208, v21, 8, v208
	v_lshl_or_b32 v212, v22, 8, v212
	v_mul_f32_e32 v23, v131, v11
	v_rndne_f32_e32 v23, v23
	v_med3_f32 v23, v23, s33, v13
	v_fma_f32 v30, -v7, v23, v131
	v_mul_f32_e32 v30, v30, v12
	v_rndne_f32_e32 v30, v30
	v_med3_f32 v30, v30, s33, v13
	v_cvt_i32_f32_e32 v23, v23
	v_cvt_i32_f32_e32 v30, v30
	v_and_b32_e32 v23, 15, v23
	v_and_b32_e32 v30, 15, v30
	v_lshl_or_b32 v208, v23, 12, v208
	v_lshl_or_b32 v212, v30, 12, v212
	v_mul_f32_e32 v21, v132, v11
	v_rndne_f32_e32 v21, v21
	v_med3_f32 v21, v21, s33, v13
	v_fma_f32 v22, -v7, v21, v132
	v_mul_f32_e32 v22, v22, v12
	v_rndne_f32_e32 v22, v22
	v_med3_f32 v22, v22, s33, v13
	v_cvt_i32_f32_e32 v21, v21
	v_cvt_i32_f32_e32 v22, v22
	v_and_b32_e32 v21, 15, v21
	v_and_b32_e32 v22, 15, v22
	v_lshl_or_b32 v208, v21, 16, v208
	v_lshl_or_b32 v212, v22, 16, v212
	v_mul_f32_e32 v23, v133, v11
	v_rndne_f32_e32 v23, v23
	v_med3_f32 v23, v23, s33, v13
	v_fma_f32 v30, -v7, v23, v133
	v_mul_f32_e32 v30, v30, v12
	v_rndne_f32_e32 v30, v30
	v_med3_f32 v30, v30, s33, v13
	v_cvt_i32_f32_e32 v23, v23
	v_cvt_i32_f32_e32 v30, v30
	v_and_b32_e32 v23, 15, v23
	v_and_b32_e32 v30, 15, v30
	v_lshl_or_b32 v208, v23, 20, v208
	v_lshl_or_b32 v212, v30, 20, v212
	v_mul_f32_e32 v21, v134, v11
	v_rndne_f32_e32 v21, v21
	v_med3_f32 v21, v21, s33, v13
	v_fma_f32 v22, -v7, v21, v134
	v_mul_f32_e32 v22, v22, v12
	v_rndne_f32_e32 v22, v22
	v_med3_f32 v22, v22, s33, v13
	v_cvt_i32_f32_e32 v21, v21
	v_cvt_i32_f32_e32 v22, v22
	v_and_b32_e32 v21, 15, v21
	v_and_b32_e32 v22, 15, v22
	v_lshl_or_b32 v208, v21, 24, v208
	v_lshl_or_b32 v212, v22, 24, v212
	v_mul_f32_e32 v23, v135, v11
	v_rndne_f32_e32 v23, v23
	v_med3_f32 v23, v23, s33, v13
	v_fma_f32 v30, -v7, v23, v135
	v_mul_f32_e32 v30, v30, v12
	v_rndne_f32_e32 v30, v30
	v_med3_f32 v30, v30, s33, v13
	v_cvt_i32_f32_e32 v23, v23
	v_cvt_i32_f32_e32 v30, v30
	v_lshl_or_b32 v208, v23, 28, v208
	v_lshl_or_b32 v212, v30, 28, v212
	v_mul_f32_e32 v21, v136, v11
	v_rndne_f32_e32 v21, v21
	v_med3_f32 v21, v21, s33, v13
	v_fma_f32 v22, -v7, v21, v136
	v_mul_f32_e32 v22, v22, v12
	v_rndne_f32_e32 v22, v22
	v_med3_f32 v22, v22, s33, v13
	v_cvt_i32_f32_e32 v21, v21
	v_cvt_i32_f32_e32 v22, v22
	v_and_b32_e32 v209, 15, v21
	v_and_b32_e32 v213, 15, v22
	v_mul_f32_e32 v23, v137, v11
	v_rndne_f32_e32 v23, v23
	v_med3_f32 v23, v23, s33, v13
	v_fma_f32 v30, -v7, v23, v137
	v_mul_f32_e32 v30, v30, v12
	v_rndne_f32_e32 v30, v30
	v_med3_f32 v30, v30, s33, v13
	v_cvt_i32_f32_e32 v23, v23
	v_cvt_i32_f32_e32 v30, v30
	v_and_b32_e32 v23, 15, v23
	v_and_b32_e32 v30, 15, v30
	v_lshl_or_b32 v209, v23, 4, v209
	v_lshl_or_b32 v213, v30, 4, v213
	v_mul_f32_e32 v21, v138, v11
	v_rndne_f32_e32 v21, v21
	v_med3_f32 v21, v21, s33, v13
	v_fma_f32 v22, -v7, v21, v138
	v_mul_f32_e32 v22, v22, v12
	v_rndne_f32_e32 v22, v22
	v_med3_f32 v22, v22, s33, v13
	v_cvt_i32_f32_e32 v21, v21
	v_cvt_i32_f32_e32 v22, v22
	v_and_b32_e32 v21, 15, v21
	v_and_b32_e32 v22, 15, v22
	v_lshl_or_b32 v209, v21, 8, v209
	v_lshl_or_b32 v213, v22, 8, v213
	v_mul_f32_e32 v23, v139, v11
	v_rndne_f32_e32 v23, v23
	v_med3_f32 v23, v23, s33, v13
	v_fma_f32 v30, -v7, v23, v139
	v_mul_f32_e32 v30, v30, v12
	v_rndne_f32_e32 v30, v30
	v_med3_f32 v30, v30, s33, v13
	v_cvt_i32_f32_e32 v23, v23
	v_cvt_i32_f32_e32 v30, v30
	v_and_b32_e32 v23, 15, v23
	v_and_b32_e32 v30, 15, v30
	v_lshl_or_b32 v209, v23, 12, v209
	v_lshl_or_b32 v213, v30, 12, v213
	v_mul_f32_e32 v21, v140, v11
	v_rndne_f32_e32 v21, v21
	v_med3_f32 v21, v21, s33, v13
	v_fma_f32 v22, -v7, v21, v140
	v_mul_f32_e32 v22, v22, v12
	v_rndne_f32_e32 v22, v22
	v_med3_f32 v22, v22, s33, v13
	v_cvt_i32_f32_e32 v21, v21
	v_cvt_i32_f32_e32 v22, v22
	v_and_b32_e32 v21, 15, v21
	v_and_b32_e32 v22, 15, v22
	v_lshl_or_b32 v209, v21, 16, v209
	v_lshl_or_b32 v213, v22, 16, v213
	v_mul_f32_e32 v23, v141, v11
	v_rndne_f32_e32 v23, v23
	v_med3_f32 v23, v23, s33, v13
	v_fma_f32 v30, -v7, v23, v141
	v_mul_f32_e32 v30, v30, v12
	v_rndne_f32_e32 v30, v30
	v_med3_f32 v30, v30, s33, v13
	v_cvt_i32_f32_e32 v23, v23
	v_cvt_i32_f32_e32 v30, v30
	v_and_b32_e32 v23, 15, v23
	v_and_b32_e32 v30, 15, v30
	v_lshl_or_b32 v209, v23, 20, v209
	v_lshl_or_b32 v213, v30, 20, v213
	v_mul_f32_e32 v21, v142, v11
	v_rndne_f32_e32 v21, v21
	v_med3_f32 v21, v21, s33, v13
	v_fma_f32 v22, -v7, v21, v142
	v_mul_f32_e32 v22, v22, v12
	v_rndne_f32_e32 v22, v22
	v_med3_f32 v22, v22, s33, v13
	v_cvt_i32_f32_e32 v21, v21
	v_cvt_i32_f32_e32 v22, v22
	v_and_b32_e32 v21, 15, v21
	v_and_b32_e32 v22, 15, v22
	v_lshl_or_b32 v209, v21, 24, v209
	v_lshl_or_b32 v213, v22, 24, v213
	v_mul_f32_e32 v23, v143, v11
	v_rndne_f32_e32 v23, v23
	v_med3_f32 v23, v23, s33, v13
	v_fma_f32 v30, -v7, v23, v143
	v_mul_f32_e32 v30, v30, v12
	v_rndne_f32_e32 v30, v30
	v_med3_f32 v30, v30, s33, v13
	v_cvt_i32_f32_e32 v23, v23
	v_cvt_i32_f32_e32 v30, v30
	v_lshl_or_b32 v209, v23, 28, v209
	v_lshl_or_b32 v213, v30, 28, v213
	v_mul_f32_e32 v21, v144, v11
	v_rndne_f32_e32 v21, v21
	v_med3_f32 v21, v21, s33, v13
	v_fma_f32 v22, -v7, v21, v144
	v_mul_f32_e32 v22, v22, v12
	v_rndne_f32_e32 v22, v22
	v_med3_f32 v22, v22, s33, v13
	v_cvt_i32_f32_e32 v21, v21
	v_cvt_i32_f32_e32 v22, v22
	v_and_b32_e32 v210, 15, v21
	v_and_b32_e32 v214, 15, v22
	v_mul_f32_e32 v23, v145, v11
	v_rndne_f32_e32 v23, v23
	v_med3_f32 v23, v23, s33, v13
	v_fma_f32 v30, -v7, v23, v145
	v_mul_f32_e32 v30, v30, v12
	v_rndne_f32_e32 v30, v30
	v_med3_f32 v30, v30, s33, v13
	v_cvt_i32_f32_e32 v23, v23
	v_cvt_i32_f32_e32 v30, v30
	v_and_b32_e32 v23, 15, v23
	v_and_b32_e32 v30, 15, v30
	v_lshl_or_b32 v210, v23, 4, v210
	v_lshl_or_b32 v214, v30, 4, v214
	v_mul_f32_e32 v21, v146, v11
	v_rndne_f32_e32 v21, v21
	v_med3_f32 v21, v21, s33, v13
	v_fma_f32 v22, -v7, v21, v146
	v_mul_f32_e32 v22, v22, v12
	v_rndne_f32_e32 v22, v22
	v_med3_f32 v22, v22, s33, v13
	v_cvt_i32_f32_e32 v21, v21
	v_cvt_i32_f32_e32 v22, v22
	v_and_b32_e32 v21, 15, v21
	v_and_b32_e32 v22, 15, v22
	v_lshl_or_b32 v210, v21, 8, v210
	v_lshl_or_b32 v214, v22, 8, v214
	v_mul_f32_e32 v23, v147, v11
	v_rndne_f32_e32 v23, v23
	v_med3_f32 v23, v23, s33, v13
	v_fma_f32 v30, -v7, v23, v147
	v_mul_f32_e32 v30, v30, v12
	v_rndne_f32_e32 v30, v30
	v_med3_f32 v30, v30, s33, v13
	v_cvt_i32_f32_e32 v23, v23
	v_cvt_i32_f32_e32 v30, v30
	v_and_b32_e32 v23, 15, v23
	v_and_b32_e32 v30, 15, v30
	v_lshl_or_b32 v210, v23, 12, v210
	v_lshl_or_b32 v214, v30, 12, v214
	v_mul_f32_e32 v21, v148, v11
	v_rndne_f32_e32 v21, v21
	v_med3_f32 v21, v21, s33, v13
	v_fma_f32 v22, -v7, v21, v148
	v_mul_f32_e32 v22, v22, v12
	v_rndne_f32_e32 v22, v22
	v_med3_f32 v22, v22, s33, v13
	v_cvt_i32_f32_e32 v21, v21
	v_cvt_i32_f32_e32 v22, v22
	v_and_b32_e32 v21, 15, v21
	v_and_b32_e32 v22, 15, v22
	v_lshl_or_b32 v210, v21, 16, v210
	v_lshl_or_b32 v214, v22, 16, v214
	v_mul_f32_e32 v23, v149, v11
	v_rndne_f32_e32 v23, v23
	v_med3_f32 v23, v23, s33, v13
	v_fma_f32 v30, -v7, v23, v149
	v_mul_f32_e32 v30, v30, v12
	v_rndne_f32_e32 v30, v30
	v_med3_f32 v30, v30, s33, v13
	v_cvt_i32_f32_e32 v23, v23
	v_cvt_i32_f32_e32 v30, v30
	v_and_b32_e32 v23, 15, v23
	v_and_b32_e32 v30, 15, v30
	v_lshl_or_b32 v210, v23, 20, v210
	v_lshl_or_b32 v214, v30, 20, v214
	v_mul_f32_e32 v21, v150, v11
	v_rndne_f32_e32 v21, v21
	v_med3_f32 v21, v21, s33, v13
	v_fma_f32 v22, -v7, v21, v150
	v_mul_f32_e32 v22, v22, v12
	v_rndne_f32_e32 v22, v22
	v_med3_f32 v22, v22, s33, v13
	v_cvt_i32_f32_e32 v21, v21
	v_cvt_i32_f32_e32 v22, v22
	v_and_b32_e32 v21, 15, v21
	v_and_b32_e32 v22, 15, v22
	v_lshl_or_b32 v210, v21, 24, v210
	v_lshl_or_b32 v214, v22, 24, v214
	v_mul_f32_e32 v23, v151, v11
	v_rndne_f32_e32 v23, v23
	v_med3_f32 v23, v23, s33, v13
	v_fma_f32 v30, -v7, v23, v151
	v_mul_f32_e32 v30, v30, v12
	v_rndne_f32_e32 v30, v30
	v_med3_f32 v30, v30, s33, v13
	v_cvt_i32_f32_e32 v23, v23
	v_cvt_i32_f32_e32 v30, v30
	v_lshl_or_b32 v210, v23, 28, v210
	v_lshl_or_b32 v214, v30, 28, v214
	v_mul_f32_e32 v21, v152, v11
	v_rndne_f32_e32 v21, v21
	v_med3_f32 v21, v21, s33, v13
	v_fma_f32 v22, -v7, v21, v152
	v_mul_f32_e32 v22, v22, v12
	v_rndne_f32_e32 v22, v22
	v_med3_f32 v22, v22, s33, v13
	v_cvt_i32_f32_e32 v21, v21
	v_cvt_i32_f32_e32 v22, v22
	v_and_b32_e32 v211, 15, v21
	v_and_b32_e32 v215, 15, v22
	v_mul_f32_e32 v23, v153, v11
	v_rndne_f32_e32 v23, v23
	v_med3_f32 v23, v23, s33, v13
	v_fma_f32 v30, -v7, v23, v153
	v_mul_f32_e32 v30, v30, v12
	v_rndne_f32_e32 v30, v30
	v_med3_f32 v30, v30, s33, v13
	v_cvt_i32_f32_e32 v23, v23
	v_cvt_i32_f32_e32 v30, v30
	v_and_b32_e32 v23, 15, v23
	v_and_b32_e32 v30, 15, v30
	v_lshl_or_b32 v211, v23, 4, v211
	v_lshl_or_b32 v215, v30, 4, v215
	v_mul_f32_e32 v21, v154, v11
	v_rndne_f32_e32 v21, v21
	v_med3_f32 v21, v21, s33, v13
	v_fma_f32 v22, -v7, v21, v154
	v_mul_f32_e32 v22, v22, v12
	v_rndne_f32_e32 v22, v22
	v_med3_f32 v22, v22, s33, v13
	v_cvt_i32_f32_e32 v21, v21
	v_cvt_i32_f32_e32 v22, v22
	v_and_b32_e32 v21, 15, v21
	v_and_b32_e32 v22, 15, v22
	v_lshl_or_b32 v211, v21, 8, v211
	v_lshl_or_b32 v215, v22, 8, v215
	v_mul_f32_e32 v23, v155, v11
	v_rndne_f32_e32 v23, v23
	v_med3_f32 v23, v23, s33, v13
	v_fma_f32 v30, -v7, v23, v155
	v_mul_f32_e32 v30, v30, v12
	v_rndne_f32_e32 v30, v30
	v_med3_f32 v30, v30, s33, v13
	v_cvt_i32_f32_e32 v23, v23
	v_cvt_i32_f32_e32 v30, v30
	v_and_b32_e32 v23, 15, v23
	v_and_b32_e32 v30, 15, v30
	v_lshl_or_b32 v211, v23, 12, v211
	v_lshl_or_b32 v215, v30, 12, v215
	v_mul_f32_e32 v21, v156, v11
	v_rndne_f32_e32 v21, v21
	v_med3_f32 v21, v21, s33, v13
	v_fma_f32 v22, -v7, v21, v156
	v_mul_f32_e32 v22, v22, v12
	v_rndne_f32_e32 v22, v22
	v_med3_f32 v22, v22, s33, v13
	v_cvt_i32_f32_e32 v21, v21
	v_cvt_i32_f32_e32 v22, v22
	v_and_b32_e32 v21, 15, v21
	v_and_b32_e32 v22, 15, v22
	v_lshl_or_b32 v211, v21, 16, v211
	v_lshl_or_b32 v215, v22, 16, v215
	v_mul_f32_e32 v23, v157, v11
	v_rndne_f32_e32 v23, v23
	v_med3_f32 v23, v23, s33, v13
	v_fma_f32 v30, -v7, v23, v157
	v_mul_f32_e32 v30, v30, v12
	v_rndne_f32_e32 v30, v30
	v_med3_f32 v30, v30, s33, v13
	v_cvt_i32_f32_e32 v23, v23
	v_cvt_i32_f32_e32 v30, v30
	v_and_b32_e32 v23, 15, v23
	v_and_b32_e32 v30, 15, v30
	v_lshl_or_b32 v211, v23, 20, v211
	v_lshl_or_b32 v215, v30, 20, v215
	v_mul_f32_e32 v21, v158, v11
	v_rndne_f32_e32 v21, v21
	v_med3_f32 v21, v21, s33, v13
	v_fma_f32 v22, -v7, v21, v158
	v_mul_f32_e32 v22, v22, v12
	v_rndne_f32_e32 v22, v22
	v_med3_f32 v22, v22, s33, v13
	v_cvt_i32_f32_e32 v21, v21
	v_cvt_i32_f32_e32 v22, v22
	v_and_b32_e32 v21, 15, v21
	v_and_b32_e32 v22, 15, v22
	v_lshl_or_b32 v211, v21, 24, v211
	v_lshl_or_b32 v215, v22, 24, v215
	v_mul_f32_e32 v23, v159, v11
	v_rndne_f32_e32 v23, v23
	v_med3_f32 v23, v23, s33, v13
	v_fma_f32 v30, -v7, v23, v159
	v_mul_f32_e32 v30, v30, v12
	v_rndne_f32_e32 v30, v30
	v_med3_f32 v30, v30, s33, v13
	v_cvt_i32_f32_e32 v23, v23
	v_cvt_i32_f32_e32 v30, v30
	v_lshl_or_b32 v211, v23, 28, v211
	v_lshl_or_b32 v215, v30, 28, v215
	s_waitcnt vmcnt(0)
	v_mul_f32_e32 v2, v24, v10
	v_mul_f32_e32 v84, v84, v2
	v_mul_f32_e32 v85, v85, v2
	v_mul_f32_e32 v86, v86, v82
	v_mul_f32_e32 v87, v87, v83
	ds_write_b32 v5, v84
	ds_write_b32 v5, v85 offset:256
	ds_write_b32 v5, v86 offset:512
	ds_write_b32 v5, v87 offset:768
	ds_read_b128 v[10:13], v25
	ds_read_b128 v[18:21], v25 offset:16
	v_add_u32_e32 v25, 32, v25
	s_waitcnt lgkmcnt(0)
	v_readfirstlane_b32 s33, v10
	s_lshl_b32 s33, s33, 10
	s_add_u32 s72, s94, s33
	s_addc_u32 s73, s95, 0
	global_load_dwordx2 v[64:65], v28, s[72:73]
	global_load_dwordx2 v[66:67], v28, s[72:73] offset:512
	global_load_dwordx2 v[96:97], v29, s[72:73]
	global_load_dwordx2 v[98:99], v29, s[72:73] offset:512
	v_readfirstlane_b32 s33, v11
	s_lshl_b32 s33, s33, 10
	s_add_u32 s72, s94, s33
	s_addc_u32 s73, s95, 0
	global_load_dwordx2 v[68:69], v28, s[72:73]
	global_load_dwordx2 v[70:71], v28, s[72:73] offset:512
	global_load_dwordx2 v[100:101], v29, s[72:73]
	global_load_dwordx2 v[102:103], v29, s[72:73] offset:512
	v_readfirstlane_b32 s33, v12
	s_lshl_b32 s33, s33, 10
	s_add_u32 s72, s94, s33
	s_addc_u32 s73, s95, 0
	global_load_dwordx2 v[72:73], v28, s[72:73]
	global_load_dwordx2 v[74:75], v28, s[72:73] offset:512
	global_load_dwordx2 v[104:105], v29, s[72:73]
	global_load_dwordx2 v[106:107], v29, s[72:73] offset:512
	v_readfirstlane_b32 s33, v13
	s_lshl_b32 s33, s33, 10
	s_add_u32 s72, s94, s33
	s_addc_u32 s73, s95, 0
	global_load_dwordx2 v[76:77], v28, s[72:73]
	global_load_dwordx2 v[78:79], v28, s[72:73] offset:512
	global_load_dwordx2 v[108:109], v29, s[72:73]
	global_load_dwordx2 v[110:111], v29, s[72:73] offset:512
	v_readfirstlane_b32 s33, v18
	s_lshl_b32 s33, s33, 10
	s_add_u32 s72, s94, s33
	s_addc_u32 s73, s95, 0
	global_load_dwordx2 v[80:81], v28, s[72:73]
	global_load_dwordx2 v[82:83], v28, s[72:73] offset:512
	global_load_dwordx2 v[112:113], v29, s[72:73]
	global_load_dwordx2 v[114:115], v29, s[72:73] offset:512
	v_readfirstlane_b32 s33, v19
	s_lshl_b32 s33, s33, 10
	s_add_u32 s72, s94, s33
	s_addc_u32 s73, s95, 0
	global_load_dwordx2 v[84:85], v28, s[72:73]
	global_load_dwordx2 v[86:87], v28, s[72:73] offset:512
	global_load_dwordx2 v[116:117], v29, s[72:73]
	global_load_dwordx2 v[118:119], v29, s[72:73] offset:512
	v_readfirstlane_b32 s33, v20
	s_lshl_b32 s33, s33, 10
	s_add_u32 s72, s94, s33
	s_addc_u32 s73, s95, 0
	global_load_dwordx2 v[88:89], v28, s[72:73]
	global_load_dwordx2 v[90:91], v28, s[72:73] offset:512
	global_load_dwordx2 v[120:121], v29, s[72:73]
	global_load_dwordx2 v[122:123], v29, s[72:73] offset:512
	v_readfirstlane_b32 s33, v21
	s_lshl_b32 s33, s33, 10
	s_add_u32 s72, s94, s33
	s_addc_u32 s73, s95, 0
	global_load_dwordx2 v[92:93], v28, s[72:73]
	global_load_dwordx2 v[94:95], v28, s[72:73] offset:512
	global_load_dwordx2 v[124:125], v29, s[72:73]
	global_load_dwordx2 v[126:127], v29, s[72:73] offset:512
	s_mov_b32 s86, 1
.Lp8b_eloop:
	ds_read_b128 v[10:13], v25
	ds_read_b128 v[18:21], v25 offset:16
	v_add_u32_e32 v25, 32, v25
	ds_read_b32 v232, v26
	ds_read_b32 v233, v27
	ds_read_b32 v234, v26 offset:512
	ds_read_b32 v235, v27 offset:512
	v_add_u32_e32 v26, 32, v26
	v_add_u32_e32 v27, 32, v27
	s_waitcnt vmcnt(30)
	v_mov_b32_e32 v216, 0
	v_mov_b32_e32 v224, 0
	v_dot8c_i32_i4_e32 v216, v64, v208
	v_dot8c_i32_i4_e32 v224, v64, v212
	v_dot8c_i32_i4_e32 v216, v65, v209
	v_dot8c_i32_i4_e32 v224, v65, v213
	v_dot8c_i32_i4_e32 v216, v66, v210
	v_dot8c_i32_i4_e32 v224, v66, v214
	v_dot8c_i32_i4_e32 v216, v67, v211
	v_dot8c_i32_i4_e32 v224, v67, v215
	s_waitcnt vmcnt(26)
	v_mov_b32_e32 v217, 0
	v_mov_b32_e32 v225, 0
	v_dot8c_i32_i4_e32 v217, v68, v208
	v_dot8c_i32_i4_e32 v225, v68, v212
	v_dot8c_i32_i4_e32 v217, v69, v209
	v_dot8c_i32_i4_e32 v225, v69, v213
	v_dot8c_i32_i4_e32 v217, v70, v210
	v_dot8c_i32_i4_e32 v225, v70, v214
	v_dot8c_i32_i4_e32 v217, v71, v211
	v_dot8c_i32_i4_e32 v225, v71, v215
	s_waitcnt vmcnt(22)
	v_mov_b32_e32 v218, 0
	v_mov_b32_e32 v226, 0
	v_dot8c_i32_i4_e32 v218, v72, v208
	v_dot8c_i32_i4_e32 v226, v72, v212
	v_dot8c_i32_i4_e32 v218, v73, v209
	v_dot8c_i32_i4_e32 v226, v73, v213
	v_dot8c_i32_i4_e32 v218, v74, v210
	v_dot8c_i32_i4_e32 v226, v74, v214
	v_dot8c_i32_i4_e32 v218, v75, v211
	v_dot8c_i32_i4_e32 v226, v75, v215
	s_waitcnt vmcnt(18)
	v_mov_b32_e32 v219, 0
	v_mov_b32_e32 v227, 0
	v_dot8c_i32_i4_e32 v219, v76, v208
	v_dot8c_i32_i4_e32 v227, v76, v212
	v_dot8c_i32_i4_e32 v219, v77, v209
	v_dot8c_i32_i4_e32 v227, v77, v213
	v_dot8c_i32_i4_e32 v219, v78, v210
	v_dot8c_i32_i4_e32 v227, v78, v214
	v_dot8c_i32_i4_e32 v219, v79, v211
	v_dot8c_i32_i4_e32 v227, v79, v215
	s_waitcnt vmcnt(14)
	v_mov_b32_e32 v220, 0
	v_mov_b32_e32 v228, 0
	v_dot8c_i32_i4_e32 v220, v80, v208
	v_dot8c_i32_i4_e32 v228, v80, v212
	v_dot8c_i32_i4_e32 v220, v81, v209
	v_dot8c_i32_i4_e32 v228, v81, v213
	v_dot8c_i32_i4_e32 v220, v82, v210
	v_dot8c_i32_i4_e32 v228, v82, v214
	v_dot8c_i32_i4_e32 v220, v83, v211
	v_dot8c_i32_i4_e32 v228, v83, v215
	s_waitcnt vmcnt(10)
	v_mov_b32_e32 v221, 0
	v_mov_b32_e32 v229, 0
	v_dot8c_i32_i4_e32 v221, v84, v208
	v_dot8c_i32_i4_e32 v229, v84, v212
	v_dot8c_i32_i4_e32 v221, v85, v209
	v_dot8c_i32_i4_e32 v229, v85, v213
	v_dot8c_i32_i4_e32 v221, v86, v210
	v_dot8c_i32_i4_e32 v229, v86, v214
	v_dot8c_i32_i4_e32 v221, v87, v211
	v_dot8c_i32_i4_e32 v229, v87, v215
	s_waitcnt vmcnt(6)
	v_mov_b32_e32 v222, 0
	v_mov_b32_e32 v230, 0
	v_dot8c_i32_i4_e32 v222, v88, v208
	v_dot8c_i32_i4_e32 v230, v88, v212
	v_dot8c_i32_i4_e32 v222, v89, v209
	v_dot8c_i32_i4_e32 v230, v89, v213
	v_dot8c_i32_i4_e32 v222, v90, v210
	v_dot8c_i32_i4_e32 v230, v90, v214
	v_dot8c_i32_i4_e32 v222, v91, v211
	v_dot8c_i32_i4_e32 v230, v91, v215
	s_waitcnt vmcnt(2)
	v_mov_b32_e32 v223, 0
	v_mov_b32_e32 v231, 0
	v_dot8c_i32_i4_e32 v223, v92, v208
	v_dot8c_i32_i4_e32 v231, v92, v212
	v_dot8c_i32_i4_e32 v223, v93, v209
	v_dot8c_i32_i4_e32 v231, v93, v213
	v_dot8c_i32_i4_e32 v223, v94, v210
	v_dot8c_i32_i4_e32 v231, v94, v214
	v_dot8c_i32_i4_e32 v223, v95, v211
	v_dot8c_i32_i4_e32 v231, v95, v215
	s_nop 2
	v_mad_i32_i24 v216, v216, 14, v224
	v_mad_i32_i24 v217, v217, 14, v225
	v_mad_i32_i24 v218, v218, 14, v226
	v_mad_i32_i24 v219, v219, 14, v227
	v_mad_i32_i24 v220, v220, 14, v228
	v_mad_i32_i24 v221, v221, 14, v229
	v_mad_i32_i24 v222, v222, 14, v230
	v_mad_i32_i24 v223, v223, 14, v231
	s_waitcnt lgkmcnt(4)
	v_readfirstlane_b32 s33, v10
	s_lshl_b32 s33, s33, 10
	s_add_u32 s72, s94, s33
	s_addc_u32 s73, s95, 0
	global_load_dwordx2 v[128:129], v28, s[72:73]
	global_load_dwordx2 v[130:131], v28, s[72:73] offset:512
	global_load_dwordx2 v[176:177], v29, s[72:73]
	global_load_dwordx2 v[178:179], v29, s[72:73] offset:512
	v_readfirstlane_b32 s33, v11
	s_lshl_b32 s33, s33, 10
	s_add_u32 s72, s94, s33
	s_addc_u32 s73, s95, 0
	global_load_dwordx2 v[132:133], v28, s[72:73]
	global_load_dwordx2 v[134:135], v28, s[72:73] offset:512
	global_load_dwordx2 v[180:181], v29, s[72:73]
	global_load_dwordx2 v[182:183], v29, s[72:73] offset:512
	v_readfirstlane_b32 s33, v12
	s_lshl_b32 s33, s33, 10
	s_add_u32 s72, s94, s33
	s_addc_u32 s73, s95, 0
	global_load_dwordx2 v[136:137], v28, s[72:73]
	global_load_dwordx2 v[138:139], v28, s[72:73] offset:512
	global_load_dwordx2 v[184:185], v29, s[72:73]
	global_load_dwordx2 v[186:187], v29, s[72:73] offset:512
	v_readfirstlane_b32 s33, v13
	s_lshl_b32 s33, s33, 10
	s_add_u32 s72, s94, s33
	s_addc_u32 s73, s95, 0
	global_load_dwordx2 v[140:141], v28, s[72:73]
	global_load_dwordx2 v[142:143], v28, s[72:73] offset:512
	global_load_dwordx2 v[188:189], v29, s[72:73]
	global_load_dwordx2 v[190:191], v29, s[72:73] offset:512
	v_readfirstlane_b32 s33, v18
	s_lshl_b32 s33, s33, 10
	s_add_u32 s72, s94, s33
	s_addc_u32 s73, s95, 0
	global_load_dwordx2 v[144:145], v28, s[72:73]
	global_load_dwordx2 v[146:147], v28, s[72:73] offset:512
	global_load_dwordx2 v[192:193], v29, s[72:73]
	global_load_dwordx2 v[194:195], v29, s[72:73] offset:512
	v_readfirstlane_b32 s33, v19
	s_lshl_b32 s33, s33, 10
	s_add_u32 s72, s94, s33
	s_addc_u32 s73, s95, 0
	global_load_dwordx2 v[148:149], v28, s[72:73]
	global_load_dwordx2 v[150:151], v28, s[72:73] offset:512
	global_load_dwordx2 v[196:197], v29, s[72:73]
	global_load_dwordx2 v[198:199], v29, s[72:73] offset:512
	v_readfirstlane_b32 s33, v20
	s_lshl_b32 s33, s33, 10
	s_add_u32 s72, s94, s33
	s_addc_u32 s73, s95, 0
	global_load_dwordx2 v[152:153], v28, s[72:73]
	global_load_dwordx2 v[154:155], v28, s[72:73] offset:512
	global_load_dwordx2 v[200:201], v29, s[72:73]
	global_load_dwordx2 v[202:203], v29, s[72:73] offset:512
	v_readfirstlane_b32 s33, v21
	s_lshl_b32 s33, s33, 10
	s_add_u32 s72, s94, s33
	s_addc_u32 s73, s95, 0
	global_load_dwordx2 v[156:157], v28, s[72:73]
	global_load_dwordx2 v[158:159], v28, s[72:73] offset:512
	global_load_dwordx2 v[240:241], v29, s[72:73]
	global_load_dwordx2 v[242:243], v29, s[72:73] offset:512
	s_nop 1
	v_permlane32_swap_b32_e32 v216, v217
	v_permlane32_swap_b32_e32 v218, v219
	v_permlane32_swap_b32_e32 v220, v221
	v_permlane32_swap_b32_e32 v222, v223
	v_add_u32_e32 v216, v216, v217
	v_add_u32_e32 v218, v218, v219
	v_add_u32_e32 v220, v220, v221
	v_add_u32_e32 v222, v222, v223
	s_nop 1
	v_permlane16_swap_b32_e32 v216, v218
	v_permlane16_swap_b32_e32 v220, v222
	v_add_u32_e32 v216, v216, v218
	v_add_u32_e32 v220, v220, v222
	s_nop 1
	v_add_u32_dpp v216, v216, v216 row_ror:8 row_mask:0xf bank_mask:0xf
	v_add_u32_dpp v220, v220, v220 row_ror:8 row_mask:0xf bank_mask:0xf
	s_nop 1
	v_add_u32_dpp v216, v216, v216 row_ror:4 row_mask:0xf bank_mask:0xf
	v_add_u32_dpp v220, v220, v220 row_ror:4 row_mask:0xf bank_mask:0xf
	s_nop 1
	v_add_u32_dpp v216, v216, v216 row_ror:2 row_mask:0xf bank_mask:0xf
	v_add_u32_dpp v220, v220, v220 row_ror:2 row_mask:0xf bank_mask:0xf
	s_nop 1
	v_add_u32_dpp v216, v216, v216 row_ror:1 row_mask:0xf bank_mask:0xf
	v_add_u32_dpp v220, v220, v220 row_ror:1 row_mask:0xf bank_mask:0xf
	s_waitcnt lgkmcnt(0)
	v_cvt_f32_i32_e32 v216, v216
	v_cvt_f32_i32_e32 v220, v220
	v_mul_f32_e32 v216, v216, v232
	v_mul_f32_e32 v220, v220, v233
	v_fma_f32 v2, |v216|, s83, 1.0
	v_fma_f32 v7, |v220|, s83, 1.0
	v_rcp_f32_e32 v2, v2
	v_rcp_f32_e32 v7, v7
	v_mul_f32_e32 v5, v216, v216
	v_mul_f32_e32 v11, v220, v220
	v_mul_f32_e32 v5, 0xbf38aa3b, v5
	v_mul_f32_e32 v11, 0xbf38aa3b, v11
	v_exp_f32_e32 v5, v5
	v_exp_f32_e32 v11, v11
	v_fmamk_f32 v3, v2, 0x3f07dc22, v172
	v_fmamk_f32 v10, v7, 0x3f07dc22, v172
	v_fmaak_f32 v3, v2, v3, 0x3f35f0e3
	v_fmaak_f32 v10, v7, v10, 0x3f35f0e3
	v_fmaak_f32 v3, v2, v3, 0xbe11a98e
	v_fmaak_f32 v10, v7, v10, 0xbe11a98e
	v_fmaak_f32 v3, v2, v3, 0x3e027906
	v_fmaak_f32 v10, v7, v10, 0x3e027906
	v_mul_f32_e32 v3, v2, v3
	v_mul_f32_e32 v10, v7, v10
	v_mul_f32_e32 v3, v5, v3
	v_mul_f32_e32 v10, v11, v10
	v_mul_f32_e32 v6, v216, v3
	v_mul_f32_e32 v12, v220, v10
	v_fma_f32 v3, -v216, v3, v216
	v_fma_f32 v10, -v220, v10, v220
	v_cmp_gt_f32_e32 vcc, 0, v216
	v_cmp_gt_f32_e64 s[96:97], 0, v220
	s_nop 1
	v_cndmask_b32_e32 v216, v3, v6, vcc
	v_cndmask_b32_e64 v220, v10, v12, s[96:97]
	v_mul_f32_e32 v216, v216, v234
	v_mul_f32_e32 v220, v220, v235
	s_nop 0
	v_readlane_b32 s64, v216, 0
	v_readlane_b32 s65, v216, 32
	v_readlane_b32 s66, v216, 16
	v_readlane_b32 s67, v216, 48
	v_readlane_b32 s68, v220, 0
	v_readlane_b32 s69, v220, 32
	v_readlane_b32 s70, v220, 16
	v_readlane_b32 s71, v220, 48
	s_waitcnt vmcnt(60)
	v_cvt_scalef32_pk_f32_fp4 v[160:161], v96, 1.0
	v_cvt_scalef32_pk_f32_fp4 v[162:163], v96, 1.0 op_sel:[1,0,0]
	v_cvt_scalef32_pk_f32_fp4 v[18:19], v96, 1.0 op_sel:[0,1,0]
	v_pk_fma_f32 v[32:33], v[160:161], s[64:65], v[32:33] op_sel_hi:[1,0,1]
	v_cvt_scalef32_pk_f32_fp4 v[20:21], v96, 1.0 op_sel:[1,1,0]
	v_pk_fma_f32 v[34:35], v[162:163], s[64:65], v[34:35] op_sel_hi:[1,0,1]
	v_cvt_scalef32_pk_f32_fp4 v[22:23], v97, 1.0
	v_pk_fma_f32 v[36:37], v[18:19], s[64:65], v[36:37] op_sel_hi:[1,0,1]
	v_cvt_scalef32_pk_f32_fp4 v[30:31], v97, 1.0 op_sel:[1,0,0]
	v_pk_fma_f32 v[38:39], v[20:21], s[64:65], v[38:39] op_sel_hi:[1,0,1]
	v_cvt_scalef32_pk_f32_fp4 v[2:3], v97, 1.0 op_sel:[0,1,0]
	v_pk_fma_f32 v[40:41], v[22:23], s[64:65], v[40:41] op_sel_hi:[1,0,1]
	v_cvt_scalef32_pk_f32_fp4 v[6:7], v97, 1.0 op_sel:[1,1,0]
	v_pk_fma_f32 v[42:43], v[30:31], s[64:65], v[42:43] op_sel_hi:[1,0,1]
	v_cvt_scalef32_pk_f32_fp4 v[160:161], v98, 1.0
	v_pk_fma_f32 v[44:45], v[2:3], s[64:65], v[44:45] op_sel_hi:[1,0,1]
	v_cvt_scalef32_pk_f32_fp4 v[162:163], v98, 1.0 op_sel:[1,0,0]
	v_pk_fma_f32 v[46:47], v[6:7], s[64:65], v[46:47] op_sel_hi:[1,0,1]
	v_cvt_scalef32_pk_f32_fp4 v[18:19], v98, 1.0 op_sel:[0,1,0]
	v_pk_fma_f32 v[48:49], v[160:161], s[64:65], v[48:49] op_sel_hi:[1,0,1]
	v_cvt_scalef32_pk_f32_fp4 v[20:21], v98, 1.0 op_sel:[1,1,0]
	v_pk_fma_f32 v[50:51], v[162:163], s[64:65], v[50:51] op_sel_hi:[1,0,1]
	v_cvt_scalef32_pk_f32_fp4 v[22:23], v99, 1.0
	v_pk_fma_f32 v[52:53], v[18:19], s[64:65], v[52:53] op_sel_hi:[1,0,1]
	v_cvt_scalef32_pk_f32_fp4 v[30:31], v99, 1.0 op_sel:[1,0,0]
	v_pk_fma_f32 v[54:55], v[20:21], s[64:65], v[54:55] op_sel_hi:[1,0,1]
	v_cvt_scalef32_pk_f32_fp4 v[2:3], v99, 1.0 op_sel:[0,1,0]
	v_pk_fma_f32 v[56:57], v[22:23], s[64:65], v[56:57] op_sel_hi:[1,0,1]
	v_cvt_scalef32_pk_f32_fp4 v[6:7], v99, 1.0 op_sel:[1,1,0]
	v_pk_fma_f32 v[58:59], v[30:31], s[64:65], v[58:59] op_sel_hi:[1,0,1]
	v_pk_fma_f32 v[60:61], v[2:3], s[64:65], v[60:61] op_sel_hi:[1,0,1]
	v_pk_fma_f32 v[62:63], v[6:7], s[64:65], v[62:63] op_sel_hi:[1,0,1]
	s_waitcnt vmcnt(56)
	v_cvt_scalef32_pk_f32_fp4 v[160:161], v100, 1.0
	v_cvt_scalef32_pk_f32_fp4 v[162:163], v100, 1.0 op_sel:[1,0,0]
	v_cvt_scalef32_pk_f32_fp4 v[18:19], v100, 1.0 op_sel:[0,1,0]
	v_pk_fma_f32 v[32:33], v[160:161], s[64:65], v[32:33] op_sel:[0,1,0] op_sel_hi:[1,1,1]
	v_cvt_scalef32_pk_f32_fp4 v[20:21], v100, 1.0 op_sel:[1,1,0]
	v_pk_fma_f32 v[34:35], v[162:163], s[64:65], v[34:35] op_sel:[0,1,0] op_sel_hi:[1,1,1]
	v_cvt_scalef32_pk_f32_fp4 v[22:23], v101, 1.0
	v_pk_fma_f32 v[36:37], v[18:19], s[64:65], v[36:37] op_sel:[0,1,0] op_sel_hi:[1,1,1]
	v_cvt_scalef32_pk_f32_fp4 v[30:31], v101, 1.0 op_sel:[1,0,0]
	v_pk_fma_f32 v[38:39], v[20:21], s[64:65], v[38:39] op_sel:[0,1,0] op_sel_hi:[1,1,1]
	v_cvt_scalef32_pk_f32_fp4 v[2:3], v101, 1.0 op_sel:[0,1,0]
	v_pk_fma_f32 v[40:41], v[22:23], s[64:65], v[40:41] op_sel:[0,1,0] op_sel_hi:[1,1,1]
	v_cvt_scalef32_pk_f32_fp4 v[6:7], v101, 1.0 op_sel:[1,1,0]
	v_pk_fma_f32 v[42:43], v[30:31], s[64:65], v[42:43] op_sel:[0,1,0] op_sel_hi:[1,1,1]
	v_cvt_scalef32_pk_f32_fp4 v[160:161], v102, 1.0
	v_pk_fma_f32 v[44:45], v[2:3], s[64:65], v[44:45] op_sel:[0,1,0] op_sel_hi:[1,1,1]
	v_cvt_scalef32_pk_f32_fp4 v[162:163], v102, 1.0 op_sel:[1,0,0]
	v_pk_fma_f32 v[46:47], v[6:7], s[64:65], v[46:47] op_sel:[0,1,0] op_sel_hi:[1,1,1]
	v_cvt_scalef32_pk_f32_fp4 v[18:19], v102, 1.0 op_sel:[0,1,0]
	v_pk_fma_f32 v[48:49], v[160:161], s[64:65], v[48:49] op_sel:[0,1,0] op_sel_hi:[1,1,1]
	v_cvt_scalef32_pk_f32_fp4 v[20:21], v102, 1.0 op_sel:[1,1,0]
	v_pk_fma_f32 v[50:51], v[162:163], s[64:65], v[50:51] op_sel:[0,1,0] op_sel_hi:[1,1,1]
	v_cvt_scalef32_pk_f32_fp4 v[22:23], v103, 1.0
	v_pk_fma_f32 v[52:53], v[18:19], s[64:65], v[52:53] op_sel:[0,1,0] op_sel_hi:[1,1,1]
	v_cvt_scalef32_pk_f32_fp4 v[30:31], v103, 1.0 op_sel:[1,0,0]
	v_pk_fma_f32 v[54:55], v[20:21], s[64:65], v[54:55] op_sel:[0,1,0] op_sel_hi:[1,1,1]
	v_cvt_scalef32_pk_f32_fp4 v[2:3], v103, 1.0 op_sel:[0,1,0]
	v_pk_fma_f32 v[56:57], v[22:23], s[64:65], v[56:57] op_sel:[0,1,0] op_sel_hi:[1,1,1]
	v_cvt_scalef32_pk_f32_fp4 v[6:7], v103, 1.0 op_sel:[1,1,0]
	v_pk_fma_f32 v[58:59], v[30:31], s[64:65], v[58:59] op_sel:[0,1,0] op_sel_hi:[1,1,1]
	v_pk_fma_f32 v[60:61], v[2:3], s[64:65], v[60:61] op_sel:[0,1,0] op_sel_hi:[1,1,1]
	v_pk_fma_f32 v[62:63], v[6:7], s[64:65], v[62:63] op_sel:[0,1,0] op_sel_hi:[1,1,1]
	s_waitcnt vmcnt(52)
	v_cvt_scalef32_pk_f32_fp4 v[160:161], v104, 1.0
	v_cvt_scalef32_pk_f32_fp4 v[162:163], v104, 1.0 op_sel:[1,0,0]
	v_cvt_scalef32_pk_f32_fp4 v[18:19], v104, 1.0 op_sel:[0,1,0]
	v_pk_fma_f32 v[32:33], v[160:161], s[66:67], v[32:33] op_sel_hi:[1,0,1]
	v_cvt_scalef32_pk_f32_fp4 v[20:21], v104, 1.0 op_sel:[1,1,0]
	v_pk_fma_f32 v[34:35], v[162:163], s[66:67], v[34:35] op_sel_hi:[1,0,1]
	v_cvt_scalef32_pk_f32_fp4 v[22:23], v105, 1.0
	v_pk_fma_f32 v[36:37], v[18:19], s[66:67], v[36:37] op_sel_hi:[1,0,1]
	v_cvt_scalef32_pk_f32_fp4 v[30:31], v105, 1.0 op_sel:[1,0,0]
	v_pk_fma_f32 v[38:39], v[20:21], s[66:67], v[38:39] op_sel_hi:[1,0,1]
	v_cvt_scalef32_pk_f32_fp4 v[2:3], v105, 1.0 op_sel:[0,1,0]
	v_pk_fma_f32 v[40:41], v[22:23], s[66:67], v[40:41] op_sel_hi:[1,0,1]
	v_cvt_scalef32_pk_f32_fp4 v[6:7], v105, 1.0 op_sel:[1,1,0]
	v_pk_fma_f32 v[42:43], v[30:31], s[66:67], v[42:43] op_sel_hi:[1,0,1]
	v_cvt_scalef32_pk_f32_fp4 v[160:161], v106, 1.0
	v_pk_fma_f32 v[44:45], v[2:3], s[66:67], v[44:45] op_sel_hi:[1,0,1]
	v_cvt_scalef32_pk_f32_fp4 v[162:163], v106, 1.0 op_sel:[1,0,0]
	v_pk_fma_f32 v[46:47], v[6:7], s[66:67], v[46:47] op_sel_hi:[1,0,1]
	v_cvt_scalef32_pk_f32_fp4 v[18:19], v106, 1.0 op_sel:[0,1,0]
	v_pk_fma_f32 v[48:49], v[160:161], s[66:67], v[48:49] op_sel_hi:[1,0,1]
	v_cvt_scalef32_pk_f32_fp4 v[20:21], v106, 1.0 op_sel:[1,1,0]
	v_pk_fma_f32 v[50:51], v[162:163], s[66:67], v[50:51] op_sel_hi:[1,0,1]
	v_cvt_scalef32_pk_f32_fp4 v[22:23], v107, 1.0
	v_pk_fma_f32 v[52:53], v[18:19], s[66:67], v[52:53] op_sel_hi:[1,0,1]
	v_cvt_scalef32_pk_f32_fp4 v[30:31], v107, 1.0 op_sel:[1,0,0]
	v_pk_fma_f32 v[54:55], v[20:21], s[66:67], v[54:55] op_sel_hi:[1,0,1]
	v_cvt_scalef32_pk_f32_fp4 v[2:3], v107, 1.0 op_sel:[0,1,0]
	v_pk_fma_f32 v[56:57], v[22:23], s[66:67], v[56:57] op_sel_hi:[1,0,1]
	v_cvt_scalef32_pk_f32_fp4 v[6:7], v107, 1.0 op_sel:[1,1,0]
	v_pk_fma_f32 v[58:59], v[30:31], s[66:67], v[58:59] op_sel_hi:[1,0,1]
	v_pk_fma_f32 v[60:61], v[2:3], s[66:67], v[60:61] op_sel_hi:[1,0,1]
	v_pk_fma_f32 v[62:63], v[6:7], s[66:67], v[62:63] op_sel_hi:[1,0,1]
	s_waitcnt vmcnt(48)
	v_cvt_scalef32_pk_f32_fp4 v[160:161], v108, 1.0
	v_cvt_scalef32_pk_f32_fp4 v[162:163], v108, 1.0 op_sel:[1,0,0]
	v_cvt_scalef32_pk_f32_fp4 v[18:19], v108, 1.0 op_sel:[0,1,0]
	v_pk_fma_f32 v[32:33], v[160:161], s[66:67], v[32:33] op_sel:[0,1,0] op_sel_hi:[1,1,1]
	v_cvt_scalef32_pk_f32_fp4 v[20:21], v108, 1.0 op_sel:[1,1,0]
	v_pk_fma_f32 v[34:35], v[162:163], s[66:67], v[34:35] op_sel:[0,1,0] op_sel_hi:[1,1,1]
	v_cvt_scalef32_pk_f32_fp4 v[22:23], v109, 1.0
	v_pk_fma_f32 v[36:37], v[18:19], s[66:67], v[36:37] op_sel:[0,1,0] op_sel_hi:[1,1,1]
	v_cvt_scalef32_pk_f32_fp4 v[30:31], v109, 1.0 op_sel:[1,0,0]
	v_pk_fma_f32 v[38:39], v[20:21], s[66:67], v[38:39] op_sel:[0,1,0] op_sel_hi:[1,1,1]
	v_cvt_scalef32_pk_f32_fp4 v[2:3], v109, 1.0 op_sel:[0,1,0]
	v_pk_fma_f32 v[40:41], v[22:23], s[66:67], v[40:41] op_sel:[0,1,0] op_sel_hi:[1,1,1]
	v_cvt_scalef32_pk_f32_fp4 v[6:7], v109, 1.0 op_sel:[1,1,0]
	v_pk_fma_f32 v[42:43], v[30:31], s[66:67], v[42:43] op_sel:[0,1,0] op_sel_hi:[1,1,1]
	v_cvt_scalef32_pk_f32_fp4 v[160:161], v110, 1.0
	v_pk_fma_f32 v[44:45], v[2:3], s[66:67], v[44:45] op_sel:[0,1,0] op_sel_hi:[1,1,1]
	v_cvt_scalef32_pk_f32_fp4 v[162:163], v110, 1.0 op_sel:[1,0,0]
	v_pk_fma_f32 v[46:47], v[6:7], s[66:67], v[46:47] op_sel:[0,1,0] op_sel_hi:[1,1,1]
	v_cvt_scalef32_pk_f32_fp4 v[18:19], v110, 1.0 op_sel:[0,1,0]
	v_pk_fma_f32 v[48:49], v[160:161], s[66:67], v[48:49] op_sel:[0,1,0] op_sel_hi:[1,1,1]
	v_cvt_scalef32_pk_f32_fp4 v[20:21], v110, 1.0 op_sel:[1,1,0]
	v_pk_fma_f32 v[50:51], v[162:163], s[66:67], v[50:51] op_sel:[0,1,0] op_sel_hi:[1,1,1]
	v_cvt_scalef32_pk_f32_fp4 v[22:23], v111, 1.0
	v_pk_fma_f32 v[52:53], v[18:19], s[66:67], v[52:53] op_sel:[0,1,0] op_sel_hi:[1,1,1]
	v_cvt_scalef32_pk_f32_fp4 v[30:31], v111, 1.0 op_sel:[1,0,0]
	v_pk_fma_f32 v[54:55], v[20:21], s[66:67], v[54:55] op_sel:[0,1,0] op_sel_hi:[1,1,1]
	v_cvt_scalef32_pk_f32_fp4 v[2:3], v111, 1.0 op_sel:[0,1,0]
	v_pk_fma_f32 v[56:57], v[22:23], s[66:67], v[56:57] op_sel:[0,1,0] op_sel_hi:[1,1,1]
	v_cvt_scalef32_pk_f32_fp4 v[6:7], v111, 1.0 op_sel:[1,1,0]
	v_pk_fma_f32 v[58:59], v[30:31], s[66:67], v[58:59] op_sel:[0,1,0] op_sel_hi:[1,1,1]
	v_pk_fma_f32 v[60:61], v[2:3], s[66:67], v[60:61] op_sel:[0,1,0] op_sel_hi:[1,1,1]
	v_pk_fma_f32 v[62:63], v[6:7], s[66:67], v[62:63] op_sel:[0,1,0] op_sel_hi:[1,1,1]
	s_waitcnt vmcnt(44)
	v_cvt_scalef32_pk_f32_fp4 v[160:161], v112, 1.0
	v_cvt_scalef32_pk_f32_fp4 v[162:163], v112, 1.0 op_sel:[1,0,0]
	v_cvt_scalef32_pk_f32_fp4 v[18:19], v112, 1.0 op_sel:[0,1,0]
	v_pk_fma_f32 v[32:33], v[160:161], s[68:69], v[32:33] op_sel_hi:[1,0,1]
	v_cvt_scalef32_pk_f32_fp4 v[20:21], v112, 1.0 op_sel:[1,1,0]
	v_pk_fma_f32 v[34:35], v[162:163], s[68:69], v[34:35] op_sel_hi:[1,0,1]
	v_cvt_scalef32_pk_f32_fp4 v[22:23], v113, 1.0
	v_pk_fma_f32 v[36:37], v[18:19], s[68:69], v[36:37] op_sel_hi:[1,0,1]
	v_cvt_scalef32_pk_f32_fp4 v[30:31], v113, 1.0 op_sel:[1,0,0]
	v_pk_fma_f32 v[38:39], v[20:21], s[68:69], v[38:39] op_sel_hi:[1,0,1]
	v_cvt_scalef32_pk_f32_fp4 v[2:3], v113, 1.0 op_sel:[0,1,0]
	v_pk_fma_f32 v[40:41], v[22:23], s[68:69], v[40:41] op_sel_hi:[1,0,1]
	v_cvt_scalef32_pk_f32_fp4 v[6:7], v113, 1.0 op_sel:[1,1,0]
	v_pk_fma_f32 v[42:43], v[30:31], s[68:69], v[42:43] op_sel_hi:[1,0,1]
	v_cvt_scalef32_pk_f32_fp4 v[160:161], v114, 1.0
	v_pk_fma_f32 v[44:45], v[2:3], s[68:69], v[44:45] op_sel_hi:[1,0,1]
	v_cvt_scalef32_pk_f32_fp4 v[162:163], v114, 1.0 op_sel:[1,0,0]
	v_pk_fma_f32 v[46:47], v[6:7], s[68:69], v[46:47] op_sel_hi:[1,0,1]
	v_cvt_scalef32_pk_f32_fp4 v[18:19], v114, 1.0 op_sel:[0,1,0]
	v_pk_fma_f32 v[48:49], v[160:161], s[68:69], v[48:49] op_sel_hi:[1,0,1]
	v_cvt_scalef32_pk_f32_fp4 v[20:21], v114, 1.0 op_sel:[1,1,0]
	v_pk_fma_f32 v[50:51], v[162:163], s[68:69], v[50:51] op_sel_hi:[1,0,1]
	v_cvt_scalef32_pk_f32_fp4 v[22:23], v115, 1.0
	v_pk_fma_f32 v[52:53], v[18:19], s[68:69], v[52:53] op_sel_hi:[1,0,1]
	v_cvt_scalef32_pk_f32_fp4 v[30:31], v115, 1.0 op_sel:[1,0,0]
	v_pk_fma_f32 v[54:55], v[20:21], s[68:69], v[54:55] op_sel_hi:[1,0,1]
	v_cvt_scalef32_pk_f32_fp4 v[2:3], v115, 1.0 op_sel:[0,1,0]
	v_pk_fma_f32 v[56:57], v[22:23], s[68:69], v[56:57] op_sel_hi:[1,0,1]
	v_cvt_scalef32_pk_f32_fp4 v[6:7], v115, 1.0 op_sel:[1,1,0]
	v_pk_fma_f32 v[58:59], v[30:31], s[68:69], v[58:59] op_sel_hi:[1,0,1]
	v_pk_fma_f32 v[60:61], v[2:3], s[68:69], v[60:61] op_sel_hi:[1,0,1]
	v_pk_fma_f32 v[62:63], v[6:7], s[68:69], v[62:63] op_sel_hi:[1,0,1]
	s_waitcnt vmcnt(40)
	v_cvt_scalef32_pk_f32_fp4 v[160:161], v116, 1.0
	v_cvt_scalef32_pk_f32_fp4 v[162:163], v116, 1.0 op_sel:[1,0,0]
	v_cvt_scalef32_pk_f32_fp4 v[18:19], v116, 1.0 op_sel:[0,1,0]
	v_pk_fma_f32 v[32:33], v[160:161], s[68:69], v[32:33] op_sel:[0,1,0] op_sel_hi:[1,1,1]
	v_cvt_scalef32_pk_f32_fp4 v[20:21], v116, 1.0 op_sel:[1,1,0]
	v_pk_fma_f32 v[34:35], v[162:163], s[68:69], v[34:35] op_sel:[0,1,0] op_sel_hi:[1,1,1]
	v_cvt_scalef32_pk_f32_fp4 v[22:23], v117, 1.0
	v_pk_fma_f32 v[36:37], v[18:19], s[68:69], v[36:37] op_sel:[0,1,0] op_sel_hi:[1,1,1]
	v_cvt_scalef32_pk_f32_fp4 v[30:31], v117, 1.0 op_sel:[1,0,0]
	v_pk_fma_f32 v[38:39], v[20:21], s[68:69], v[38:39] op_sel:[0,1,0] op_sel_hi:[1,1,1]
	v_cvt_scalef32_pk_f32_fp4 v[2:3], v117, 1.0 op_sel:[0,1,0]
	v_pk_fma_f32 v[40:41], v[22:23], s[68:69], v[40:41] op_sel:[0,1,0] op_sel_hi:[1,1,1]
	v_cvt_scalef32_pk_f32_fp4 v[6:7], v117, 1.0 op_sel:[1,1,0]
	v_pk_fma_f32 v[42:43], v[30:31], s[68:69], v[42:43] op_sel:[0,1,0] op_sel_hi:[1,1,1]
	v_cvt_scalef32_pk_f32_fp4 v[160:161], v118, 1.0
	v_pk_fma_f32 v[44:45], v[2:3], s[68:69], v[44:45] op_sel:[0,1,0] op_sel_hi:[1,1,1]
	v_cvt_scalef32_pk_f32_fp4 v[162:163], v118, 1.0 op_sel:[1,0,0]
	v_pk_fma_f32 v[46:47], v[6:7], s[68:69], v[46:47] op_sel:[0,1,0] op_sel_hi:[1,1,1]
	v_cvt_scalef32_pk_f32_fp4 v[18:19], v118, 1.0 op_sel:[0,1,0]
	v_pk_fma_f32 v[48:49], v[160:161], s[68:69], v[48:49] op_sel:[0,1,0] op_sel_hi:[1,1,1]
	v_cvt_scalef32_pk_f32_fp4 v[20:21], v118, 1.0 op_sel:[1,1,0]
	v_pk_fma_f32 v[50:51], v[162:163], s[68:69], v[50:51] op_sel:[0,1,0] op_sel_hi:[1,1,1]
	v_cvt_scalef32_pk_f32_fp4 v[22:23], v119, 1.0
	v_pk_fma_f32 v[52:53], v[18:19], s[68:69], v[52:53] op_sel:[0,1,0] op_sel_hi:[1,1,1]
	v_cvt_scalef32_pk_f32_fp4 v[30:31], v119, 1.0 op_sel:[1,0,0]
	v_pk_fma_f32 v[54:55], v[20:21], s[68:69], v[54:55] op_sel:[0,1,0] op_sel_hi:[1,1,1]
	v_cvt_scalef32_pk_f32_fp4 v[2:3], v119, 1.0 op_sel:[0,1,0]
	v_pk_fma_f32 v[56:57], v[22:23], s[68:69], v[56:57] op_sel:[0,1,0] op_sel_hi:[1,1,1]
	v_cvt_scalef32_pk_f32_fp4 v[6:7], v119, 1.0 op_sel:[1,1,0]
	v_pk_fma_f32 v[58:59], v[30:31], s[68:69], v[58:59] op_sel:[0,1,0] op_sel_hi:[1,1,1]
	v_pk_fma_f32 v[60:61], v[2:3], s[68:69], v[60:61] op_sel:[0,1,0] op_sel_hi:[1,1,1]
	v_pk_fma_f32 v[62:63], v[6:7], s[68:69], v[62:63] op_sel:[0,1,0] op_sel_hi:[1,1,1]
	s_waitcnt vmcnt(36)
	v_cvt_scalef32_pk_f32_fp4 v[160:161], v120, 1.0
	v_cvt_scalef32_pk_f32_fp4 v[162:163], v120, 1.0 op_sel:[1,0,0]
	v_cvt_scalef32_pk_f32_fp4 v[18:19], v120, 1.0 op_sel:[0,1,0]
	v_pk_fma_f32 v[32:33], v[160:161], s[70:71], v[32:33] op_sel_hi:[1,0,1]
	v_cvt_scalef32_pk_f32_fp4 v[20:21], v120, 1.0 op_sel:[1,1,0]
	v_pk_fma_f32 v[34:35], v[162:163], s[70:71], v[34:35] op_sel_hi:[1,0,1]
	v_cvt_scalef32_pk_f32_fp4 v[22:23], v121, 1.0
	v_pk_fma_f32 v[36:37], v[18:19], s[70:71], v[36:37] op_sel_hi:[1,0,1]
	v_cvt_scalef32_pk_f32_fp4 v[30:31], v121, 1.0 op_sel:[1,0,0]
	v_pk_fma_f32 v[38:39], v[20:21], s[70:71], v[38:39] op_sel_hi:[1,0,1]
	v_cvt_scalef32_pk_f32_fp4 v[2:3], v121, 1.0 op_sel:[0,1,0]
	v_pk_fma_f32 v[40:41], v[22:23], s[70:71], v[40:41] op_sel_hi:[1,0,1]
	v_cvt_scalef32_pk_f32_fp4 v[6:7], v121, 1.0 op_sel:[1,1,0]
	v_pk_fma_f32 v[42:43], v[30:31], s[70:71], v[42:43] op_sel_hi:[1,0,1]
	v_cvt_scalef32_pk_f32_fp4 v[160:161], v122, 1.0
	v_pk_fma_f32 v[44:45], v[2:3], s[70:71], v[44:45] op_sel_hi:[1,0,1]
	v_cvt_scalef32_pk_f32_fp4 v[162:163], v122, 1.0 op_sel:[1,0,0]
	v_pk_fma_f32 v[46:47], v[6:7], s[70:71], v[46:47] op_sel_hi:[1,0,1]
	v_cvt_scalef32_pk_f32_fp4 v[18:19], v122, 1.0 op_sel:[0,1,0]
	v_pk_fma_f32 v[48:49], v[160:161], s[70:71], v[48:49] op_sel_hi:[1,0,1]
	v_cvt_scalef32_pk_f32_fp4 v[20:21], v122, 1.0 op_sel:[1,1,0]
	v_pk_fma_f32 v[50:51], v[162:163], s[70:71], v[50:51] op_sel_hi:[1,0,1]
	v_cvt_scalef32_pk_f32_fp4 v[22:23], v123, 1.0
	v_pk_fma_f32 v[52:53], v[18:19], s[70:71], v[52:53] op_sel_hi:[1,0,1]
	v_cvt_scalef32_pk_f32_fp4 v[30:31], v123, 1.0 op_sel:[1,0,0]
	v_pk_fma_f32 v[54:55], v[20:21], s[70:71], v[54:55] op_sel_hi:[1,0,1]
	v_cvt_scalef32_pk_f32_fp4 v[2:3], v123, 1.0 op_sel:[0,1,0]
	v_pk_fma_f32 v[56:57], v[22:23], s[70:71], v[56:57] op_sel_hi:[1,0,1]
	v_cvt_scalef32_pk_f32_fp4 v[6:7], v123, 1.0 op_sel:[1,1,0]
	v_pk_fma_f32 v[58:59], v[30:31], s[70:71], v[58:59] op_sel_hi:[1,0,1]
	v_pk_fma_f32 v[60:61], v[2:3], s[70:71], v[60:61] op_sel_hi:[1,0,1]
	v_pk_fma_f32 v[62:63], v[6:7], s[70:71], v[62:63] op_sel_hi:[1,0,1]
	s_waitcnt vmcnt(32)
	v_cvt_scalef32_pk_f32_fp4 v[160:161], v124, 1.0
	v_cvt_scalef32_pk_f32_fp4 v[162:163], v124, 1.0 op_sel:[1,0,0]
	v_cvt_scalef32_pk_f32_fp4 v[18:19], v124, 1.0 op_sel:[0,1,0]
	v_pk_fma_f32 v[32:33], v[160:161], s[70:71], v[32:33] op_sel:[0,1,0] op_sel_hi:[1,1,1]
	v_cvt_scalef32_pk_f32_fp4 v[20:21], v124, 1.0 op_sel:[1,1,0]
	v_pk_fma_f32 v[34:35], v[162:163], s[70:71], v[34:35] op_sel:[0,1,0] op_sel_hi:[1,1,1]
	v_cvt_scalef32_pk_f32_fp4 v[22:23], v125, 1.0
	v_pk_fma_f32 v[36:37], v[18:19], s[70:71], v[36:37] op_sel:[0,1,0] op_sel_hi:[1,1,1]
	v_cvt_scalef32_pk_f32_fp4 v[30:31], v125, 1.0 op_sel:[1,0,0]
	v_pk_fma_f32 v[38:39], v[20:21], s[70:71], v[38:39] op_sel:[0,1,0] op_sel_hi:[1,1,1]
	v_cvt_scalef32_pk_f32_fp4 v[2:3], v125, 1.0 op_sel:[0,1,0]
	v_pk_fma_f32 v[40:41], v[22:23], s[70:71], v[40:41] op_sel:[0,1,0] op_sel_hi:[1,1,1]
	v_cvt_scalef32_pk_f32_fp4 v[6:7], v125, 1.0 op_sel:[1,1,0]
	v_pk_fma_f32 v[42:43], v[30:31], s[70:71], v[42:43] op_sel:[0,1,0] op_sel_hi:[1,1,1]
	v_cvt_scalef32_pk_f32_fp4 v[160:161], v126, 1.0
	v_pk_fma_f32 v[44:45], v[2:3], s[70:71], v[44:45] op_sel:[0,1,0] op_sel_hi:[1,1,1]
	v_cvt_scalef32_pk_f32_fp4 v[162:163], v126, 1.0 op_sel:[1,0,0]
	v_pk_fma_f32 v[46:47], v[6:7], s[70:71], v[46:47] op_sel:[0,1,0] op_sel_hi:[1,1,1]
	v_cvt_scalef32_pk_f32_fp4 v[18:19], v126, 1.0 op_sel:[0,1,0]
	v_pk_fma_f32 v[48:49], v[160:161], s[70:71], v[48:49] op_sel:[0,1,0] op_sel_hi:[1,1,1]
	v_cvt_scalef32_pk_f32_fp4 v[20:21], v126, 1.0 op_sel:[1,1,0]
	v_pk_fma_f32 v[50:51], v[162:163], s[70:71], v[50:51] op_sel:[0,1,0] op_sel_hi:[1,1,1]
	v_cvt_scalef32_pk_f32_fp4 v[22:23], v127, 1.0
	v_pk_fma_f32 v[52:53], v[18:19], s[70:71], v[52:53] op_sel:[0,1,0] op_sel_hi:[1,1,1]
	v_cvt_scalef32_pk_f32_fp4 v[30:31], v127, 1.0 op_sel:[1,0,0]
	v_pk_fma_f32 v[54:55], v[20:21], s[70:71], v[54:55] op_sel:[0,1,0] op_sel_hi:[1,1,1]
	v_cvt_scalef32_pk_f32_fp4 v[2:3], v127, 1.0 op_sel:[0,1,0]
	v_pk_fma_f32 v[56:57], v[22:23], s[70:71], v[56:57] op_sel:[0,1,0] op_sel_hi:[1,1,1]
	v_cvt_scalef32_pk_f32_fp4 v[6:7], v127, 1.0 op_sel:[1,1,0]
	v_pk_fma_f32 v[58:59], v[30:31], s[70:71], v[58:59] op_sel:[0,1,0] op_sel_hi:[1,1,1]
	v_pk_fma_f32 v[60:61], v[2:3], s[70:71], v[60:61] op_sel:[0,1,0] op_sel_hi:[1,1,1]
	v_pk_fma_f32 v[62:63], v[6:7], s[70:71], v[62:63] op_sel:[0,1,0] op_sel_hi:[1,1,1]
	ds_read_b128 v[10:13], v25
	ds_read_b128 v[18:21], v25 offset:16
	v_add_u32_e32 v25, 32, v25
	ds_read_b32 v232, v26
	ds_read_b32 v233, v27
	ds_read_b32 v234, v26 offset:512
	ds_read_b32 v235, v27 offset:512
	v_add_u32_e32 v26, 32, v26
	v_add_u32_e32 v27, 32, v27
	s_waitcnt vmcnt(30)
	v_mov_b32_e32 v216, 0
	v_mov_b32_e32 v224, 0
	v_dot8c_i32_i4_e32 v216, v128, v208
	v_dot8c_i32_i4_e32 v224, v128, v212
	v_dot8c_i32_i4_e32 v216, v129, v209
	v_dot8c_i32_i4_e32 v224, v129, v213
	v_dot8c_i32_i4_e32 v216, v130, v210
	v_dot8c_i32_i4_e32 v224, v130, v214
	v_dot8c_i32_i4_e32 v216, v131, v211
	v_dot8c_i32_i4_e32 v224, v131, v215
	s_waitcnt vmcnt(26)
	v_mov_b32_e32 v217, 0
	v_mov_b32_e32 v225, 0
	v_dot8c_i32_i4_e32 v217, v132, v208
	v_dot8c_i32_i4_e32 v225, v132, v212
	v_dot8c_i32_i4_e32 v217, v133, v209
	v_dot8c_i32_i4_e32 v225, v133, v213
	v_dot8c_i32_i4_e32 v217, v134, v210
	v_dot8c_i32_i4_e32 v225, v134, v214
	v_dot8c_i32_i4_e32 v217, v135, v211
	v_dot8c_i32_i4_e32 v225, v135, v215
	s_waitcnt vmcnt(22)
	v_mov_b32_e32 v218, 0
	v_mov_b32_e32 v226, 0
	v_dot8c_i32_i4_e32 v218, v136, v208
	v_dot8c_i32_i4_e32 v226, v136, v212
	v_dot8c_i32_i4_e32 v218, v137, v209
	v_dot8c_i32_i4_e32 v226, v137, v213
	v_dot8c_i32_i4_e32 v218, v138, v210
	v_dot8c_i32_i4_e32 v226, v138, v214
	v_dot8c_i32_i4_e32 v218, v139, v211
	v_dot8c_i32_i4_e32 v226, v139, v215
	s_waitcnt vmcnt(18)
	v_mov_b32_e32 v219, 0
	v_mov_b32_e32 v227, 0
	v_dot8c_i32_i4_e32 v219, v140, v208
	v_dot8c_i32_i4_e32 v227, v140, v212
	v_dot8c_i32_i4_e32 v219, v141, v209
	v_dot8c_i32_i4_e32 v227, v141, v213
	v_dot8c_i32_i4_e32 v219, v142, v210
	v_dot8c_i32_i4_e32 v227, v142, v214
	v_dot8c_i32_i4_e32 v219, v143, v211
	v_dot8c_i32_i4_e32 v227, v143, v215
	s_waitcnt vmcnt(14)
	v_mov_b32_e32 v220, 0
	v_mov_b32_e32 v228, 0
	v_dot8c_i32_i4_e32 v220, v144, v208
	v_dot8c_i32_i4_e32 v228, v144, v212
	v_dot8c_i32_i4_e32 v220, v145, v209
	v_dot8c_i32_i4_e32 v228, v145, v213
	v_dot8c_i32_i4_e32 v220, v146, v210
	v_dot8c_i32_i4_e32 v228, v146, v214
	v_dot8c_i32_i4_e32 v220, v147, v211
	v_dot8c_i32_i4_e32 v228, v147, v215
	s_waitcnt vmcnt(10)
	v_mov_b32_e32 v221, 0
	v_mov_b32_e32 v229, 0
	v_dot8c_i32_i4_e32 v221, v148, v208
	v_dot8c_i32_i4_e32 v229, v148, v212
	v_dot8c_i32_i4_e32 v221, v149, v209
	v_dot8c_i32_i4_e32 v229, v149, v213
	v_dot8c_i32_i4_e32 v221, v150, v210
	v_dot8c_i32_i4_e32 v229, v150, v214
	v_dot8c_i32_i4_e32 v221, v151, v211
	v_dot8c_i32_i4_e32 v229, v151, v215
	s_waitcnt vmcnt(6)
	v_mov_b32_e32 v222, 0
	v_mov_b32_e32 v230, 0
	v_dot8c_i32_i4_e32 v222, v152, v208
	v_dot8c_i32_i4_e32 v230, v152, v212
	v_dot8c_i32_i4_e32 v222, v153, v209
	v_dot8c_i32_i4_e32 v230, v153, v213
	v_dot8c_i32_i4_e32 v222, v154, v210
	v_dot8c_i32_i4_e32 v230, v154, v214
	v_dot8c_i32_i4_e32 v222, v155, v211
	v_dot8c_i32_i4_e32 v230, v155, v215
	s_waitcnt vmcnt(2)
	v_mov_b32_e32 v223, 0
	v_mov_b32_e32 v231, 0
	v_dot8c_i32_i4_e32 v223, v156, v208
	v_dot8c_i32_i4_e32 v231, v156, v212
	v_dot8c_i32_i4_e32 v223, v157, v209
	v_dot8c_i32_i4_e32 v231, v157, v213
	v_dot8c_i32_i4_e32 v223, v158, v210
	v_dot8c_i32_i4_e32 v231, v158, v214
	v_dot8c_i32_i4_e32 v223, v159, v211
	v_dot8c_i32_i4_e32 v231, v159, v215
	s_nop 2
	v_mad_i32_i24 v216, v216, 14, v224
	v_mad_i32_i24 v217, v217, 14, v225
	v_mad_i32_i24 v218, v218, 14, v226
	v_mad_i32_i24 v219, v219, 14, v227
	v_mad_i32_i24 v220, v220, 14, v228
	v_mad_i32_i24 v221, v221, 14, v229
	v_mad_i32_i24 v222, v222, 14, v230
	v_mad_i32_i24 v223, v223, 14, v231
	s_waitcnt lgkmcnt(4)
	v_readfirstlane_b32 s33, v10
	s_lshl_b32 s33, s33, 10
	s_add_u32 s72, s94, s33
	s_addc_u32 s73, s95, 0
	global_load_dwordx2 v[64:65], v28, s[72:73]
	global_load_dwordx2 v[66:67], v28, s[72:73] offset:512
	global_load_dwordx2 v[96:97], v29, s[72:73]
	global_load_dwordx2 v[98:99], v29, s[72:73] offset:512
	v_readfirstlane_b32 s33, v11
	s_lshl_b32 s33, s33, 10
	s_add_u32 s72, s94, s33
	s_addc_u32 s73, s95, 0
	global_load_dwordx2 v[68:69], v28, s[72:73]
	global_load_dwordx2 v[70:71], v28, s[72:73] offset:512
	global_load_dwordx2 v[100:101], v29, s[72:73]
	global_load_dwordx2 v[102:103], v29, s[72:73] offset:512
	v_readfirstlane_b32 s33, v12
	s_lshl_b32 s33, s33, 10
	s_add_u32 s72, s94, s33
	s_addc_u32 s73, s95, 0
	global_load_dwordx2 v[72:73], v28, s[72:73]
	global_load_dwordx2 v[74:75], v28, s[72:73] offset:512
	global_load_dwordx2 v[104:105], v29, s[72:73]
	global_load_dwordx2 v[106:107], v29, s[72:73] offset:512
	v_readfirstlane_b32 s33, v13
	s_lshl_b32 s33, s33, 10
	s_add_u32 s72, s94, s33
	s_addc_u32 s73, s95, 0
	global_load_dwordx2 v[76:77], v28, s[72:73]
	global_load_dwordx2 v[78:79], v28, s[72:73] offset:512
	global_load_dwordx2 v[108:109], v29, s[72:73]
	global_load_dwordx2 v[110:111], v29, s[72:73] offset:512
	v_readfirstlane_b32 s33, v18
	s_lshl_b32 s33, s33, 10
	s_add_u32 s72, s94, s33
	s_addc_u32 s73, s95, 0
	global_load_dwordx2 v[80:81], v28, s[72:73]
	global_load_dwordx2 v[82:83], v28, s[72:73] offset:512
	global_load_dwordx2 v[112:113], v29, s[72:73]
	global_load_dwordx2 v[114:115], v29, s[72:73] offset:512
	v_readfirstlane_b32 s33, v19
	s_lshl_b32 s33, s33, 10
	s_add_u32 s72, s94, s33
	s_addc_u32 s73, s95, 0
	global_load_dwordx2 v[84:85], v28, s[72:73]
	global_load_dwordx2 v[86:87], v28, s[72:73] offset:512
	global_load_dwordx2 v[116:117], v29, s[72:73]
	global_load_dwordx2 v[118:119], v29, s[72:73] offset:512
	v_readfirstlane_b32 s33, v20
	s_lshl_b32 s33, s33, 10
	s_add_u32 s72, s94, s33
	s_addc_u32 s73, s95, 0
	global_load_dwordx2 v[88:89], v28, s[72:73]
	global_load_dwordx2 v[90:91], v28, s[72:73] offset:512
	global_load_dwordx2 v[120:121], v29, s[72:73]
	global_load_dwordx2 v[122:123], v29, s[72:73] offset:512
	v_readfirstlane_b32 s33, v21
	s_lshl_b32 s33, s33, 10
	s_add_u32 s72, s94, s33
	s_addc_u32 s73, s95, 0
	global_load_dwordx2 v[92:93], v28, s[72:73]
	global_load_dwordx2 v[94:95], v28, s[72:73] offset:512
	global_load_dwordx2 v[124:125], v29, s[72:73]
	global_load_dwordx2 v[126:127], v29, s[72:73] offset:512
	s_nop 1
	v_permlane32_swap_b32_e32 v216, v217
	v_permlane32_swap_b32_e32 v218, v219
	v_permlane32_swap_b32_e32 v220, v221
	v_permlane32_swap_b32_e32 v222, v223
	v_add_u32_e32 v216, v216, v217
	v_add_u32_e32 v218, v218, v219
	v_add_u32_e32 v220, v220, v221
	v_add_u32_e32 v222, v222, v223
	s_nop 1
	v_permlane16_swap_b32_e32 v216, v218
	v_permlane16_swap_b32_e32 v220, v222
	v_add_u32_e32 v216, v216, v218
	v_add_u32_e32 v220, v220, v222
	s_nop 1
	v_add_u32_dpp v216, v216, v216 row_ror:8 row_mask:0xf bank_mask:0xf
	v_add_u32_dpp v220, v220, v220 row_ror:8 row_mask:0xf bank_mask:0xf
	s_nop 1
	v_add_u32_dpp v216, v216, v216 row_ror:4 row_mask:0xf bank_mask:0xf
	v_add_u32_dpp v220, v220, v220 row_ror:4 row_mask:0xf bank_mask:0xf
	s_nop 1
	v_add_u32_dpp v216, v216, v216 row_ror:2 row_mask:0xf bank_mask:0xf
	v_add_u32_dpp v220, v220, v220 row_ror:2 row_mask:0xf bank_mask:0xf
	s_nop 1
	v_add_u32_dpp v216, v216, v216 row_ror:1 row_mask:0xf bank_mask:0xf
	v_add_u32_dpp v220, v220, v220 row_ror:1 row_mask:0xf bank_mask:0xf
	s_waitcnt lgkmcnt(0)
	v_cvt_f32_i32_e32 v216, v216
	v_cvt_f32_i32_e32 v220, v220
	v_mul_f32_e32 v216, v216, v232
	v_mul_f32_e32 v220, v220, v233
	v_fma_f32 v2, |v216|, s83, 1.0
	v_fma_f32 v7, |v220|, s83, 1.0
	v_rcp_f32_e32 v2, v2
	v_rcp_f32_e32 v7, v7
	v_mul_f32_e32 v5, v216, v216
	v_mul_f32_e32 v11, v220, v220
	v_mul_f32_e32 v5, 0xbf38aa3b, v5
	v_mul_f32_e32 v11, 0xbf38aa3b, v11
	v_exp_f32_e32 v5, v5
	v_exp_f32_e32 v11, v11
	v_fmamk_f32 v3, v2, 0x3f07dc22, v172
	v_fmamk_f32 v10, v7, 0x3f07dc22, v172
	v_fmaak_f32 v3, v2, v3, 0x3f35f0e3
	v_fmaak_f32 v10, v7, v10, 0x3f35f0e3
	v_fmaak_f32 v3, v2, v3, 0xbe11a98e
	v_fmaak_f32 v10, v7, v10, 0xbe11a98e
	v_fmaak_f32 v3, v2, v3, 0x3e027906
	v_fmaak_f32 v10, v7, v10, 0x3e027906
	v_mul_f32_e32 v3, v2, v3
	v_mul_f32_e32 v10, v7, v10
	v_mul_f32_e32 v3, v5, v3
	v_mul_f32_e32 v10, v11, v10
	v_mul_f32_e32 v6, v216, v3
	v_mul_f32_e32 v12, v220, v10
	v_fma_f32 v3, -v216, v3, v216
	v_fma_f32 v10, -v220, v10, v220
	v_cmp_gt_f32_e32 vcc, 0, v216
	v_cmp_gt_f32_e64 s[96:97], 0, v220
	s_nop 1
	v_cndmask_b32_e32 v216, v3, v6, vcc
	v_cndmask_b32_e64 v220, v10, v12, s[96:97]
	v_mul_f32_e32 v216, v216, v234
	v_mul_f32_e32 v220, v220, v235
	s_nop 0
	v_readlane_b32 s64, v216, 0
	v_readlane_b32 s65, v216, 32
	v_readlane_b32 s66, v216, 16
	v_readlane_b32 s67, v216, 48
	v_readlane_b32 s68, v220, 0
	v_readlane_b32 s69, v220, 32
	v_readlane_b32 s70, v220, 16
	v_readlane_b32 s71, v220, 48
	s_waitcnt vmcnt(60)
	v_cvt_scalef32_pk_f32_fp4 v[160:161], v176, 1.0
	v_cvt_scalef32_pk_f32_fp4 v[162:163], v176, 1.0 op_sel:[1,0,0]
	v_cvt_scalef32_pk_f32_fp4 v[18:19], v176, 1.0 op_sel:[0,1,0]
	v_pk_fma_f32 v[32:33], v[160:161], s[64:65], v[32:33] op_sel_hi:[1,0,1]
	v_cvt_scalef32_pk_f32_fp4 v[20:21], v176, 1.0 op_sel:[1,1,0]
	v_pk_fma_f32 v[34:35], v[162:163], s[64:65], v[34:35] op_sel_hi:[1,0,1]
	v_cvt_scalef32_pk_f32_fp4 v[22:23], v177, 1.0
	v_pk_fma_f32 v[36:37], v[18:19], s[64:65], v[36:37] op_sel_hi:[1,0,1]
	v_cvt_scalef32_pk_f32_fp4 v[30:31], v177, 1.0 op_sel:[1,0,0]
	v_pk_fma_f32 v[38:39], v[20:21], s[64:65], v[38:39] op_sel_hi:[1,0,1]
	v_cvt_scalef32_pk_f32_fp4 v[2:3], v177, 1.0 op_sel:[0,1,0]
	v_pk_fma_f32 v[40:41], v[22:23], s[64:65], v[40:41] op_sel_hi:[1,0,1]
	v_cvt_scalef32_pk_f32_fp4 v[6:7], v177, 1.0 op_sel:[1,1,0]
	v_pk_fma_f32 v[42:43], v[30:31], s[64:65], v[42:43] op_sel_hi:[1,0,1]
	v_cvt_scalef32_pk_f32_fp4 v[160:161], v178, 1.0
	v_pk_fma_f32 v[44:45], v[2:3], s[64:65], v[44:45] op_sel_hi:[1,0,1]
	v_cvt_scalef32_pk_f32_fp4 v[162:163], v178, 1.0 op_sel:[1,0,0]
	v_pk_fma_f32 v[46:47], v[6:7], s[64:65], v[46:47] op_sel_hi:[1,0,1]
	v_cvt_scalef32_pk_f32_fp4 v[18:19], v178, 1.0 op_sel:[0,1,0]
	v_pk_fma_f32 v[48:49], v[160:161], s[64:65], v[48:49] op_sel_hi:[1,0,1]
	v_cvt_scalef32_pk_f32_fp4 v[20:21], v178, 1.0 op_sel:[1,1,0]
	v_pk_fma_f32 v[50:51], v[162:163], s[64:65], v[50:51] op_sel_hi:[1,0,1]
	v_cvt_scalef32_pk_f32_fp4 v[22:23], v179, 1.0
	v_pk_fma_f32 v[52:53], v[18:19], s[64:65], v[52:53] op_sel_hi:[1,0,1]
	v_cvt_scalef32_pk_f32_fp4 v[30:31], v179, 1.0 op_sel:[1,0,0]
	v_pk_fma_f32 v[54:55], v[20:21], s[64:65], v[54:55] op_sel_hi:[1,0,1]
	v_cvt_scalef32_pk_f32_fp4 v[2:3], v179, 1.0 op_sel:[0,1,0]
	v_pk_fma_f32 v[56:57], v[22:23], s[64:65], v[56:57] op_sel_hi:[1,0,1]
	v_cvt_scalef32_pk_f32_fp4 v[6:7], v179, 1.0 op_sel:[1,1,0]
	v_pk_fma_f32 v[58:59], v[30:31], s[64:65], v[58:59] op_sel_hi:[1,0,1]
	v_pk_fma_f32 v[60:61], v[2:3], s[64:65], v[60:61] op_sel_hi:[1,0,1]
	v_pk_fma_f32 v[62:63], v[6:7], s[64:65], v[62:63] op_sel_hi:[1,0,1]
	s_waitcnt vmcnt(56)
	v_cvt_scalef32_pk_f32_fp4 v[160:161], v180, 1.0
	v_cvt_scalef32_pk_f32_fp4 v[162:163], v180, 1.0 op_sel:[1,0,0]
	v_cvt_scalef32_pk_f32_fp4 v[18:19], v180, 1.0 op_sel:[0,1,0]
	v_pk_fma_f32 v[32:33], v[160:161], s[64:65], v[32:33] op_sel:[0,1,0] op_sel_hi:[1,1,1]
	v_cvt_scalef32_pk_f32_fp4 v[20:21], v180, 1.0 op_sel:[1,1,0]
	v_pk_fma_f32 v[34:35], v[162:163], s[64:65], v[34:35] op_sel:[0,1,0] op_sel_hi:[1,1,1]
	v_cvt_scalef32_pk_f32_fp4 v[22:23], v181, 1.0
	v_pk_fma_f32 v[36:37], v[18:19], s[64:65], v[36:37] op_sel:[0,1,0] op_sel_hi:[1,1,1]
	v_cvt_scalef32_pk_f32_fp4 v[30:31], v181, 1.0 op_sel:[1,0,0]
	v_pk_fma_f32 v[38:39], v[20:21], s[64:65], v[38:39] op_sel:[0,1,0] op_sel_hi:[1,1,1]
	v_cvt_scalef32_pk_f32_fp4 v[2:3], v181, 1.0 op_sel:[0,1,0]
	v_pk_fma_f32 v[40:41], v[22:23], s[64:65], v[40:41] op_sel:[0,1,0] op_sel_hi:[1,1,1]
	v_cvt_scalef32_pk_f32_fp4 v[6:7], v181, 1.0 op_sel:[1,1,0]
	v_pk_fma_f32 v[42:43], v[30:31], s[64:65], v[42:43] op_sel:[0,1,0] op_sel_hi:[1,1,1]
	v_cvt_scalef32_pk_f32_fp4 v[160:161], v182, 1.0
	v_pk_fma_f32 v[44:45], v[2:3], s[64:65], v[44:45] op_sel:[0,1,0] op_sel_hi:[1,1,1]
	v_cvt_scalef32_pk_f32_fp4 v[162:163], v182, 1.0 op_sel:[1,0,0]
	v_pk_fma_f32 v[46:47], v[6:7], s[64:65], v[46:47] op_sel:[0,1,0] op_sel_hi:[1,1,1]
	v_cvt_scalef32_pk_f32_fp4 v[18:19], v182, 1.0 op_sel:[0,1,0]
	v_pk_fma_f32 v[48:49], v[160:161], s[64:65], v[48:49] op_sel:[0,1,0] op_sel_hi:[1,1,1]
	v_cvt_scalef32_pk_f32_fp4 v[20:21], v182, 1.0 op_sel:[1,1,0]
	v_pk_fma_f32 v[50:51], v[162:163], s[64:65], v[50:51] op_sel:[0,1,0] op_sel_hi:[1,1,1]
	v_cvt_scalef32_pk_f32_fp4 v[22:23], v183, 1.0
	v_pk_fma_f32 v[52:53], v[18:19], s[64:65], v[52:53] op_sel:[0,1,0] op_sel_hi:[1,1,1]
	v_cvt_scalef32_pk_f32_fp4 v[30:31], v183, 1.0 op_sel:[1,0,0]
	v_pk_fma_f32 v[54:55], v[20:21], s[64:65], v[54:55] op_sel:[0,1,0] op_sel_hi:[1,1,1]
	v_cvt_scalef32_pk_f32_fp4 v[2:3], v183, 1.0 op_sel:[0,1,0]
	v_pk_fma_f32 v[56:57], v[22:23], s[64:65], v[56:57] op_sel:[0,1,0] op_sel_hi:[1,1,1]
	v_cvt_scalef32_pk_f32_fp4 v[6:7], v183, 1.0 op_sel:[1,1,0]
	v_pk_fma_f32 v[58:59], v[30:31], s[64:65], v[58:59] op_sel:[0,1,0] op_sel_hi:[1,1,1]
	v_pk_fma_f32 v[60:61], v[2:3], s[64:65], v[60:61] op_sel:[0,1,0] op_sel_hi:[1,1,1]
	v_pk_fma_f32 v[62:63], v[6:7], s[64:65], v[62:63] op_sel:[0,1,0] op_sel_hi:[1,1,1]
	s_waitcnt vmcnt(52)
	v_cvt_scalef32_pk_f32_fp4 v[160:161], v184, 1.0
	v_cvt_scalef32_pk_f32_fp4 v[162:163], v184, 1.0 op_sel:[1,0,0]
	v_cvt_scalef32_pk_f32_fp4 v[18:19], v184, 1.0 op_sel:[0,1,0]
	v_pk_fma_f32 v[32:33], v[160:161], s[66:67], v[32:33] op_sel_hi:[1,0,1]
	v_cvt_scalef32_pk_f32_fp4 v[20:21], v184, 1.0 op_sel:[1,1,0]
	v_pk_fma_f32 v[34:35], v[162:163], s[66:67], v[34:35] op_sel_hi:[1,0,1]
	v_cvt_scalef32_pk_f32_fp4 v[22:23], v185, 1.0
	v_pk_fma_f32 v[36:37], v[18:19], s[66:67], v[36:37] op_sel_hi:[1,0,1]
	v_cvt_scalef32_pk_f32_fp4 v[30:31], v185, 1.0 op_sel:[1,0,0]
	v_pk_fma_f32 v[38:39], v[20:21], s[66:67], v[38:39] op_sel_hi:[1,0,1]
	v_cvt_scalef32_pk_f32_fp4 v[2:3], v185, 1.0 op_sel:[0,1,0]
	v_pk_fma_f32 v[40:41], v[22:23], s[66:67], v[40:41] op_sel_hi:[1,0,1]
	v_cvt_scalef32_pk_f32_fp4 v[6:7], v185, 1.0 op_sel:[1,1,0]
	v_pk_fma_f32 v[42:43], v[30:31], s[66:67], v[42:43] op_sel_hi:[1,0,1]
	v_cvt_scalef32_pk_f32_fp4 v[160:161], v186, 1.0
	v_pk_fma_f32 v[44:45], v[2:3], s[66:67], v[44:45] op_sel_hi:[1,0,1]
	v_cvt_scalef32_pk_f32_fp4 v[162:163], v186, 1.0 op_sel:[1,0,0]
	v_pk_fma_f32 v[46:47], v[6:7], s[66:67], v[46:47] op_sel_hi:[1,0,1]
	v_cvt_scalef32_pk_f32_fp4 v[18:19], v186, 1.0 op_sel:[0,1,0]
	v_pk_fma_f32 v[48:49], v[160:161], s[66:67], v[48:49] op_sel_hi:[1,0,1]
	v_cvt_scalef32_pk_f32_fp4 v[20:21], v186, 1.0 op_sel:[1,1,0]
	v_pk_fma_f32 v[50:51], v[162:163], s[66:67], v[50:51] op_sel_hi:[1,0,1]
	v_cvt_scalef32_pk_f32_fp4 v[22:23], v187, 1.0
	v_pk_fma_f32 v[52:53], v[18:19], s[66:67], v[52:53] op_sel_hi:[1,0,1]
	v_cvt_scalef32_pk_f32_fp4 v[30:31], v187, 1.0 op_sel:[1,0,0]
	v_pk_fma_f32 v[54:55], v[20:21], s[66:67], v[54:55] op_sel_hi:[1,0,1]
	v_cvt_scalef32_pk_f32_fp4 v[2:3], v187, 1.0 op_sel:[0,1,0]
	v_pk_fma_f32 v[56:57], v[22:23], s[66:67], v[56:57] op_sel_hi:[1,0,1]
	v_cvt_scalef32_pk_f32_fp4 v[6:7], v187, 1.0 op_sel:[1,1,0]
	v_pk_fma_f32 v[58:59], v[30:31], s[66:67], v[58:59] op_sel_hi:[1,0,1]
	v_pk_fma_f32 v[60:61], v[2:3], s[66:67], v[60:61] op_sel_hi:[1,0,1]
	v_pk_fma_f32 v[62:63], v[6:7], s[66:67], v[62:63] op_sel_hi:[1,0,1]
	s_waitcnt vmcnt(48)
	v_cvt_scalef32_pk_f32_fp4 v[160:161], v188, 1.0
	v_cvt_scalef32_pk_f32_fp4 v[162:163], v188, 1.0 op_sel:[1,0,0]
	v_cvt_scalef32_pk_f32_fp4 v[18:19], v188, 1.0 op_sel:[0,1,0]
	v_pk_fma_f32 v[32:33], v[160:161], s[66:67], v[32:33] op_sel:[0,1,0] op_sel_hi:[1,1,1]
	v_cvt_scalef32_pk_f32_fp4 v[20:21], v188, 1.0 op_sel:[1,1,0]
	v_pk_fma_f32 v[34:35], v[162:163], s[66:67], v[34:35] op_sel:[0,1,0] op_sel_hi:[1,1,1]
	v_cvt_scalef32_pk_f32_fp4 v[22:23], v189, 1.0
	v_pk_fma_f32 v[36:37], v[18:19], s[66:67], v[36:37] op_sel:[0,1,0] op_sel_hi:[1,1,1]
	v_cvt_scalef32_pk_f32_fp4 v[30:31], v189, 1.0 op_sel:[1,0,0]
	v_pk_fma_f32 v[38:39], v[20:21], s[66:67], v[38:39] op_sel:[0,1,0] op_sel_hi:[1,1,1]
	v_cvt_scalef32_pk_f32_fp4 v[2:3], v189, 1.0 op_sel:[0,1,0]
	v_pk_fma_f32 v[40:41], v[22:23], s[66:67], v[40:41] op_sel:[0,1,0] op_sel_hi:[1,1,1]
	v_cvt_scalef32_pk_f32_fp4 v[6:7], v189, 1.0 op_sel:[1,1,0]
	v_pk_fma_f32 v[42:43], v[30:31], s[66:67], v[42:43] op_sel:[0,1,0] op_sel_hi:[1,1,1]
	v_cvt_scalef32_pk_f32_fp4 v[160:161], v190, 1.0
	v_pk_fma_f32 v[44:45], v[2:3], s[66:67], v[44:45] op_sel:[0,1,0] op_sel_hi:[1,1,1]
	v_cvt_scalef32_pk_f32_fp4 v[162:163], v190, 1.0 op_sel:[1,0,0]
	v_pk_fma_f32 v[46:47], v[6:7], s[66:67], v[46:47] op_sel:[0,1,0] op_sel_hi:[1,1,1]
	v_cvt_scalef32_pk_f32_fp4 v[18:19], v190, 1.0 op_sel:[0,1,0]
	v_pk_fma_f32 v[48:49], v[160:161], s[66:67], v[48:49] op_sel:[0,1,0] op_sel_hi:[1,1,1]
	v_cvt_scalef32_pk_f32_fp4 v[20:21], v190, 1.0 op_sel:[1,1,0]
	v_pk_fma_f32 v[50:51], v[162:163], s[66:67], v[50:51] op_sel:[0,1,0] op_sel_hi:[1,1,1]
	v_cvt_scalef32_pk_f32_fp4 v[22:23], v191, 1.0
	v_pk_fma_f32 v[52:53], v[18:19], s[66:67], v[52:53] op_sel:[0,1,0] op_sel_hi:[1,1,1]
	v_cvt_scalef32_pk_f32_fp4 v[30:31], v191, 1.0 op_sel:[1,0,0]
	v_pk_fma_f32 v[54:55], v[20:21], s[66:67], v[54:55] op_sel:[0,1,0] op_sel_hi:[1,1,1]
	v_cvt_scalef32_pk_f32_fp4 v[2:3], v191, 1.0 op_sel:[0,1,0]
	v_pk_fma_f32 v[56:57], v[22:23], s[66:67], v[56:57] op_sel:[0,1,0] op_sel_hi:[1,1,1]
	v_cvt_scalef32_pk_f32_fp4 v[6:7], v191, 1.0 op_sel:[1,1,0]
	v_pk_fma_f32 v[58:59], v[30:31], s[66:67], v[58:59] op_sel:[0,1,0] op_sel_hi:[1,1,1]
	v_pk_fma_f32 v[60:61], v[2:3], s[66:67], v[60:61] op_sel:[0,1,0] op_sel_hi:[1,1,1]
	v_pk_fma_f32 v[62:63], v[6:7], s[66:67], v[62:63] op_sel:[0,1,0] op_sel_hi:[1,1,1]
	s_waitcnt vmcnt(44)
	v_cvt_scalef32_pk_f32_fp4 v[160:161], v192, 1.0
	v_cvt_scalef32_pk_f32_fp4 v[162:163], v192, 1.0 op_sel:[1,0,0]
	v_cvt_scalef32_pk_f32_fp4 v[18:19], v192, 1.0 op_sel:[0,1,0]
	v_pk_fma_f32 v[32:33], v[160:161], s[68:69], v[32:33] op_sel_hi:[1,0,1]
	v_cvt_scalef32_pk_f32_fp4 v[20:21], v192, 1.0 op_sel:[1,1,0]
	v_pk_fma_f32 v[34:35], v[162:163], s[68:69], v[34:35] op_sel_hi:[1,0,1]
	v_cvt_scalef32_pk_f32_fp4 v[22:23], v193, 1.0
	v_pk_fma_f32 v[36:37], v[18:19], s[68:69], v[36:37] op_sel_hi:[1,0,1]
	v_cvt_scalef32_pk_f32_fp4 v[30:31], v193, 1.0 op_sel:[1,0,0]
	v_pk_fma_f32 v[38:39], v[20:21], s[68:69], v[38:39] op_sel_hi:[1,0,1]
	v_cvt_scalef32_pk_f32_fp4 v[2:3], v193, 1.0 op_sel:[0,1,0]
	v_pk_fma_f32 v[40:41], v[22:23], s[68:69], v[40:41] op_sel_hi:[1,0,1]
	v_cvt_scalef32_pk_f32_fp4 v[6:7], v193, 1.0 op_sel:[1,1,0]
	v_pk_fma_f32 v[42:43], v[30:31], s[68:69], v[42:43] op_sel_hi:[1,0,1]
	v_cvt_scalef32_pk_f32_fp4 v[160:161], v194, 1.0
	v_pk_fma_f32 v[44:45], v[2:3], s[68:69], v[44:45] op_sel_hi:[1,0,1]
	v_cvt_scalef32_pk_f32_fp4 v[162:163], v194, 1.0 op_sel:[1,0,0]
	v_pk_fma_f32 v[46:47], v[6:7], s[68:69], v[46:47] op_sel_hi:[1,0,1]
	v_cvt_scalef32_pk_f32_fp4 v[18:19], v194, 1.0 op_sel:[0,1,0]
	v_pk_fma_f32 v[48:49], v[160:161], s[68:69], v[48:49] op_sel_hi:[1,0,1]
	v_cvt_scalef32_pk_f32_fp4 v[20:21], v194, 1.0 op_sel:[1,1,0]
	v_pk_fma_f32 v[50:51], v[162:163], s[68:69], v[50:51] op_sel_hi:[1,0,1]
	v_cvt_scalef32_pk_f32_fp4 v[22:23], v195, 1.0
	v_pk_fma_f32 v[52:53], v[18:19], s[68:69], v[52:53] op_sel_hi:[1,0,1]
	v_cvt_scalef32_pk_f32_fp4 v[30:31], v195, 1.0 op_sel:[1,0,0]
	v_pk_fma_f32 v[54:55], v[20:21], s[68:69], v[54:55] op_sel_hi:[1,0,1]
	v_cvt_scalef32_pk_f32_fp4 v[2:3], v195, 1.0 op_sel:[0,1,0]
	v_pk_fma_f32 v[56:57], v[22:23], s[68:69], v[56:57] op_sel_hi:[1,0,1]
	v_cvt_scalef32_pk_f32_fp4 v[6:7], v195, 1.0 op_sel:[1,1,0]
	v_pk_fma_f32 v[58:59], v[30:31], s[68:69], v[58:59] op_sel_hi:[1,0,1]
	v_pk_fma_f32 v[60:61], v[2:3], s[68:69], v[60:61] op_sel_hi:[1,0,1]
	v_pk_fma_f32 v[62:63], v[6:7], s[68:69], v[62:63] op_sel_hi:[1,0,1]
	s_waitcnt vmcnt(40)
	v_cvt_scalef32_pk_f32_fp4 v[160:161], v196, 1.0
	v_cvt_scalef32_pk_f32_fp4 v[162:163], v196, 1.0 op_sel:[1,0,0]
	v_cvt_scalef32_pk_f32_fp4 v[18:19], v196, 1.0 op_sel:[0,1,0]
	v_pk_fma_f32 v[32:33], v[160:161], s[68:69], v[32:33] op_sel:[0,1,0] op_sel_hi:[1,1,1]
	v_cvt_scalef32_pk_f32_fp4 v[20:21], v196, 1.0 op_sel:[1,1,0]
	v_pk_fma_f32 v[34:35], v[162:163], s[68:69], v[34:35] op_sel:[0,1,0] op_sel_hi:[1,1,1]
	v_cvt_scalef32_pk_f32_fp4 v[22:23], v197, 1.0
	v_pk_fma_f32 v[36:37], v[18:19], s[68:69], v[36:37] op_sel:[0,1,0] op_sel_hi:[1,1,1]
	v_cvt_scalef32_pk_f32_fp4 v[30:31], v197, 1.0 op_sel:[1,0,0]
	v_pk_fma_f32 v[38:39], v[20:21], s[68:69], v[38:39] op_sel:[0,1,0] op_sel_hi:[1,1,1]
	v_cvt_scalef32_pk_f32_fp4 v[2:3], v197, 1.0 op_sel:[0,1,0]
	v_pk_fma_f32 v[40:41], v[22:23], s[68:69], v[40:41] op_sel:[0,1,0] op_sel_hi:[1,1,1]
	v_cvt_scalef32_pk_f32_fp4 v[6:7], v197, 1.0 op_sel:[1,1,0]
	v_pk_fma_f32 v[42:43], v[30:31], s[68:69], v[42:43] op_sel:[0,1,0] op_sel_hi:[1,1,1]
	v_cvt_scalef32_pk_f32_fp4 v[160:161], v198, 1.0
	v_pk_fma_f32 v[44:45], v[2:3], s[68:69], v[44:45] op_sel:[0,1,0] op_sel_hi:[1,1,1]
	v_cvt_scalef32_pk_f32_fp4 v[162:163], v198, 1.0 op_sel:[1,0,0]
	v_pk_fma_f32 v[46:47], v[6:7], s[68:69], v[46:47] op_sel:[0,1,0] op_sel_hi:[1,1,1]
	v_cvt_scalef32_pk_f32_fp4 v[18:19], v198, 1.0 op_sel:[0,1,0]
	v_pk_fma_f32 v[48:49], v[160:161], s[68:69], v[48:49] op_sel:[0,1,0] op_sel_hi:[1,1,1]
	v_cvt_scalef32_pk_f32_fp4 v[20:21], v198, 1.0 op_sel:[1,1,0]
	v_pk_fma_f32 v[50:51], v[162:163], s[68:69], v[50:51] op_sel:[0,1,0] op_sel_hi:[1,1,1]
	v_cvt_scalef32_pk_f32_fp4 v[22:23], v199, 1.0
	v_pk_fma_f32 v[52:53], v[18:19], s[68:69], v[52:53] op_sel:[0,1,0] op_sel_hi:[1,1,1]
	v_cvt_scalef32_pk_f32_fp4 v[30:31], v199, 1.0 op_sel:[1,0,0]
	v_pk_fma_f32 v[54:55], v[20:21], s[68:69], v[54:55] op_sel:[0,1,0] op_sel_hi:[1,1,1]
	v_cvt_scalef32_pk_f32_fp4 v[2:3], v199, 1.0 op_sel:[0,1,0]
	v_pk_fma_f32 v[56:57], v[22:23], s[68:69], v[56:57] op_sel:[0,1,0] op_sel_hi:[1,1,1]
	v_cvt_scalef32_pk_f32_fp4 v[6:7], v199, 1.0 op_sel:[1,1,0]
	v_pk_fma_f32 v[58:59], v[30:31], s[68:69], v[58:59] op_sel:[0,1,0] op_sel_hi:[1,1,1]
	v_pk_fma_f32 v[60:61], v[2:3], s[68:69], v[60:61] op_sel:[0,1,0] op_sel_hi:[1,1,1]
	v_pk_fma_f32 v[62:63], v[6:7], s[68:69], v[62:63] op_sel:[0,1,0] op_sel_hi:[1,1,1]
	s_waitcnt vmcnt(36)
	v_cvt_scalef32_pk_f32_fp4 v[160:161], v200, 1.0
	v_cvt_scalef32_pk_f32_fp4 v[162:163], v200, 1.0 op_sel:[1,0,0]
	v_cvt_scalef32_pk_f32_fp4 v[18:19], v200, 1.0 op_sel:[0,1,0]
	v_pk_fma_f32 v[32:33], v[160:161], s[70:71], v[32:33] op_sel_hi:[1,0,1]
	v_cvt_scalef32_pk_f32_fp4 v[20:21], v200, 1.0 op_sel:[1,1,0]
	v_pk_fma_f32 v[34:35], v[162:163], s[70:71], v[34:35] op_sel_hi:[1,0,1]
	v_cvt_scalef32_pk_f32_fp4 v[22:23], v201, 1.0
	v_pk_fma_f32 v[36:37], v[18:19], s[70:71], v[36:37] op_sel_hi:[1,0,1]
	v_cvt_scalef32_pk_f32_fp4 v[30:31], v201, 1.0 op_sel:[1,0,0]
	v_pk_fma_f32 v[38:39], v[20:21], s[70:71], v[38:39] op_sel_hi:[1,0,1]
	v_cvt_scalef32_pk_f32_fp4 v[2:3], v201, 1.0 op_sel:[0,1,0]
	v_pk_fma_f32 v[40:41], v[22:23], s[70:71], v[40:41] op_sel_hi:[1,0,1]
	v_cvt_scalef32_pk_f32_fp4 v[6:7], v201, 1.0 op_sel:[1,1,0]
	v_pk_fma_f32 v[42:43], v[30:31], s[70:71], v[42:43] op_sel_hi:[1,0,1]
	v_cvt_scalef32_pk_f32_fp4 v[160:161], v202, 1.0
	v_pk_fma_f32 v[44:45], v[2:3], s[70:71], v[44:45] op_sel_hi:[1,0,1]
	v_cvt_scalef32_pk_f32_fp4 v[162:163], v202, 1.0 op_sel:[1,0,0]
	v_pk_fma_f32 v[46:47], v[6:7], s[70:71], v[46:47] op_sel_hi:[1,0,1]
	v_cvt_scalef32_pk_f32_fp4 v[18:19], v202, 1.0 op_sel:[0,1,0]
	v_pk_fma_f32 v[48:49], v[160:161], s[70:71], v[48:49] op_sel_hi:[1,0,1]
	v_cvt_scalef32_pk_f32_fp4 v[20:21], v202, 1.0 op_sel:[1,1,0]
	v_pk_fma_f32 v[50:51], v[162:163], s[70:71], v[50:51] op_sel_hi:[1,0,1]
	v_cvt_scalef32_pk_f32_fp4 v[22:23], v203, 1.0
	v_pk_fma_f32 v[52:53], v[18:19], s[70:71], v[52:53] op_sel_hi:[1,0,1]
	v_cvt_scalef32_pk_f32_fp4 v[30:31], v203, 1.0 op_sel:[1,0,0]
	v_pk_fma_f32 v[54:55], v[20:21], s[70:71], v[54:55] op_sel_hi:[1,0,1]
	v_cvt_scalef32_pk_f32_fp4 v[2:3], v203, 1.0 op_sel:[0,1,0]
	v_pk_fma_f32 v[56:57], v[22:23], s[70:71], v[56:57] op_sel_hi:[1,0,1]
	v_cvt_scalef32_pk_f32_fp4 v[6:7], v203, 1.0 op_sel:[1,1,0]
	v_pk_fma_f32 v[58:59], v[30:31], s[70:71], v[58:59] op_sel_hi:[1,0,1]
	v_pk_fma_f32 v[60:61], v[2:3], s[70:71], v[60:61] op_sel_hi:[1,0,1]
	v_pk_fma_f32 v[62:63], v[6:7], s[70:71], v[62:63] op_sel_hi:[1,0,1]
	s_waitcnt vmcnt(32)
	v_cvt_scalef32_pk_f32_fp4 v[160:161], v240, 1.0
	v_cvt_scalef32_pk_f32_fp4 v[162:163], v240, 1.0 op_sel:[1,0,0]
	v_cvt_scalef32_pk_f32_fp4 v[18:19], v240, 1.0 op_sel:[0,1,0]
	v_pk_fma_f32 v[32:33], v[160:161], s[70:71], v[32:33] op_sel:[0,1,0] op_sel_hi:[1,1,1]
	v_cvt_scalef32_pk_f32_fp4 v[20:21], v240, 1.0 op_sel:[1,1,0]
	v_pk_fma_f32 v[34:35], v[162:163], s[70:71], v[34:35] op_sel:[0,1,0] op_sel_hi:[1,1,1]
	v_cvt_scalef32_pk_f32_fp4 v[22:23], v241, 1.0
	v_pk_fma_f32 v[36:37], v[18:19], s[70:71], v[36:37] op_sel:[0,1,0] op_sel_hi:[1,1,1]
	v_cvt_scalef32_pk_f32_fp4 v[30:31], v241, 1.0 op_sel:[1,0,0]
	v_pk_fma_f32 v[38:39], v[20:21], s[70:71], v[38:39] op_sel:[0,1,0] op_sel_hi:[1,1,1]
	v_cvt_scalef32_pk_f32_fp4 v[2:3], v241, 1.0 op_sel:[0,1,0]
	v_pk_fma_f32 v[40:41], v[22:23], s[70:71], v[40:41] op_sel:[0,1,0] op_sel_hi:[1,1,1]
	v_cvt_scalef32_pk_f32_fp4 v[6:7], v241, 1.0 op_sel:[1,1,0]
	v_pk_fma_f32 v[42:43], v[30:31], s[70:71], v[42:43] op_sel:[0,1,0] op_sel_hi:[1,1,1]
	v_cvt_scalef32_pk_f32_fp4 v[160:161], v242, 1.0
	v_pk_fma_f32 v[44:45], v[2:3], s[70:71], v[44:45] op_sel:[0,1,0] op_sel_hi:[1,1,1]
	v_cvt_scalef32_pk_f32_fp4 v[162:163], v242, 1.0 op_sel:[1,0,0]
	v_pk_fma_f32 v[46:47], v[6:7], s[70:71], v[46:47] op_sel:[0,1,0] op_sel_hi:[1,1,1]
	v_cvt_scalef32_pk_f32_fp4 v[18:19], v242, 1.0 op_sel:[0,1,0]
	v_pk_fma_f32 v[48:49], v[160:161], s[70:71], v[48:49] op_sel:[0,1,0] op_sel_hi:[1,1,1]
	v_cvt_scalef32_pk_f32_fp4 v[20:21], v242, 1.0 op_sel:[1,1,0]
	v_pk_fma_f32 v[50:51], v[162:163], s[70:71], v[50:51] op_sel:[0,1,0] op_sel_hi:[1,1,1]
	v_cvt_scalef32_pk_f32_fp4 v[22:23], v243, 1.0
	v_pk_fma_f32 v[52:53], v[18:19], s[70:71], v[52:53] op_sel:[0,1,0] op_sel_hi:[1,1,1]
	v_cvt_scalef32_pk_f32_fp4 v[30:31], v243, 1.0 op_sel:[1,0,0]
	v_pk_fma_f32 v[54:55], v[20:21], s[70:71], v[54:55] op_sel:[0,1,0] op_sel_hi:[1,1,1]
	v_cvt_scalef32_pk_f32_fp4 v[2:3], v243, 1.0 op_sel:[0,1,0]
	v_pk_fma_f32 v[56:57], v[22:23], s[70:71], v[56:57] op_sel:[0,1,0] op_sel_hi:[1,1,1]
	v_cvt_scalef32_pk_f32_fp4 v[6:7], v243, 1.0 op_sel:[1,1,0]
	v_pk_fma_f32 v[58:59], v[30:31], s[70:71], v[58:59] op_sel:[0,1,0] op_sel_hi:[1,1,1]
	v_pk_fma_f32 v[60:61], v[2:3], s[70:71], v[60:61] op_sel:[0,1,0] op_sel_hi:[1,1,1]
	v_pk_fma_f32 v[62:63], v[6:7], s[70:71], v[62:63] op_sel:[0,1,0] op_sel_hi:[1,1,1]
	s_sub_u32 s86, s86, 1
	s_cmp_lg_u32 s86, 0
	s_cbranch_scc1 .Lp8b_eloop
	ds_read_b128 v[10:13], v25
	ds_read_b128 v[18:21], v25 offset:16
	v_add_u32_e32 v25, 32, v25
	ds_read_b32 v232, v26
	ds_read_b32 v233, v27
	ds_read_b32 v234, v26 offset:512
	ds_read_b32 v235, v27 offset:512
	v_add_u32_e32 v26, 32, v26
	v_add_u32_e32 v27, 32, v27
	s_waitcnt vmcnt(30)
	v_mov_b32_e32 v216, 0
	v_mov_b32_e32 v224, 0
	v_dot8c_i32_i4_e32 v216, v64, v208
	v_dot8c_i32_i4_e32 v224, v64, v212
	v_dot8c_i32_i4_e32 v216, v65, v209
	v_dot8c_i32_i4_e32 v224, v65, v213
	v_dot8c_i32_i4_e32 v216, v66, v210
	v_dot8c_i32_i4_e32 v224, v66, v214
	v_dot8c_i32_i4_e32 v216, v67, v211
	v_dot8c_i32_i4_e32 v224, v67, v215
	s_waitcnt vmcnt(26)
	v_mov_b32_e32 v217, 0
	v_mov_b32_e32 v225, 0
	v_dot8c_i32_i4_e32 v217, v68, v208
	v_dot8c_i32_i4_e32 v225, v68, v212
	v_dot8c_i32_i4_e32 v217, v69, v209
	v_dot8c_i32_i4_e32 v225, v69, v213
	v_dot8c_i32_i4_e32 v217, v70, v210
	v_dot8c_i32_i4_e32 v225, v70, v214
	v_dot8c_i32_i4_e32 v217, v71, v211
	v_dot8c_i32_i4_e32 v225, v71, v215
	s_waitcnt vmcnt(22)
	v_mov_b32_e32 v218, 0
	v_mov_b32_e32 v226, 0
	v_dot8c_i32_i4_e32 v218, v72, v208
	v_dot8c_i32_i4_e32 v226, v72, v212
	v_dot8c_i32_i4_e32 v218, v73, v209
	v_dot8c_i32_i4_e32 v226, v73, v213
	v_dot8c_i32_i4_e32 v218, v74, v210
	v_dot8c_i32_i4_e32 v226, v74, v214
	v_dot8c_i32_i4_e32 v218, v75, v211
	v_dot8c_i32_i4_e32 v226, v75, v215
	s_waitcnt vmcnt(18)
	v_mov_b32_e32 v219, 0
	v_mov_b32_e32 v227, 0
	v_dot8c_i32_i4_e32 v219, v76, v208
	v_dot8c_i32_i4_e32 v227, v76, v212
	v_dot8c_i32_i4_e32 v219, v77, v209
	v_dot8c_i32_i4_e32 v227, v77, v213
	v_dot8c_i32_i4_e32 v219, v78, v210
	v_dot8c_i32_i4_e32 v227, v78, v214
	v_dot8c_i32_i4_e32 v219, v79, v211
	v_dot8c_i32_i4_e32 v227, v79, v215
	s_waitcnt vmcnt(14)
	v_mov_b32_e32 v220, 0
	v_mov_b32_e32 v228, 0
	v_dot8c_i32_i4_e32 v220, v80, v208
	v_dot8c_i32_i4_e32 v228, v80, v212
	v_dot8c_i32_i4_e32 v220, v81, v209
	v_dot8c_i32_i4_e32 v228, v81, v213
	v_dot8c_i32_i4_e32 v220, v82, v210
	v_dot8c_i32_i4_e32 v228, v82, v214
	v_dot8c_i32_i4_e32 v220, v83, v211
	v_dot8c_i32_i4_e32 v228, v83, v215
	s_waitcnt vmcnt(10)
	v_mov_b32_e32 v221, 0
	v_mov_b32_e32 v229, 0
	v_dot8c_i32_i4_e32 v221, v84, v208
	v_dot8c_i32_i4_e32 v229, v84, v212
	v_dot8c_i32_i4_e32 v221, v85, v209
	v_dot8c_i32_i4_e32 v229, v85, v213
	v_dot8c_i32_i4_e32 v221, v86, v210
	v_dot8c_i32_i4_e32 v229, v86, v214
	v_dot8c_i32_i4_e32 v221, v87, v211
	v_dot8c_i32_i4_e32 v229, v87, v215
	s_waitcnt vmcnt(6)
	v_mov_b32_e32 v222, 0
	v_mov_b32_e32 v230, 0
	v_dot8c_i32_i4_e32 v222, v88, v208
	v_dot8c_i32_i4_e32 v230, v88, v212
	v_dot8c_i32_i4_e32 v222, v89, v209
	v_dot8c_i32_i4_e32 v230, v89, v213
	v_dot8c_i32_i4_e32 v222, v90, v210
	v_dot8c_i32_i4_e32 v230, v90, v214
	v_dot8c_i32_i4_e32 v222, v91, v211
	v_dot8c_i32_i4_e32 v230, v91, v215
	s_waitcnt vmcnt(2)
	v_mov_b32_e32 v223, 0
	v_mov_b32_e32 v231, 0
	v_dot8c_i32_i4_e32 v223, v92, v208
	v_dot8c_i32_i4_e32 v231, v92, v212
	v_dot8c_i32_i4_e32 v223, v93, v209
	v_dot8c_i32_i4_e32 v231, v93, v213
	v_dot8c_i32_i4_e32 v223, v94, v210
	v_dot8c_i32_i4_e32 v231, v94, v214
	v_dot8c_i32_i4_e32 v223, v95, v211
	v_dot8c_i32_i4_e32 v231, v95, v215
	s_nop 2
	v_mad_i32_i24 v216, v216, 14, v224
	v_mad_i32_i24 v217, v217, 14, v225
	v_mad_i32_i24 v218, v218, 14, v226
	v_mad_i32_i24 v219, v219, 14, v227
	v_mad_i32_i24 v220, v220, 14, v228
	v_mad_i32_i24 v221, v221, 14, v229
	v_mad_i32_i24 v222, v222, 14, v230
	v_mad_i32_i24 v223, v223, 14, v231
	s_waitcnt lgkmcnt(4)
	v_readfirstlane_b32 s33, v10
	s_lshl_b32 s33, s33, 10
	s_add_u32 s72, s94, s33
	s_addc_u32 s73, s95, 0
	global_load_dwordx2 v[128:129], v28, s[72:73]
	global_load_dwordx2 v[130:131], v28, s[72:73] offset:512
	global_load_dwordx2 v[176:177], v29, s[72:73]
	global_load_dwordx2 v[178:179], v29, s[72:73] offset:512
	v_readfirstlane_b32 s33, v11
	s_lshl_b32 s33, s33, 10
	s_add_u32 s72, s94, s33
	s_addc_u32 s73, s95, 0
	global_load_dwordx2 v[132:133], v28, s[72:73]
	global_load_dwordx2 v[134:135], v28, s[72:73] offset:512
	global_load_dwordx2 v[180:181], v29, s[72:73]
	global_load_dwordx2 v[182:183], v29, s[72:73] offset:512
	v_readfirstlane_b32 s33, v12
	s_lshl_b32 s33, s33, 10
	s_add_u32 s72, s94, s33
	s_addc_u32 s73, s95, 0
	global_load_dwordx2 v[136:137], v28, s[72:73]
	global_load_dwordx2 v[138:139], v28, s[72:73] offset:512
	global_load_dwordx2 v[184:185], v29, s[72:73]
	global_load_dwordx2 v[186:187], v29, s[72:73] offset:512
	v_readfirstlane_b32 s33, v13
	s_lshl_b32 s33, s33, 10
	s_add_u32 s72, s94, s33
	s_addc_u32 s73, s95, 0
	global_load_dwordx2 v[140:141], v28, s[72:73]
	global_load_dwordx2 v[142:143], v28, s[72:73] offset:512
	global_load_dwordx2 v[188:189], v29, s[72:73]
	global_load_dwordx2 v[190:191], v29, s[72:73] offset:512
	v_readfirstlane_b32 s33, v18
	s_lshl_b32 s33, s33, 10
	s_add_u32 s72, s94, s33
	s_addc_u32 s73, s95, 0
	global_load_dwordx2 v[144:145], v28, s[72:73]
	global_load_dwordx2 v[146:147], v28, s[72:73] offset:512
	global_load_dwordx2 v[192:193], v29, s[72:73]
	global_load_dwordx2 v[194:195], v29, s[72:73] offset:512
	v_readfirstlane_b32 s33, v19
	s_lshl_b32 s33, s33, 10
	s_add_u32 s72, s94, s33
	s_addc_u32 s73, s95, 0
	global_load_dwordx2 v[148:149], v28, s[72:73]
	global_load_dwordx2 v[150:151], v28, s[72:73] offset:512
	global_load_dwordx2 v[196:197], v29, s[72:73]
	global_load_dwordx2 v[198:199], v29, s[72:73] offset:512
	v_readfirstlane_b32 s33, v20
	s_lshl_b32 s33, s33, 10
	s_add_u32 s72, s94, s33
	s_addc_u32 s73, s95, 0
	global_load_dwordx2 v[152:153], v28, s[72:73]
	global_load_dwordx2 v[154:155], v28, s[72:73] offset:512
	global_load_dwordx2 v[200:201], v29, s[72:73]
	global_load_dwordx2 v[202:203], v29, s[72:73] offset:512
	v_readfirstlane_b32 s33, v21
	s_lshl_b32 s33, s33, 10
	s_add_u32 s72, s94, s33
	s_addc_u32 s73, s95, 0
	global_load_dwordx2 v[156:157], v28, s[72:73]
	global_load_dwordx2 v[158:159], v28, s[72:73] offset:512
	global_load_dwordx2 v[240:241], v29, s[72:73]
	global_load_dwordx2 v[242:243], v29, s[72:73] offset:512
	s_nop 1
	v_permlane32_swap_b32_e32 v216, v217
	v_permlane32_swap_b32_e32 v218, v219
	v_permlane32_swap_b32_e32 v220, v221
	v_permlane32_swap_b32_e32 v222, v223
	v_add_u32_e32 v216, v216, v217
	v_add_u32_e32 v218, v218, v219
	v_add_u32_e32 v220, v220, v221
	v_add_u32_e32 v222, v222, v223
	s_nop 1
	v_permlane16_swap_b32_e32 v216, v218
	v_permlane16_swap_b32_e32 v220, v222
	v_add_u32_e32 v216, v216, v218
	v_add_u32_e32 v220, v220, v222
	s_nop 1
	v_add_u32_dpp v216, v216, v216 row_ror:8 row_mask:0xf bank_mask:0xf
	v_add_u32_dpp v220, v220, v220 row_ror:8 row_mask:0xf bank_mask:0xf
	s_nop 1
	v_add_u32_dpp v216, v216, v216 row_ror:4 row_mask:0xf bank_mask:0xf
	v_add_u32_dpp v220, v220, v220 row_ror:4 row_mask:0xf bank_mask:0xf
	s_nop 1
	v_add_u32_dpp v216, v216, v216 row_ror:2 row_mask:0xf bank_mask:0xf
	v_add_u32_dpp v220, v220, v220 row_ror:2 row_mask:0xf bank_mask:0xf
	s_nop 1
	v_add_u32_dpp v216, v216, v216 row_ror:1 row_mask:0xf bank_mask:0xf
	v_add_u32_dpp v220, v220, v220 row_ror:1 row_mask:0xf bank_mask:0xf
	s_waitcnt lgkmcnt(0)
	v_cvt_f32_i32_e32 v216, v216
	v_cvt_f32_i32_e32 v220, v220
	v_mul_f32_e32 v216, v216, v232
	v_mul_f32_e32 v220, v220, v233
	v_fma_f32 v2, |v216|, s83, 1.0
	v_fma_f32 v7, |v220|, s83, 1.0
	v_rcp_f32_e32 v2, v2
	v_rcp_f32_e32 v7, v7
	v_mul_f32_e32 v5, v216, v216
	v_mul_f32_e32 v11, v220, v220
	v_mul_f32_e32 v5, 0xbf38aa3b, v5
	v_mul_f32_e32 v11, 0xbf38aa3b, v11
	v_exp_f32_e32 v5, v5
	v_exp_f32_e32 v11, v11
	v_fmamk_f32 v3, v2, 0x3f07dc22, v172
	v_fmamk_f32 v10, v7, 0x3f07dc22, v172
	v_fmaak_f32 v3, v2, v3, 0x3f35f0e3
	v_fmaak_f32 v10, v7, v10, 0x3f35f0e3
	v_fmaak_f32 v3, v2, v3, 0xbe11a98e
	v_fmaak_f32 v10, v7, v10, 0xbe11a98e
	v_fmaak_f32 v3, v2, v3, 0x3e027906
	v_fmaak_f32 v10, v7, v10, 0x3e027906
	v_mul_f32_e32 v3, v2, v3
	v_mul_f32_e32 v10, v7, v10
	v_mul_f32_e32 v3, v5, v3
	v_mul_f32_e32 v10, v11, v10
	v_mul_f32_e32 v6, v216, v3
	v_mul_f32_e32 v12, v220, v10
	v_fma_f32 v3, -v216, v3, v216
	v_fma_f32 v10, -v220, v10, v220
	v_cmp_gt_f32_e32 vcc, 0, v216
	v_cmp_gt_f32_e64 s[96:97], 0, v220
	s_nop 1
	v_cndmask_b32_e32 v216, v3, v6, vcc
	v_cndmask_b32_e64 v220, v10, v12, s[96:97]
	v_mul_f32_e32 v216, v216, v234
	v_mul_f32_e32 v220, v220, v235
	s_nop 0
	v_readlane_b32 s64, v216, 0
	v_readlane_b32 s65, v216, 32
	v_readlane_b32 s66, v216, 16
	v_readlane_b32 s67, v216, 48
	v_readlane_b32 s68, v220, 0
	v_readlane_b32 s69, v220, 32
	v_readlane_b32 s70, v220, 16
	v_readlane_b32 s71, v220, 48
	s_waitcnt vmcnt(60)
	v_cvt_scalef32_pk_f32_fp4 v[160:161], v96, 1.0
	v_cvt_scalef32_pk_f32_fp4 v[162:163], v96, 1.0 op_sel:[1,0,0]
	v_cvt_scalef32_pk_f32_fp4 v[18:19], v96, 1.0 op_sel:[0,1,0]
	v_pk_fma_f32 v[32:33], v[160:161], s[64:65], v[32:33] op_sel_hi:[1,0,1]
	v_cvt_scalef32_pk_f32_fp4 v[20:21], v96, 1.0 op_sel:[1,1,0]
	v_pk_fma_f32 v[34:35], v[162:163], s[64:65], v[34:35] op_sel_hi:[1,0,1]
	v_cvt_scalef32_pk_f32_fp4 v[22:23], v97, 1.0
	v_pk_fma_f32 v[36:37], v[18:19], s[64:65], v[36:37] op_sel_hi:[1,0,1]
	v_cvt_scalef32_pk_f32_fp4 v[30:31], v97, 1.0 op_sel:[1,0,0]
	v_pk_fma_f32 v[38:39], v[20:21], s[64:65], v[38:39] op_sel_hi:[1,0,1]
	v_cvt_scalef32_pk_f32_fp4 v[2:3], v97, 1.0 op_sel:[0,1,0]
	v_pk_fma_f32 v[40:41], v[22:23], s[64:65], v[40:41] op_sel_hi:[1,0,1]
	v_cvt_scalef32_pk_f32_fp4 v[6:7], v97, 1.0 op_sel:[1,1,0]
	v_pk_fma_f32 v[42:43], v[30:31], s[64:65], v[42:43] op_sel_hi:[1,0,1]
	v_cvt_scalef32_pk_f32_fp4 v[160:161], v98, 1.0
	v_pk_fma_f32 v[44:45], v[2:3], s[64:65], v[44:45] op_sel_hi:[1,0,1]
	v_cvt_scalef32_pk_f32_fp4 v[162:163], v98, 1.0 op_sel:[1,0,0]
	v_pk_fma_f32 v[46:47], v[6:7], s[64:65], v[46:47] op_sel_hi:[1,0,1]
	v_cvt_scalef32_pk_f32_fp4 v[18:19], v98, 1.0 op_sel:[0,1,0]
	v_pk_fma_f32 v[48:49], v[160:161], s[64:65], v[48:49] op_sel_hi:[1,0,1]
	v_cvt_scalef32_pk_f32_fp4 v[20:21], v98, 1.0 op_sel:[1,1,0]
	v_pk_fma_f32 v[50:51], v[162:163], s[64:65], v[50:51] op_sel_hi:[1,0,1]
	v_cvt_scalef32_pk_f32_fp4 v[22:23], v99, 1.0
	v_pk_fma_f32 v[52:53], v[18:19], s[64:65], v[52:53] op_sel_hi:[1,0,1]
	v_cvt_scalef32_pk_f32_fp4 v[30:31], v99, 1.0 op_sel:[1,0,0]
	v_pk_fma_f32 v[54:55], v[20:21], s[64:65], v[54:55] op_sel_hi:[1,0,1]
	v_cvt_scalef32_pk_f32_fp4 v[2:3], v99, 1.0 op_sel:[0,1,0]
	v_pk_fma_f32 v[56:57], v[22:23], s[64:65], v[56:57] op_sel_hi:[1,0,1]
	v_cvt_scalef32_pk_f32_fp4 v[6:7], v99, 1.0 op_sel:[1,1,0]
	v_pk_fma_f32 v[58:59], v[30:31], s[64:65], v[58:59] op_sel_hi:[1,0,1]
	v_pk_fma_f32 v[60:61], v[2:3], s[64:65], v[60:61] op_sel_hi:[1,0,1]
	v_pk_fma_f32 v[62:63], v[6:7], s[64:65], v[62:63] op_sel_hi:[1,0,1]
	s_waitcnt vmcnt(56)
	v_cvt_scalef32_pk_f32_fp4 v[160:161], v100, 1.0
	v_cvt_scalef32_pk_f32_fp4 v[162:163], v100, 1.0 op_sel:[1,0,0]
	v_cvt_scalef32_pk_f32_fp4 v[18:19], v100, 1.0 op_sel:[0,1,0]
	v_pk_fma_f32 v[32:33], v[160:161], s[64:65], v[32:33] op_sel:[0,1,0] op_sel_hi:[1,1,1]
	v_cvt_scalef32_pk_f32_fp4 v[20:21], v100, 1.0 op_sel:[1,1,0]
	v_pk_fma_f32 v[34:35], v[162:163], s[64:65], v[34:35] op_sel:[0,1,0] op_sel_hi:[1,1,1]
	v_cvt_scalef32_pk_f32_fp4 v[22:23], v101, 1.0
	v_pk_fma_f32 v[36:37], v[18:19], s[64:65], v[36:37] op_sel:[0,1,0] op_sel_hi:[1,1,1]
	v_cvt_scalef32_pk_f32_fp4 v[30:31], v101, 1.0 op_sel:[1,0,0]
	v_pk_fma_f32 v[38:39], v[20:21], s[64:65], v[38:39] op_sel:[0,1,0] op_sel_hi:[1,1,1]
	v_cvt_scalef32_pk_f32_fp4 v[2:3], v101, 1.0 op_sel:[0,1,0]
	v_pk_fma_f32 v[40:41], v[22:23], s[64:65], v[40:41] op_sel:[0,1,0] op_sel_hi:[1,1,1]
	v_cvt_scalef32_pk_f32_fp4 v[6:7], v101, 1.0 op_sel:[1,1,0]
	v_pk_fma_f32 v[42:43], v[30:31], s[64:65], v[42:43] op_sel:[0,1,0] op_sel_hi:[1,1,1]
	v_cvt_scalef32_pk_f32_fp4 v[160:161], v102, 1.0
	v_pk_fma_f32 v[44:45], v[2:3], s[64:65], v[44:45] op_sel:[0,1,0] op_sel_hi:[1,1,1]
	v_cvt_scalef32_pk_f32_fp4 v[162:163], v102, 1.0 op_sel:[1,0,0]
	v_pk_fma_f32 v[46:47], v[6:7], s[64:65], v[46:47] op_sel:[0,1,0] op_sel_hi:[1,1,1]
	v_cvt_scalef32_pk_f32_fp4 v[18:19], v102, 1.0 op_sel:[0,1,0]
	v_pk_fma_f32 v[48:49], v[160:161], s[64:65], v[48:49] op_sel:[0,1,0] op_sel_hi:[1,1,1]
	v_cvt_scalef32_pk_f32_fp4 v[20:21], v102, 1.0 op_sel:[1,1,0]
	v_pk_fma_f32 v[50:51], v[162:163], s[64:65], v[50:51] op_sel:[0,1,0] op_sel_hi:[1,1,1]
	v_cvt_scalef32_pk_f32_fp4 v[22:23], v103, 1.0
	v_pk_fma_f32 v[52:53], v[18:19], s[64:65], v[52:53] op_sel:[0,1,0] op_sel_hi:[1,1,1]
	v_cvt_scalef32_pk_f32_fp4 v[30:31], v103, 1.0 op_sel:[1,0,0]
	v_pk_fma_f32 v[54:55], v[20:21], s[64:65], v[54:55] op_sel:[0,1,0] op_sel_hi:[1,1,1]
	v_cvt_scalef32_pk_f32_fp4 v[2:3], v103, 1.0 op_sel:[0,1,0]
	v_pk_fma_f32 v[56:57], v[22:23], s[64:65], v[56:57] op_sel:[0,1,0] op_sel_hi:[1,1,1]
	v_cvt_scalef32_pk_f32_fp4 v[6:7], v103, 1.0 op_sel:[1,1,0]
	v_pk_fma_f32 v[58:59], v[30:31], s[64:65], v[58:59] op_sel:[0,1,0] op_sel_hi:[1,1,1]
	v_pk_fma_f32 v[60:61], v[2:3], s[64:65], v[60:61] op_sel:[0,1,0] op_sel_hi:[1,1,1]
	v_pk_fma_f32 v[62:63], v[6:7], s[64:65], v[62:63] op_sel:[0,1,0] op_sel_hi:[1,1,1]
	s_waitcnt vmcnt(52)
	v_cvt_scalef32_pk_f32_fp4 v[160:161], v104, 1.0
	v_cvt_scalef32_pk_f32_fp4 v[162:163], v104, 1.0 op_sel:[1,0,0]
	v_cvt_scalef32_pk_f32_fp4 v[18:19], v104, 1.0 op_sel:[0,1,0]
	v_pk_fma_f32 v[32:33], v[160:161], s[66:67], v[32:33] op_sel_hi:[1,0,1]
	v_cvt_scalef32_pk_f32_fp4 v[20:21], v104, 1.0 op_sel:[1,1,0]
	v_pk_fma_f32 v[34:35], v[162:163], s[66:67], v[34:35] op_sel_hi:[1,0,1]
	v_cvt_scalef32_pk_f32_fp4 v[22:23], v105, 1.0
	v_pk_fma_f32 v[36:37], v[18:19], s[66:67], v[36:37] op_sel_hi:[1,0,1]
	v_cvt_scalef32_pk_f32_fp4 v[30:31], v105, 1.0 op_sel:[1,0,0]
	v_pk_fma_f32 v[38:39], v[20:21], s[66:67], v[38:39] op_sel_hi:[1,0,1]
	v_cvt_scalef32_pk_f32_fp4 v[2:3], v105, 1.0 op_sel:[0,1,0]
	v_pk_fma_f32 v[40:41], v[22:23], s[66:67], v[40:41] op_sel_hi:[1,0,1]
	v_cvt_scalef32_pk_f32_fp4 v[6:7], v105, 1.0 op_sel:[1,1,0]
	v_pk_fma_f32 v[42:43], v[30:31], s[66:67], v[42:43] op_sel_hi:[1,0,1]
	v_cvt_scalef32_pk_f32_fp4 v[160:161], v106, 1.0
	v_pk_fma_f32 v[44:45], v[2:3], s[66:67], v[44:45] op_sel_hi:[1,0,1]
	v_cvt_scalef32_pk_f32_fp4 v[162:163], v106, 1.0 op_sel:[1,0,0]
	v_pk_fma_f32 v[46:47], v[6:7], s[66:67], v[46:47] op_sel_hi:[1,0,1]
	v_cvt_scalef32_pk_f32_fp4 v[18:19], v106, 1.0 op_sel:[0,1,0]
	v_pk_fma_f32 v[48:49], v[160:161], s[66:67], v[48:49] op_sel_hi:[1,0,1]
	v_cvt_scalef32_pk_f32_fp4 v[20:21], v106, 1.0 op_sel:[1,1,0]
	v_pk_fma_f32 v[50:51], v[162:163], s[66:67], v[50:51] op_sel_hi:[1,0,1]
	v_cvt_scalef32_pk_f32_fp4 v[22:23], v107, 1.0
	v_pk_fma_f32 v[52:53], v[18:19], s[66:67], v[52:53] op_sel_hi:[1,0,1]
	v_cvt_scalef32_pk_f32_fp4 v[30:31], v107, 1.0 op_sel:[1,0,0]
	v_pk_fma_f32 v[54:55], v[20:21], s[66:67], v[54:55] op_sel_hi:[1,0,1]
	v_cvt_scalef32_pk_f32_fp4 v[2:3], v107, 1.0 op_sel:[0,1,0]
	v_pk_fma_f32 v[56:57], v[22:23], s[66:67], v[56:57] op_sel_hi:[1,0,1]
	v_cvt_scalef32_pk_f32_fp4 v[6:7], v107, 1.0 op_sel:[1,1,0]
	v_pk_fma_f32 v[58:59], v[30:31], s[66:67], v[58:59] op_sel_hi:[1,0,1]
	v_pk_fma_f32 v[60:61], v[2:3], s[66:67], v[60:61] op_sel_hi:[1,0,1]
	v_pk_fma_f32 v[62:63], v[6:7], s[66:67], v[62:63] op_sel_hi:[1,0,1]
	s_waitcnt vmcnt(48)
	v_cvt_scalef32_pk_f32_fp4 v[160:161], v108, 1.0
	v_cvt_scalef32_pk_f32_fp4 v[162:163], v108, 1.0 op_sel:[1,0,0]
	v_cvt_scalef32_pk_f32_fp4 v[18:19], v108, 1.0 op_sel:[0,1,0]
	v_pk_fma_f32 v[32:33], v[160:161], s[66:67], v[32:33] op_sel:[0,1,0] op_sel_hi:[1,1,1]
	v_cvt_scalef32_pk_f32_fp4 v[20:21], v108, 1.0 op_sel:[1,1,0]
	v_pk_fma_f32 v[34:35], v[162:163], s[66:67], v[34:35] op_sel:[0,1,0] op_sel_hi:[1,1,1]
	v_cvt_scalef32_pk_f32_fp4 v[22:23], v109, 1.0
	v_pk_fma_f32 v[36:37], v[18:19], s[66:67], v[36:37] op_sel:[0,1,0] op_sel_hi:[1,1,1]
	v_cvt_scalef32_pk_f32_fp4 v[30:31], v109, 1.0 op_sel:[1,0,0]
	v_pk_fma_f32 v[38:39], v[20:21], s[66:67], v[38:39] op_sel:[0,1,0] op_sel_hi:[1,1,1]
	v_cvt_scalef32_pk_f32_fp4 v[2:3], v109, 1.0 op_sel:[0,1,0]
	v_pk_fma_f32 v[40:41], v[22:23], s[66:67], v[40:41] op_sel:[0,1,0] op_sel_hi:[1,1,1]
	v_cvt_scalef32_pk_f32_fp4 v[6:7], v109, 1.0 op_sel:[1,1,0]
	v_pk_fma_f32 v[42:43], v[30:31], s[66:67], v[42:43] op_sel:[0,1,0] op_sel_hi:[1,1,1]
	v_cvt_scalef32_pk_f32_fp4 v[160:161], v110, 1.0
	v_pk_fma_f32 v[44:45], v[2:3], s[66:67], v[44:45] op_sel:[0,1,0] op_sel_hi:[1,1,1]
	v_cvt_scalef32_pk_f32_fp4 v[162:163], v110, 1.0 op_sel:[1,0,0]
	v_pk_fma_f32 v[46:47], v[6:7], s[66:67], v[46:47] op_sel:[0,1,0] op_sel_hi:[1,1,1]
	v_cvt_scalef32_pk_f32_fp4 v[18:19], v110, 1.0 op_sel:[0,1,0]
	v_pk_fma_f32 v[48:49], v[160:161], s[66:67], v[48:49] op_sel:[0,1,0] op_sel_hi:[1,1,1]
	v_cvt_scalef32_pk_f32_fp4 v[20:21], v110, 1.0 op_sel:[1,1,0]
	v_pk_fma_f32 v[50:51], v[162:163], s[66:67], v[50:51] op_sel:[0,1,0] op_sel_hi:[1,1,1]
	v_cvt_scalef32_pk_f32_fp4 v[22:23], v111, 1.0
	v_pk_fma_f32 v[52:53], v[18:19], s[66:67], v[52:53] op_sel:[0,1,0] op_sel_hi:[1,1,1]
	v_cvt_scalef32_pk_f32_fp4 v[30:31], v111, 1.0 op_sel:[1,0,0]
	v_pk_fma_f32 v[54:55], v[20:21], s[66:67], v[54:55] op_sel:[0,1,0] op_sel_hi:[1,1,1]
	v_cvt_scalef32_pk_f32_fp4 v[2:3], v111, 1.0 op_sel:[0,1,0]
	v_pk_fma_f32 v[56:57], v[22:23], s[66:67], v[56:57] op_sel:[0,1,0] op_sel_hi:[1,1,1]
	v_cvt_scalef32_pk_f32_fp4 v[6:7], v111, 1.0 op_sel:[1,1,0]
	v_pk_fma_f32 v[58:59], v[30:31], s[66:67], v[58:59] op_sel:[0,1,0] op_sel_hi:[1,1,1]
	v_pk_fma_f32 v[60:61], v[2:3], s[66:67], v[60:61] op_sel:[0,1,0] op_sel_hi:[1,1,1]
	v_pk_fma_f32 v[62:63], v[6:7], s[66:67], v[62:63] op_sel:[0,1,0] op_sel_hi:[1,1,1]
	s_waitcnt vmcnt(44)
	v_cvt_scalef32_pk_f32_fp4 v[160:161], v112, 1.0
	v_cvt_scalef32_pk_f32_fp4 v[162:163], v112, 1.0 op_sel:[1,0,0]
	v_cvt_scalef32_pk_f32_fp4 v[18:19], v112, 1.0 op_sel:[0,1,0]
	v_pk_fma_f32 v[32:33], v[160:161], s[68:69], v[32:33] op_sel_hi:[1,0,1]
	v_cvt_scalef32_pk_f32_fp4 v[20:21], v112, 1.0 op_sel:[1,1,0]
	v_pk_fma_f32 v[34:35], v[162:163], s[68:69], v[34:35] op_sel_hi:[1,0,1]
	v_cvt_scalef32_pk_f32_fp4 v[22:23], v113, 1.0
	v_pk_fma_f32 v[36:37], v[18:19], s[68:69], v[36:37] op_sel_hi:[1,0,1]
	v_cvt_scalef32_pk_f32_fp4 v[30:31], v113, 1.0 op_sel:[1,0,0]
	v_pk_fma_f32 v[38:39], v[20:21], s[68:69], v[38:39] op_sel_hi:[1,0,1]
	v_cvt_scalef32_pk_f32_fp4 v[2:3], v113, 1.0 op_sel:[0,1,0]
	v_pk_fma_f32 v[40:41], v[22:23], s[68:69], v[40:41] op_sel_hi:[1,0,1]
	v_cvt_scalef32_pk_f32_fp4 v[6:7], v113, 1.0 op_sel:[1,1,0]
	v_pk_fma_f32 v[42:43], v[30:31], s[68:69], v[42:43] op_sel_hi:[1,0,1]
	v_cvt_scalef32_pk_f32_fp4 v[160:161], v114, 1.0
	v_pk_fma_f32 v[44:45], v[2:3], s[68:69], v[44:45] op_sel_hi:[1,0,1]
	v_cvt_scalef32_pk_f32_fp4 v[162:163], v114, 1.0 op_sel:[1,0,0]
	v_pk_fma_f32 v[46:47], v[6:7], s[68:69], v[46:47] op_sel_hi:[1,0,1]
	v_cvt_scalef32_pk_f32_fp4 v[18:19], v114, 1.0 op_sel:[0,1,0]
	v_pk_fma_f32 v[48:49], v[160:161], s[68:69], v[48:49] op_sel_hi:[1,0,1]
	v_cvt_scalef32_pk_f32_fp4 v[20:21], v114, 1.0 op_sel:[1,1,0]
	v_pk_fma_f32 v[50:51], v[162:163], s[68:69], v[50:51] op_sel_hi:[1,0,1]
	v_cvt_scalef32_pk_f32_fp4 v[22:23], v115, 1.0
	v_pk_fma_f32 v[52:53], v[18:19], s[68:69], v[52:53] op_sel_hi:[1,0,1]
	v_cvt_scalef32_pk_f32_fp4 v[30:31], v115, 1.0 op_sel:[1,0,0]
	v_pk_fma_f32 v[54:55], v[20:21], s[68:69], v[54:55] op_sel_hi:[1,0,1]
	v_cvt_scalef32_pk_f32_fp4 v[2:3], v115, 1.0 op_sel:[0,1,0]
	v_pk_fma_f32 v[56:57], v[22:23], s[68:69], v[56:57] op_sel_hi:[1,0,1]
	v_cvt_scalef32_pk_f32_fp4 v[6:7], v115, 1.0 op_sel:[1,1,0]
	v_pk_fma_f32 v[58:59], v[30:31], s[68:69], v[58:59] op_sel_hi:[1,0,1]
	v_pk_fma_f32 v[60:61], v[2:3], s[68:69], v[60:61] op_sel_hi:[1,0,1]
	v_pk_fma_f32 v[62:63], v[6:7], s[68:69], v[62:63] op_sel_hi:[1,0,1]
	s_waitcnt vmcnt(40)
	v_cvt_scalef32_pk_f32_fp4 v[160:161], v116, 1.0
	v_cvt_scalef32_pk_f32_fp4 v[162:163], v116, 1.0 op_sel:[1,0,0]
	v_cvt_scalef32_pk_f32_fp4 v[18:19], v116, 1.0 op_sel:[0,1,0]
	v_pk_fma_f32 v[32:33], v[160:161], s[68:69], v[32:33] op_sel:[0,1,0] op_sel_hi:[1,1,1]
	v_cvt_scalef32_pk_f32_fp4 v[20:21], v116, 1.0 op_sel:[1,1,0]
	v_pk_fma_f32 v[34:35], v[162:163], s[68:69], v[34:35] op_sel:[0,1,0] op_sel_hi:[1,1,1]
	v_cvt_scalef32_pk_f32_fp4 v[22:23], v117, 1.0
	v_pk_fma_f32 v[36:37], v[18:19], s[68:69], v[36:37] op_sel:[0,1,0] op_sel_hi:[1,1,1]
	v_cvt_scalef32_pk_f32_fp4 v[30:31], v117, 1.0 op_sel:[1,0,0]
	v_pk_fma_f32 v[38:39], v[20:21], s[68:69], v[38:39] op_sel:[0,1,0] op_sel_hi:[1,1,1]
	v_cvt_scalef32_pk_f32_fp4 v[2:3], v117, 1.0 op_sel:[0,1,0]
	v_pk_fma_f32 v[40:41], v[22:23], s[68:69], v[40:41] op_sel:[0,1,0] op_sel_hi:[1,1,1]
	v_cvt_scalef32_pk_f32_fp4 v[6:7], v117, 1.0 op_sel:[1,1,0]
	v_pk_fma_f32 v[42:43], v[30:31], s[68:69], v[42:43] op_sel:[0,1,0] op_sel_hi:[1,1,1]
	v_cvt_scalef32_pk_f32_fp4 v[160:161], v118, 1.0
	v_pk_fma_f32 v[44:45], v[2:3], s[68:69], v[44:45] op_sel:[0,1,0] op_sel_hi:[1,1,1]
	v_cvt_scalef32_pk_f32_fp4 v[162:163], v118, 1.0 op_sel:[1,0,0]
	v_pk_fma_f32 v[46:47], v[6:7], s[68:69], v[46:47] op_sel:[0,1,0] op_sel_hi:[1,1,1]
	v_cvt_scalef32_pk_f32_fp4 v[18:19], v118, 1.0 op_sel:[0,1,0]
	v_pk_fma_f32 v[48:49], v[160:161], s[68:69], v[48:49] op_sel:[0,1,0] op_sel_hi:[1,1,1]
	v_cvt_scalef32_pk_f32_fp4 v[20:21], v118, 1.0 op_sel:[1,1,0]
	v_pk_fma_f32 v[50:51], v[162:163], s[68:69], v[50:51] op_sel:[0,1,0] op_sel_hi:[1,1,1]
	v_cvt_scalef32_pk_f32_fp4 v[22:23], v119, 1.0
	v_pk_fma_f32 v[52:53], v[18:19], s[68:69], v[52:53] op_sel:[0,1,0] op_sel_hi:[1,1,1]
	v_cvt_scalef32_pk_f32_fp4 v[30:31], v119, 1.0 op_sel:[1,0,0]
	v_pk_fma_f32 v[54:55], v[20:21], s[68:69], v[54:55] op_sel:[0,1,0] op_sel_hi:[1,1,1]
	v_cvt_scalef32_pk_f32_fp4 v[2:3], v119, 1.0 op_sel:[0,1,0]
	v_pk_fma_f32 v[56:57], v[22:23], s[68:69], v[56:57] op_sel:[0,1,0] op_sel_hi:[1,1,1]
	v_cvt_scalef32_pk_f32_fp4 v[6:7], v119, 1.0 op_sel:[1,1,0]
	v_pk_fma_f32 v[58:59], v[30:31], s[68:69], v[58:59] op_sel:[0,1,0] op_sel_hi:[1,1,1]
	v_pk_fma_f32 v[60:61], v[2:3], s[68:69], v[60:61] op_sel:[0,1,0] op_sel_hi:[1,1,1]
	v_pk_fma_f32 v[62:63], v[6:7], s[68:69], v[62:63] op_sel:[0,1,0] op_sel_hi:[1,1,1]
	s_waitcnt vmcnt(36)
	v_cvt_scalef32_pk_f32_fp4 v[160:161], v120, 1.0
	v_cvt_scalef32_pk_f32_fp4 v[162:163], v120, 1.0 op_sel:[1,0,0]
	v_cvt_scalef32_pk_f32_fp4 v[18:19], v120, 1.0 op_sel:[0,1,0]
	v_pk_fma_f32 v[32:33], v[160:161], s[70:71], v[32:33] op_sel_hi:[1,0,1]
	v_cvt_scalef32_pk_f32_fp4 v[20:21], v120, 1.0 op_sel:[1,1,0]
	v_pk_fma_f32 v[34:35], v[162:163], s[70:71], v[34:35] op_sel_hi:[1,0,1]
	v_cvt_scalef32_pk_f32_fp4 v[22:23], v121, 1.0
	v_pk_fma_f32 v[36:37], v[18:19], s[70:71], v[36:37] op_sel_hi:[1,0,1]
	v_cvt_scalef32_pk_f32_fp4 v[30:31], v121, 1.0 op_sel:[1,0,0]
	v_pk_fma_f32 v[38:39], v[20:21], s[70:71], v[38:39] op_sel_hi:[1,0,1]
	v_cvt_scalef32_pk_f32_fp4 v[2:3], v121, 1.0 op_sel:[0,1,0]
	v_pk_fma_f32 v[40:41], v[22:23], s[70:71], v[40:41] op_sel_hi:[1,0,1]
	v_cvt_scalef32_pk_f32_fp4 v[6:7], v121, 1.0 op_sel:[1,1,0]
	v_pk_fma_f32 v[42:43], v[30:31], s[70:71], v[42:43] op_sel_hi:[1,0,1]
	v_cvt_scalef32_pk_f32_fp4 v[160:161], v122, 1.0
	v_pk_fma_f32 v[44:45], v[2:3], s[70:71], v[44:45] op_sel_hi:[1,0,1]
	v_cvt_scalef32_pk_f32_fp4 v[162:163], v122, 1.0 op_sel:[1,0,0]
	v_pk_fma_f32 v[46:47], v[6:7], s[70:71], v[46:47] op_sel_hi:[1,0,1]
	v_cvt_scalef32_pk_f32_fp4 v[18:19], v122, 1.0 op_sel:[0,1,0]
	v_pk_fma_f32 v[48:49], v[160:161], s[70:71], v[48:49] op_sel_hi:[1,0,1]
	v_cvt_scalef32_pk_f32_fp4 v[20:21], v122, 1.0 op_sel:[1,1,0]
	v_pk_fma_f32 v[50:51], v[162:163], s[70:71], v[50:51] op_sel_hi:[1,0,1]
	v_cvt_scalef32_pk_f32_fp4 v[22:23], v123, 1.0
	v_pk_fma_f32 v[52:53], v[18:19], s[70:71], v[52:53] op_sel_hi:[1,0,1]
	v_cvt_scalef32_pk_f32_fp4 v[30:31], v123, 1.0 op_sel:[1,0,0]
	v_pk_fma_f32 v[54:55], v[20:21], s[70:71], v[54:55] op_sel_hi:[1,0,1]
	v_cvt_scalef32_pk_f32_fp4 v[2:3], v123, 1.0 op_sel:[0,1,0]
	v_pk_fma_f32 v[56:57], v[22:23], s[70:71], v[56:57] op_sel_hi:[1,0,1]
	v_cvt_scalef32_pk_f32_fp4 v[6:7], v123, 1.0 op_sel:[1,1,0]
	v_pk_fma_f32 v[58:59], v[30:31], s[70:71], v[58:59] op_sel_hi:[1,0,1]
	v_pk_fma_f32 v[60:61], v[2:3], s[70:71], v[60:61] op_sel_hi:[1,0,1]
	v_pk_fma_f32 v[62:63], v[6:7], s[70:71], v[62:63] op_sel_hi:[1,0,1]
	s_waitcnt vmcnt(32)
	v_cvt_scalef32_pk_f32_fp4 v[160:161], v124, 1.0
	v_cvt_scalef32_pk_f32_fp4 v[162:163], v124, 1.0 op_sel:[1,0,0]
	v_cvt_scalef32_pk_f32_fp4 v[18:19], v124, 1.0 op_sel:[0,1,0]
	v_pk_fma_f32 v[32:33], v[160:161], s[70:71], v[32:33] op_sel:[0,1,0] op_sel_hi:[1,1,1]
	v_cvt_scalef32_pk_f32_fp4 v[20:21], v124, 1.0 op_sel:[1,1,0]
	v_pk_fma_f32 v[34:35], v[162:163], s[70:71], v[34:35] op_sel:[0,1,0] op_sel_hi:[1,1,1]
	v_cvt_scalef32_pk_f32_fp4 v[22:23], v125, 1.0
	v_pk_fma_f32 v[36:37], v[18:19], s[70:71], v[36:37] op_sel:[0,1,0] op_sel_hi:[1,1,1]
	v_cvt_scalef32_pk_f32_fp4 v[30:31], v125, 1.0 op_sel:[1,0,0]
	v_pk_fma_f32 v[38:39], v[20:21], s[70:71], v[38:39] op_sel:[0,1,0] op_sel_hi:[1,1,1]
	v_cvt_scalef32_pk_f32_fp4 v[2:3], v125, 1.0 op_sel:[0,1,0]
	v_pk_fma_f32 v[40:41], v[22:23], s[70:71], v[40:41] op_sel:[0,1,0] op_sel_hi:[1,1,1]
	v_cvt_scalef32_pk_f32_fp4 v[6:7], v125, 1.0 op_sel:[1,1,0]
	v_pk_fma_f32 v[42:43], v[30:31], s[70:71], v[42:43] op_sel:[0,1,0] op_sel_hi:[1,1,1]
	v_cvt_scalef32_pk_f32_fp4 v[160:161], v126, 1.0
	v_pk_fma_f32 v[44:45], v[2:3], s[70:71], v[44:45] op_sel:[0,1,0] op_sel_hi:[1,1,1]
	v_cvt_scalef32_pk_f32_fp4 v[162:163], v126, 1.0 op_sel:[1,0,0]
	v_pk_fma_f32 v[46:47], v[6:7], s[70:71], v[46:47] op_sel:[0,1,0] op_sel_hi:[1,1,1]
	v_cvt_scalef32_pk_f32_fp4 v[18:19], v126, 1.0 op_sel:[0,1,0]
	v_pk_fma_f32 v[48:49], v[160:161], s[70:71], v[48:49] op_sel:[0,1,0] op_sel_hi:[1,1,1]
	v_cvt_scalef32_pk_f32_fp4 v[20:21], v126, 1.0 op_sel:[1,1,0]
	v_pk_fma_f32 v[50:51], v[162:163], s[70:71], v[50:51] op_sel:[0,1,0] op_sel_hi:[1,1,1]
	v_cvt_scalef32_pk_f32_fp4 v[22:23], v127, 1.0
	v_pk_fma_f32 v[52:53], v[18:19], s[70:71], v[52:53] op_sel:[0,1,0] op_sel_hi:[1,1,1]
	v_cvt_scalef32_pk_f32_fp4 v[30:31], v127, 1.0 op_sel:[1,0,0]
	v_pk_fma_f32 v[54:55], v[20:21], s[70:71], v[54:55] op_sel:[0,1,0] op_sel_hi:[1,1,1]
	v_cvt_scalef32_pk_f32_fp4 v[2:3], v127, 1.0 op_sel:[0,1,0]
	v_pk_fma_f32 v[56:57], v[22:23], s[70:71], v[56:57] op_sel:[0,1,0] op_sel_hi:[1,1,1]
	v_cvt_scalef32_pk_f32_fp4 v[6:7], v127, 1.0 op_sel:[1,1,0]
	v_pk_fma_f32 v[58:59], v[30:31], s[70:71], v[58:59] op_sel:[0,1,0] op_sel_hi:[1,1,1]
	v_pk_fma_f32 v[60:61], v[2:3], s[70:71], v[60:61] op_sel:[0,1,0] op_sel_hi:[1,1,1]
	v_pk_fma_f32 v[62:63], v[6:7], s[70:71], v[62:63] op_sel:[0,1,0] op_sel_hi:[1,1,1]
	ds_read_b32 v232, v26
	ds_read_b32 v233, v27
	ds_read_b32 v234, v26 offset:512
	ds_read_b32 v235, v27 offset:512
	v_add_u32_e32 v26, 32, v26
	v_add_u32_e32 v27, 32, v27
	s_waitcnt vmcnt(30)
	v_mov_b32_e32 v216, 0
	v_mov_b32_e32 v224, 0
	v_dot8c_i32_i4_e32 v216, v128, v208
	v_dot8c_i32_i4_e32 v224, v128, v212
	v_dot8c_i32_i4_e32 v216, v129, v209
	v_dot8c_i32_i4_e32 v224, v129, v213
	v_dot8c_i32_i4_e32 v216, v130, v210
	v_dot8c_i32_i4_e32 v224, v130, v214
	v_dot8c_i32_i4_e32 v216, v131, v211
	v_dot8c_i32_i4_e32 v224, v131, v215
	s_waitcnt vmcnt(26)
	v_mov_b32_e32 v217, 0
	v_mov_b32_e32 v225, 0
	v_dot8c_i32_i4_e32 v217, v132, v208
	v_dot8c_i32_i4_e32 v225, v132, v212
	v_dot8c_i32_i4_e32 v217, v133, v209
	v_dot8c_i32_i4_e32 v225, v133, v213
	v_dot8c_i32_i4_e32 v217, v134, v210
	v_dot8c_i32_i4_e32 v225, v134, v214
	v_dot8c_i32_i4_e32 v217, v135, v211
	v_dot8c_i32_i4_e32 v225, v135, v215
	s_waitcnt vmcnt(22)
	v_mov_b32_e32 v218, 0
	v_mov_b32_e32 v226, 0
	v_dot8c_i32_i4_e32 v218, v136, v208
	v_dot8c_i32_i4_e32 v226, v136, v212
	v_dot8c_i32_i4_e32 v218, v137, v209
	v_dot8c_i32_i4_e32 v226, v137, v213
	v_dot8c_i32_i4_e32 v218, v138, v210
	v_dot8c_i32_i4_e32 v226, v138, v214
	v_dot8c_i32_i4_e32 v218, v139, v211
	v_dot8c_i32_i4_e32 v226, v139, v215
	s_waitcnt vmcnt(18)
	v_mov_b32_e32 v219, 0
	v_mov_b32_e32 v227, 0
	v_dot8c_i32_i4_e32 v219, v140, v208
	v_dot8c_i32_i4_e32 v227, v140, v212
	v_dot8c_i32_i4_e32 v219, v141, v209
	v_dot8c_i32_i4_e32 v227, v141, v213
	v_dot8c_i32_i4_e32 v219, v142, v210
	v_dot8c_i32_i4_e32 v227, v142, v214
	v_dot8c_i32_i4_e32 v219, v143, v211
	v_dot8c_i32_i4_e32 v227, v143, v215
	s_waitcnt vmcnt(14)
	v_mov_b32_e32 v220, 0
	v_mov_b32_e32 v228, 0
	v_dot8c_i32_i4_e32 v220, v144, v208
	v_dot8c_i32_i4_e32 v228, v144, v212
	v_dot8c_i32_i4_e32 v220, v145, v209
	v_dot8c_i32_i4_e32 v228, v145, v213
	v_dot8c_i32_i4_e32 v220, v146, v210
	v_dot8c_i32_i4_e32 v228, v146, v214
	v_dot8c_i32_i4_e32 v220, v147, v211
	v_dot8c_i32_i4_e32 v228, v147, v215
	s_waitcnt vmcnt(10)
	v_mov_b32_e32 v221, 0
	v_mov_b32_e32 v229, 0
	v_dot8c_i32_i4_e32 v221, v148, v208
	v_dot8c_i32_i4_e32 v229, v148, v212
	v_dot8c_i32_i4_e32 v221, v149, v209
	v_dot8c_i32_i4_e32 v229, v149, v213
	v_dot8c_i32_i4_e32 v221, v150, v210
	v_dot8c_i32_i4_e32 v229, v150, v214
	v_dot8c_i32_i4_e32 v221, v151, v211
	v_dot8c_i32_i4_e32 v229, v151, v215
	s_waitcnt vmcnt(6)
	v_mov_b32_e32 v222, 0
	v_mov_b32_e32 v230, 0
	v_dot8c_i32_i4_e32 v222, v152, v208
	v_dot8c_i32_i4_e32 v230, v152, v212
	v_dot8c_i32_i4_e32 v222, v153, v209
	v_dot8c_i32_i4_e32 v230, v153, v213
	v_dot8c_i32_i4_e32 v222, v154, v210
	v_dot8c_i32_i4_e32 v230, v154, v214
	v_dot8c_i32_i4_e32 v222, v155, v211
	v_dot8c_i32_i4_e32 v230, v155, v215
	s_waitcnt vmcnt(2)
	v_mov_b32_e32 v223, 0
	v_mov_b32_e32 v231, 0
	v_dot8c_i32_i4_e32 v223, v156, v208
	v_dot8c_i32_i4_e32 v231, v156, v212
	v_dot8c_i32_i4_e32 v223, v157, v209
	v_dot8c_i32_i4_e32 v231, v157, v213
	v_dot8c_i32_i4_e32 v223, v158, v210
	v_dot8c_i32_i4_e32 v231, v158, v214
	v_dot8c_i32_i4_e32 v223, v159, v211
	v_dot8c_i32_i4_e32 v231, v159, v215
	s_nop 2
	v_mad_i32_i24 v216, v216, 14, v224
	v_mad_i32_i24 v217, v217, 14, v225
	v_mad_i32_i24 v218, v218, 14, v226
	v_mad_i32_i24 v219, v219, 14, v227
	v_mad_i32_i24 v220, v220, 14, v228
	v_mad_i32_i24 v221, v221, 14, v229
	v_mad_i32_i24 v222, v222, 14, v230
	v_mad_i32_i24 v223, v223, 14, v231
	s_nop 1
	v_permlane32_swap_b32_e32 v216, v217
	v_permlane32_swap_b32_e32 v218, v219
	v_permlane32_swap_b32_e32 v220, v221
	v_permlane32_swap_b32_e32 v222, v223
	v_add_u32_e32 v216, v216, v217
	v_add_u32_e32 v218, v218, v219
	v_add_u32_e32 v220, v220, v221
	v_add_u32_e32 v222, v222, v223
	s_nop 1
	v_permlane16_swap_b32_e32 v216, v218
	v_permlane16_swap_b32_e32 v220, v222
	v_add_u32_e32 v216, v216, v218
	v_add_u32_e32 v220, v220, v222
	s_nop 1
	v_add_u32_dpp v216, v216, v216 row_ror:8 row_mask:0xf bank_mask:0xf
	v_add_u32_dpp v220, v220, v220 row_ror:8 row_mask:0xf bank_mask:0xf
	s_nop 1
	v_add_u32_dpp v216, v216, v216 row_ror:4 row_mask:0xf bank_mask:0xf
	v_add_u32_dpp v220, v220, v220 row_ror:4 row_mask:0xf bank_mask:0xf
	s_nop 1
	v_add_u32_dpp v216, v216, v216 row_ror:2 row_mask:0xf bank_mask:0xf
	v_add_u32_dpp v220, v220, v220 row_ror:2 row_mask:0xf bank_mask:0xf
	s_nop 1
	v_add_u32_dpp v216, v216, v216 row_ror:1 row_mask:0xf bank_mask:0xf
	v_add_u32_dpp v220, v220, v220 row_ror:1 row_mask:0xf bank_mask:0xf
	s_waitcnt lgkmcnt(0)
	v_cvt_f32_i32_e32 v216, v216
	v_cvt_f32_i32_e32 v220, v220
	v_mul_f32_e32 v216, v216, v232
	v_mul_f32_e32 v220, v220, v233
	v_fma_f32 v2, |v216|, s83, 1.0
	v_fma_f32 v7, |v220|, s83, 1.0
	v_rcp_f32_e32 v2, v2
	v_rcp_f32_e32 v7, v7
	v_mul_f32_e32 v5, v216, v216
	v_mul_f32_e32 v11, v220, v220
	v_mul_f32_e32 v5, 0xbf38aa3b, v5
	v_mul_f32_e32 v11, 0xbf38aa3b, v11
	v_exp_f32_e32 v5, v5
	v_exp_f32_e32 v11, v11
	v_fmamk_f32 v3, v2, 0x3f07dc22, v172
	v_fmamk_f32 v10, v7, 0x3f07dc22, v172
	v_fmaak_f32 v3, v2, v3, 0x3f35f0e3
	v_fmaak_f32 v10, v7, v10, 0x3f35f0e3
	v_fmaak_f32 v3, v2, v3, 0xbe11a98e
	v_fmaak_f32 v10, v7, v10, 0xbe11a98e
	v_fmaak_f32 v3, v2, v3, 0x3e027906
	v_fmaak_f32 v10, v7, v10, 0x3e027906
	v_mul_f32_e32 v3, v2, v3
	v_mul_f32_e32 v10, v7, v10
	v_mul_f32_e32 v3, v5, v3
	v_mul_f32_e32 v10, v11, v10
	v_mul_f32_e32 v6, v216, v3
	v_mul_f32_e32 v12, v220, v10
	v_fma_f32 v3, -v216, v3, v216
	v_fma_f32 v10, -v220, v10, v220
	v_cmp_gt_f32_e32 vcc, 0, v216
	v_cmp_gt_f32_e64 s[96:97], 0, v220
	s_nop 1
	v_cndmask_b32_e32 v216, v3, v6, vcc
	v_cndmask_b32_e64 v220, v10, v12, s[96:97]
	v_mul_f32_e32 v216, v216, v234
	v_mul_f32_e32 v220, v220, v235
	s_nop 0
	v_readlane_b32 s64, v216, 0
	v_readlane_b32 s65, v216, 32
	v_readlane_b32 s66, v216, 16
	v_readlane_b32 s67, v216, 48
	v_readlane_b32 s68, v220, 0
	v_readlane_b32 s69, v220, 32
	v_readlane_b32 s70, v220, 16
	v_readlane_b32 s71, v220, 48
	s_waitcnt vmcnt(28)
	v_cvt_scalef32_pk_f32_fp4 v[160:161], v176, 1.0
	v_cvt_scalef32_pk_f32_fp4 v[162:163], v176, 1.0 op_sel:[1,0,0]
	v_cvt_scalef32_pk_f32_fp4 v[18:19], v176, 1.0 op_sel:[0,1,0]
	v_pk_fma_f32 v[32:33], v[160:161], s[64:65], v[32:33] op_sel_hi:[1,0,1]
	v_cvt_scalef32_pk_f32_fp4 v[20:21], v176, 1.0 op_sel:[1,1,0]
	v_pk_fma_f32 v[34:35], v[162:163], s[64:65], v[34:35] op_sel_hi:[1,0,1]
	v_cvt_scalef32_pk_f32_fp4 v[22:23], v177, 1.0
	v_pk_fma_f32 v[36:37], v[18:19], s[64:65], v[36:37] op_sel_hi:[1,0,1]
	v_cvt_scalef32_pk_f32_fp4 v[30:31], v177, 1.0 op_sel:[1,0,0]
	v_pk_fma_f32 v[38:39], v[20:21], s[64:65], v[38:39] op_sel_hi:[1,0,1]
	v_cvt_scalef32_pk_f32_fp4 v[2:3], v177, 1.0 op_sel:[0,1,0]
	v_pk_fma_f32 v[40:41], v[22:23], s[64:65], v[40:41] op_sel_hi:[1,0,1]
	v_cvt_scalef32_pk_f32_fp4 v[6:7], v177, 1.0 op_sel:[1,1,0]
	v_pk_fma_f32 v[42:43], v[30:31], s[64:65], v[42:43] op_sel_hi:[1,0,1]
	v_cvt_scalef32_pk_f32_fp4 v[160:161], v178, 1.0
	v_pk_fma_f32 v[44:45], v[2:3], s[64:65], v[44:45] op_sel_hi:[1,0,1]
	v_cvt_scalef32_pk_f32_fp4 v[162:163], v178, 1.0 op_sel:[1,0,0]
	v_pk_fma_f32 v[46:47], v[6:7], s[64:65], v[46:47] op_sel_hi:[1,0,1]
	v_cvt_scalef32_pk_f32_fp4 v[18:19], v178, 1.0 op_sel:[0,1,0]
	v_pk_fma_f32 v[48:49], v[160:161], s[64:65], v[48:49] op_sel_hi:[1,0,1]
	v_cvt_scalef32_pk_f32_fp4 v[20:21], v178, 1.0 op_sel:[1,1,0]
	v_pk_fma_f32 v[50:51], v[162:163], s[64:65], v[50:51] op_sel_hi:[1,0,1]
	v_cvt_scalef32_pk_f32_fp4 v[22:23], v179, 1.0
	v_pk_fma_f32 v[52:53], v[18:19], s[64:65], v[52:53] op_sel_hi:[1,0,1]
	v_cvt_scalef32_pk_f32_fp4 v[30:31], v179, 1.0 op_sel:[1,0,0]
	v_pk_fma_f32 v[54:55], v[20:21], s[64:65], v[54:55] op_sel_hi:[1,0,1]
	v_cvt_scalef32_pk_f32_fp4 v[2:3], v179, 1.0 op_sel:[0,1,0]
	v_pk_fma_f32 v[56:57], v[22:23], s[64:65], v[56:57] op_sel_hi:[1,0,1]
	v_cvt_scalef32_pk_f32_fp4 v[6:7], v179, 1.0 op_sel:[1,1,0]
	v_pk_fma_f32 v[58:59], v[30:31], s[64:65], v[58:59] op_sel_hi:[1,0,1]
	v_pk_fma_f32 v[60:61], v[2:3], s[64:65], v[60:61] op_sel_hi:[1,0,1]
	v_pk_fma_f32 v[62:63], v[6:7], s[64:65], v[62:63] op_sel_hi:[1,0,1]
	s_waitcnt vmcnt(24)
	v_cvt_scalef32_pk_f32_fp4 v[160:161], v180, 1.0
	v_cvt_scalef32_pk_f32_fp4 v[162:163], v180, 1.0 op_sel:[1,0,0]
	v_cvt_scalef32_pk_f32_fp4 v[18:19], v180, 1.0 op_sel:[0,1,0]
	v_pk_fma_f32 v[32:33], v[160:161], s[64:65], v[32:33] op_sel:[0,1,0] op_sel_hi:[1,1,1]
	v_cvt_scalef32_pk_f32_fp4 v[20:21], v180, 1.0 op_sel:[1,1,0]
	v_pk_fma_f32 v[34:35], v[162:163], s[64:65], v[34:35] op_sel:[0,1,0] op_sel_hi:[1,1,1]
	v_cvt_scalef32_pk_f32_fp4 v[22:23], v181, 1.0
	v_pk_fma_f32 v[36:37], v[18:19], s[64:65], v[36:37] op_sel:[0,1,0] op_sel_hi:[1,1,1]
	v_cvt_scalef32_pk_f32_fp4 v[30:31], v181, 1.0 op_sel:[1,0,0]
	v_pk_fma_f32 v[38:39], v[20:21], s[64:65], v[38:39] op_sel:[0,1,0] op_sel_hi:[1,1,1]
	v_cvt_scalef32_pk_f32_fp4 v[2:3], v181, 1.0 op_sel:[0,1,0]
	v_pk_fma_f32 v[40:41], v[22:23], s[64:65], v[40:41] op_sel:[0,1,0] op_sel_hi:[1,1,1]
	v_cvt_scalef32_pk_f32_fp4 v[6:7], v181, 1.0 op_sel:[1,1,0]
	v_pk_fma_f32 v[42:43], v[30:31], s[64:65], v[42:43] op_sel:[0,1,0] op_sel_hi:[1,1,1]
	v_cvt_scalef32_pk_f32_fp4 v[160:161], v182, 1.0
	v_pk_fma_f32 v[44:45], v[2:3], s[64:65], v[44:45] op_sel:[0,1,0] op_sel_hi:[1,1,1]
	v_cvt_scalef32_pk_f32_fp4 v[162:163], v182, 1.0 op_sel:[1,0,0]
	v_pk_fma_f32 v[46:47], v[6:7], s[64:65], v[46:47] op_sel:[0,1,0] op_sel_hi:[1,1,1]
	v_cvt_scalef32_pk_f32_fp4 v[18:19], v182, 1.0 op_sel:[0,1,0]
	v_pk_fma_f32 v[48:49], v[160:161], s[64:65], v[48:49] op_sel:[0,1,0] op_sel_hi:[1,1,1]
	v_cvt_scalef32_pk_f32_fp4 v[20:21], v182, 1.0 op_sel:[1,1,0]
	v_pk_fma_f32 v[50:51], v[162:163], s[64:65], v[50:51] op_sel:[0,1,0] op_sel_hi:[1,1,1]
	v_cvt_scalef32_pk_f32_fp4 v[22:23], v183, 1.0
	v_pk_fma_f32 v[52:53], v[18:19], s[64:65], v[52:53] op_sel:[0,1,0] op_sel_hi:[1,1,1]
	v_cvt_scalef32_pk_f32_fp4 v[30:31], v183, 1.0 op_sel:[1,0,0]
	v_pk_fma_f32 v[54:55], v[20:21], s[64:65], v[54:55] op_sel:[0,1,0] op_sel_hi:[1,1,1]
	v_cvt_scalef32_pk_f32_fp4 v[2:3], v183, 1.0 op_sel:[0,1,0]
	v_pk_fma_f32 v[56:57], v[22:23], s[64:65], v[56:57] op_sel:[0,1,0] op_sel_hi:[1,1,1]
	v_cvt_scalef32_pk_f32_fp4 v[6:7], v183, 1.0 op_sel:[1,1,0]
	v_pk_fma_f32 v[58:59], v[30:31], s[64:65], v[58:59] op_sel:[0,1,0] op_sel_hi:[1,1,1]
	v_pk_fma_f32 v[60:61], v[2:3], s[64:65], v[60:61] op_sel:[0,1,0] op_sel_hi:[1,1,1]
	v_pk_fma_f32 v[62:63], v[6:7], s[64:65], v[62:63] op_sel:[0,1,0] op_sel_hi:[1,1,1]
	s_waitcnt vmcnt(20)
	v_cvt_scalef32_pk_f32_fp4 v[160:161], v184, 1.0
	v_cvt_scalef32_pk_f32_fp4 v[162:163], v184, 1.0 op_sel:[1,0,0]
	v_cvt_scalef32_pk_f32_fp4 v[18:19], v184, 1.0 op_sel:[0,1,0]
	v_pk_fma_f32 v[32:33], v[160:161], s[66:67], v[32:33] op_sel_hi:[1,0,1]
	v_cvt_scalef32_pk_f32_fp4 v[20:21], v184, 1.0 op_sel:[1,1,0]
	v_pk_fma_f32 v[34:35], v[162:163], s[66:67], v[34:35] op_sel_hi:[1,0,1]
	v_cvt_scalef32_pk_f32_fp4 v[22:23], v185, 1.0
	v_pk_fma_f32 v[36:37], v[18:19], s[66:67], v[36:37] op_sel_hi:[1,0,1]
	v_cvt_scalef32_pk_f32_fp4 v[30:31], v185, 1.0 op_sel:[1,0,0]
	v_pk_fma_f32 v[38:39], v[20:21], s[66:67], v[38:39] op_sel_hi:[1,0,1]
	v_cvt_scalef32_pk_f32_fp4 v[2:3], v185, 1.0 op_sel:[0,1,0]
	v_pk_fma_f32 v[40:41], v[22:23], s[66:67], v[40:41] op_sel_hi:[1,0,1]
	v_cvt_scalef32_pk_f32_fp4 v[6:7], v185, 1.0 op_sel:[1,1,0]
	v_pk_fma_f32 v[42:43], v[30:31], s[66:67], v[42:43] op_sel_hi:[1,0,1]
	v_cvt_scalef32_pk_f32_fp4 v[160:161], v186, 1.0
	v_pk_fma_f32 v[44:45], v[2:3], s[66:67], v[44:45] op_sel_hi:[1,0,1]
	v_cvt_scalef32_pk_f32_fp4 v[162:163], v186, 1.0 op_sel:[1,0,0]
	v_pk_fma_f32 v[46:47], v[6:7], s[66:67], v[46:47] op_sel_hi:[1,0,1]
	v_cvt_scalef32_pk_f32_fp4 v[18:19], v186, 1.0 op_sel:[0,1,0]
	v_pk_fma_f32 v[48:49], v[160:161], s[66:67], v[48:49] op_sel_hi:[1,0,1]
	v_cvt_scalef32_pk_f32_fp4 v[20:21], v186, 1.0 op_sel:[1,1,0]
	v_pk_fma_f32 v[50:51], v[162:163], s[66:67], v[50:51] op_sel_hi:[1,0,1]
	v_cvt_scalef32_pk_f32_fp4 v[22:23], v187, 1.0
	v_pk_fma_f32 v[52:53], v[18:19], s[66:67], v[52:53] op_sel_hi:[1,0,1]
	v_cvt_scalef32_pk_f32_fp4 v[30:31], v187, 1.0 op_sel:[1,0,0]
	v_pk_fma_f32 v[54:55], v[20:21], s[66:67], v[54:55] op_sel_hi:[1,0,1]
	v_cvt_scalef32_pk_f32_fp4 v[2:3], v187, 1.0 op_sel:[0,1,0]
	v_pk_fma_f32 v[56:57], v[22:23], s[66:67], v[56:57] op_sel_hi:[1,0,1]
	v_cvt_scalef32_pk_f32_fp4 v[6:7], v187, 1.0 op_sel:[1,1,0]
	v_pk_fma_f32 v[58:59], v[30:31], s[66:67], v[58:59] op_sel_hi:[1,0,1]
	v_pk_fma_f32 v[60:61], v[2:3], s[66:67], v[60:61] op_sel_hi:[1,0,1]
	v_pk_fma_f32 v[62:63], v[6:7], s[66:67], v[62:63] op_sel_hi:[1,0,1]
	s_waitcnt vmcnt(16)
	v_cvt_scalef32_pk_f32_fp4 v[160:161], v188, 1.0
	v_cvt_scalef32_pk_f32_fp4 v[162:163], v188, 1.0 op_sel:[1,0,0]
	v_cvt_scalef32_pk_f32_fp4 v[18:19], v188, 1.0 op_sel:[0,1,0]
	v_pk_fma_f32 v[32:33], v[160:161], s[66:67], v[32:33] op_sel:[0,1,0] op_sel_hi:[1,1,1]
	v_cvt_scalef32_pk_f32_fp4 v[20:21], v188, 1.0 op_sel:[1,1,0]
	v_pk_fma_f32 v[34:35], v[162:163], s[66:67], v[34:35] op_sel:[0,1,0] op_sel_hi:[1,1,1]
	v_cvt_scalef32_pk_f32_fp4 v[22:23], v189, 1.0
	v_pk_fma_f32 v[36:37], v[18:19], s[66:67], v[36:37] op_sel:[0,1,0] op_sel_hi:[1,1,1]
	v_cvt_scalef32_pk_f32_fp4 v[30:31], v189, 1.0 op_sel:[1,0,0]
	v_pk_fma_f32 v[38:39], v[20:21], s[66:67], v[38:39] op_sel:[0,1,0] op_sel_hi:[1,1,1]
	v_cvt_scalef32_pk_f32_fp4 v[2:3], v189, 1.0 op_sel:[0,1,0]
	v_pk_fma_f32 v[40:41], v[22:23], s[66:67], v[40:41] op_sel:[0,1,0] op_sel_hi:[1,1,1]
	v_cvt_scalef32_pk_f32_fp4 v[6:7], v189, 1.0 op_sel:[1,1,0]
	v_pk_fma_f32 v[42:43], v[30:31], s[66:67], v[42:43] op_sel:[0,1,0] op_sel_hi:[1,1,1]
	v_cvt_scalef32_pk_f32_fp4 v[160:161], v190, 1.0
	v_pk_fma_f32 v[44:45], v[2:3], s[66:67], v[44:45] op_sel:[0,1,0] op_sel_hi:[1,1,1]
	v_cvt_scalef32_pk_f32_fp4 v[162:163], v190, 1.0 op_sel:[1,0,0]
	v_pk_fma_f32 v[46:47], v[6:7], s[66:67], v[46:47] op_sel:[0,1,0] op_sel_hi:[1,1,1]
	v_cvt_scalef32_pk_f32_fp4 v[18:19], v190, 1.0 op_sel:[0,1,0]
	v_pk_fma_f32 v[48:49], v[160:161], s[66:67], v[48:49] op_sel:[0,1,0] op_sel_hi:[1,1,1]
	v_cvt_scalef32_pk_f32_fp4 v[20:21], v190, 1.0 op_sel:[1,1,0]
	v_pk_fma_f32 v[50:51], v[162:163], s[66:67], v[50:51] op_sel:[0,1,0] op_sel_hi:[1,1,1]
	v_cvt_scalef32_pk_f32_fp4 v[22:23], v191, 1.0
	v_pk_fma_f32 v[52:53], v[18:19], s[66:67], v[52:53] op_sel:[0,1,0] op_sel_hi:[1,1,1]
	v_cvt_scalef32_pk_f32_fp4 v[30:31], v191, 1.0 op_sel:[1,0,0]
	v_pk_fma_f32 v[54:55], v[20:21], s[66:67], v[54:55] op_sel:[0,1,0] op_sel_hi:[1,1,1]
	v_cvt_scalef32_pk_f32_fp4 v[2:3], v191, 1.0 op_sel:[0,1,0]
	v_pk_fma_f32 v[56:57], v[22:23], s[66:67], v[56:57] op_sel:[0,1,0] op_sel_hi:[1,1,1]
	v_cvt_scalef32_pk_f32_fp4 v[6:7], v191, 1.0 op_sel:[1,1,0]
	v_pk_fma_f32 v[58:59], v[30:31], s[66:67], v[58:59] op_sel:[0,1,0] op_sel_hi:[1,1,1]
	v_pk_fma_f32 v[60:61], v[2:3], s[66:67], v[60:61] op_sel:[0,1,0] op_sel_hi:[1,1,1]
	v_pk_fma_f32 v[62:63], v[6:7], s[66:67], v[62:63] op_sel:[0,1,0] op_sel_hi:[1,1,1]
	s_waitcnt vmcnt(12)
	v_cvt_scalef32_pk_f32_fp4 v[160:161], v192, 1.0
	v_cvt_scalef32_pk_f32_fp4 v[162:163], v192, 1.0 op_sel:[1,0,0]
	v_cvt_scalef32_pk_f32_fp4 v[18:19], v192, 1.0 op_sel:[0,1,0]
	v_pk_fma_f32 v[32:33], v[160:161], s[68:69], v[32:33] op_sel_hi:[1,0,1]
	v_cvt_scalef32_pk_f32_fp4 v[20:21], v192, 1.0 op_sel:[1,1,0]
	v_pk_fma_f32 v[34:35], v[162:163], s[68:69], v[34:35] op_sel_hi:[1,0,1]
	v_cvt_scalef32_pk_f32_fp4 v[22:23], v193, 1.0
	v_pk_fma_f32 v[36:37], v[18:19], s[68:69], v[36:37] op_sel_hi:[1,0,1]
	v_cvt_scalef32_pk_f32_fp4 v[30:31], v193, 1.0 op_sel:[1,0,0]
	v_pk_fma_f32 v[38:39], v[20:21], s[68:69], v[38:39] op_sel_hi:[1,0,1]
	v_cvt_scalef32_pk_f32_fp4 v[2:3], v193, 1.0 op_sel:[0,1,0]
	v_pk_fma_f32 v[40:41], v[22:23], s[68:69], v[40:41] op_sel_hi:[1,0,1]
	v_cvt_scalef32_pk_f32_fp4 v[6:7], v193, 1.0 op_sel:[1,1,0]
	v_pk_fma_f32 v[42:43], v[30:31], s[68:69], v[42:43] op_sel_hi:[1,0,1]
	v_cvt_scalef32_pk_f32_fp4 v[160:161], v194, 1.0
	v_pk_fma_f32 v[44:45], v[2:3], s[68:69], v[44:45] op_sel_hi:[1,0,1]
	v_cvt_scalef32_pk_f32_fp4 v[162:163], v194, 1.0 op_sel:[1,0,0]
	v_pk_fma_f32 v[46:47], v[6:7], s[68:69], v[46:47] op_sel_hi:[1,0,1]
	v_cvt_scalef32_pk_f32_fp4 v[18:19], v194, 1.0 op_sel:[0,1,0]
	v_pk_fma_f32 v[48:49], v[160:161], s[68:69], v[48:49] op_sel_hi:[1,0,1]
	v_cvt_scalef32_pk_f32_fp4 v[20:21], v194, 1.0 op_sel:[1,1,0]
	v_pk_fma_f32 v[50:51], v[162:163], s[68:69], v[50:51] op_sel_hi:[1,0,1]
	v_cvt_scalef32_pk_f32_fp4 v[22:23], v195, 1.0
	v_pk_fma_f32 v[52:53], v[18:19], s[68:69], v[52:53] op_sel_hi:[1,0,1]
	v_cvt_scalef32_pk_f32_fp4 v[30:31], v195, 1.0 op_sel:[1,0,0]
	v_pk_fma_f32 v[54:55], v[20:21], s[68:69], v[54:55] op_sel_hi:[1,0,1]
	v_cvt_scalef32_pk_f32_fp4 v[2:3], v195, 1.0 op_sel:[0,1,0]
	v_pk_fma_f32 v[56:57], v[22:23], s[68:69], v[56:57] op_sel_hi:[1,0,1]
	v_cvt_scalef32_pk_f32_fp4 v[6:7], v195, 1.0 op_sel:[1,1,0]
	v_pk_fma_f32 v[58:59], v[30:31], s[68:69], v[58:59] op_sel_hi:[1,0,1]
	v_pk_fma_f32 v[60:61], v[2:3], s[68:69], v[60:61] op_sel_hi:[1,0,1]
	v_pk_fma_f32 v[62:63], v[6:7], s[68:69], v[62:63] op_sel_hi:[1,0,1]
	s_waitcnt vmcnt(8)
	v_cvt_scalef32_pk_f32_fp4 v[160:161], v196, 1.0
	v_cvt_scalef32_pk_f32_fp4 v[162:163], v196, 1.0 op_sel:[1,0,0]
	v_cvt_scalef32_pk_f32_fp4 v[18:19], v196, 1.0 op_sel:[0,1,0]
	v_pk_fma_f32 v[32:33], v[160:161], s[68:69], v[32:33] op_sel:[0,1,0] op_sel_hi:[1,1,1]
	v_cvt_scalef32_pk_f32_fp4 v[20:21], v196, 1.0 op_sel:[1,1,0]
	v_pk_fma_f32 v[34:35], v[162:163], s[68:69], v[34:35] op_sel:[0,1,0] op_sel_hi:[1,1,1]
	v_cvt_scalef32_pk_f32_fp4 v[22:23], v197, 1.0
	v_pk_fma_f32 v[36:37], v[18:19], s[68:69], v[36:37] op_sel:[0,1,0] op_sel_hi:[1,1,1]
	v_cvt_scalef32_pk_f32_fp4 v[30:31], v197, 1.0 op_sel:[1,0,0]
	v_pk_fma_f32 v[38:39], v[20:21], s[68:69], v[38:39] op_sel:[0,1,0] op_sel_hi:[1,1,1]
	v_cvt_scalef32_pk_f32_fp4 v[2:3], v197, 1.0 op_sel:[0,1,0]
	v_pk_fma_f32 v[40:41], v[22:23], s[68:69], v[40:41] op_sel:[0,1,0] op_sel_hi:[1,1,1]
	v_cvt_scalef32_pk_f32_fp4 v[6:7], v197, 1.0 op_sel:[1,1,0]
	v_pk_fma_f32 v[42:43], v[30:31], s[68:69], v[42:43] op_sel:[0,1,0] op_sel_hi:[1,1,1]
	v_cvt_scalef32_pk_f32_fp4 v[160:161], v198, 1.0
	v_pk_fma_f32 v[44:45], v[2:3], s[68:69], v[44:45] op_sel:[0,1,0] op_sel_hi:[1,1,1]
	v_cvt_scalef32_pk_f32_fp4 v[162:163], v198, 1.0 op_sel:[1,0,0]
	v_pk_fma_f32 v[46:47], v[6:7], s[68:69], v[46:47] op_sel:[0,1,0] op_sel_hi:[1,1,1]
	v_cvt_scalef32_pk_f32_fp4 v[18:19], v198, 1.0 op_sel:[0,1,0]
	v_pk_fma_f32 v[48:49], v[160:161], s[68:69], v[48:49] op_sel:[0,1,0] op_sel_hi:[1,1,1]
	v_cvt_scalef32_pk_f32_fp4 v[20:21], v198, 1.0 op_sel:[1,1,0]
	v_pk_fma_f32 v[50:51], v[162:163], s[68:69], v[50:51] op_sel:[0,1,0] op_sel_hi:[1,1,1]
	v_cvt_scalef32_pk_f32_fp4 v[22:23], v199, 1.0
	v_pk_fma_f32 v[52:53], v[18:19], s[68:69], v[52:53] op_sel:[0,1,0] op_sel_hi:[1,1,1]
	v_cvt_scalef32_pk_f32_fp4 v[30:31], v199, 1.0 op_sel:[1,0,0]
	v_pk_fma_f32 v[54:55], v[20:21], s[68:69], v[54:55] op_sel:[0,1,0] op_sel_hi:[1,1,1]
	v_cvt_scalef32_pk_f32_fp4 v[2:3], v199, 1.0 op_sel:[0,1,0]
	v_pk_fma_f32 v[56:57], v[22:23], s[68:69], v[56:57] op_sel:[0,1,0] op_sel_hi:[1,1,1]
	v_cvt_scalef32_pk_f32_fp4 v[6:7], v199, 1.0 op_sel:[1,1,0]
	v_pk_fma_f32 v[58:59], v[30:31], s[68:69], v[58:59] op_sel:[0,1,0] op_sel_hi:[1,1,1]
	v_pk_fma_f32 v[60:61], v[2:3], s[68:69], v[60:61] op_sel:[0,1,0] op_sel_hi:[1,1,1]
	v_pk_fma_f32 v[62:63], v[6:7], s[68:69], v[62:63] op_sel:[0,1,0] op_sel_hi:[1,1,1]
	s_waitcnt vmcnt(4)
	v_cvt_scalef32_pk_f32_fp4 v[160:161], v200, 1.0
	v_cvt_scalef32_pk_f32_fp4 v[162:163], v200, 1.0 op_sel:[1,0,0]
	v_cvt_scalef32_pk_f32_fp4 v[18:19], v200, 1.0 op_sel:[0,1,0]
	v_pk_fma_f32 v[32:33], v[160:161], s[70:71], v[32:33] op_sel_hi:[1,0,1]
	v_cvt_scalef32_pk_f32_fp4 v[20:21], v200, 1.0 op_sel:[1,1,0]
	v_pk_fma_f32 v[34:35], v[162:163], s[70:71], v[34:35] op_sel_hi:[1,0,1]
	v_cvt_scalef32_pk_f32_fp4 v[22:23], v201, 1.0
	v_pk_fma_f32 v[36:37], v[18:19], s[70:71], v[36:37] op_sel_hi:[1,0,1]
	v_cvt_scalef32_pk_f32_fp4 v[30:31], v201, 1.0 op_sel:[1,0,0]
	v_pk_fma_f32 v[38:39], v[20:21], s[70:71], v[38:39] op_sel_hi:[1,0,1]
	v_cvt_scalef32_pk_f32_fp4 v[2:3], v201, 1.0 op_sel:[0,1,0]
	v_pk_fma_f32 v[40:41], v[22:23], s[70:71], v[40:41] op_sel_hi:[1,0,1]
	v_cvt_scalef32_pk_f32_fp4 v[6:7], v201, 1.0 op_sel:[1,1,0]
	v_pk_fma_f32 v[42:43], v[30:31], s[70:71], v[42:43] op_sel_hi:[1,0,1]
	v_cvt_scalef32_pk_f32_fp4 v[160:161], v202, 1.0
	v_pk_fma_f32 v[44:45], v[2:3], s[70:71], v[44:45] op_sel_hi:[1,0,1]
	v_cvt_scalef32_pk_f32_fp4 v[162:163], v202, 1.0 op_sel:[1,0,0]
	v_pk_fma_f32 v[46:47], v[6:7], s[70:71], v[46:47] op_sel_hi:[1,0,1]
	v_cvt_scalef32_pk_f32_fp4 v[18:19], v202, 1.0 op_sel:[0,1,0]
	v_pk_fma_f32 v[48:49], v[160:161], s[70:71], v[48:49] op_sel_hi:[1,0,1]
	v_cvt_scalef32_pk_f32_fp4 v[20:21], v202, 1.0 op_sel:[1,1,0]
	v_pk_fma_f32 v[50:51], v[162:163], s[70:71], v[50:51] op_sel_hi:[1,0,1]
	v_cvt_scalef32_pk_f32_fp4 v[22:23], v203, 1.0
	v_pk_fma_f32 v[52:53], v[18:19], s[70:71], v[52:53] op_sel_hi:[1,0,1]
	v_cvt_scalef32_pk_f32_fp4 v[30:31], v203, 1.0 op_sel:[1,0,0]
	v_pk_fma_f32 v[54:55], v[20:21], s[70:71], v[54:55] op_sel_hi:[1,0,1]
	v_cvt_scalef32_pk_f32_fp4 v[2:3], v203, 1.0 op_sel:[0,1,0]
	v_pk_fma_f32 v[56:57], v[22:23], s[70:71], v[56:57] op_sel_hi:[1,0,1]
	v_cvt_scalef32_pk_f32_fp4 v[6:7], v203, 1.0 op_sel:[1,1,0]
	v_pk_fma_f32 v[58:59], v[30:31], s[70:71], v[58:59] op_sel_hi:[1,0,1]
	v_pk_fma_f32 v[60:61], v[2:3], s[70:71], v[60:61] op_sel_hi:[1,0,1]
	v_pk_fma_f32 v[62:63], v[6:7], s[70:71], v[62:63] op_sel_hi:[1,0,1]
	s_waitcnt vmcnt(0)
	v_cvt_scalef32_pk_f32_fp4 v[160:161], v240, 1.0
	v_cvt_scalef32_pk_f32_fp4 v[162:163], v240, 1.0 op_sel:[1,0,0]
	v_cvt_scalef32_pk_f32_fp4 v[18:19], v240, 1.0 op_sel:[0,1,0]
	v_pk_fma_f32 v[32:33], v[160:161], s[70:71], v[32:33] op_sel:[0,1,0] op_sel_hi:[1,1,1]
	v_cvt_scalef32_pk_f32_fp4 v[20:21], v240, 1.0 op_sel:[1,1,0]
	v_pk_fma_f32 v[34:35], v[162:163], s[70:71], v[34:35] op_sel:[0,1,0] op_sel_hi:[1,1,1]
	v_cvt_scalef32_pk_f32_fp4 v[22:23], v241, 1.0
	v_pk_fma_f32 v[36:37], v[18:19], s[70:71], v[36:37] op_sel:[0,1,0] op_sel_hi:[1,1,1]
	v_cvt_scalef32_pk_f32_fp4 v[30:31], v241, 1.0 op_sel:[1,0,0]
	v_pk_fma_f32 v[38:39], v[20:21], s[70:71], v[38:39] op_sel:[0,1,0] op_sel_hi:[1,1,1]
	v_cvt_scalef32_pk_f32_fp4 v[2:3], v241, 1.0 op_sel:[0,1,0]
	v_pk_fma_f32 v[40:41], v[22:23], s[70:71], v[40:41] op_sel:[0,1,0] op_sel_hi:[1,1,1]
	v_cvt_scalef32_pk_f32_fp4 v[6:7], v241, 1.0 op_sel:[1,1,0]
	v_pk_fma_f32 v[42:43], v[30:31], s[70:71], v[42:43] op_sel:[0,1,0] op_sel_hi:[1,1,1]
	v_cvt_scalef32_pk_f32_fp4 v[160:161], v242, 1.0
	v_pk_fma_f32 v[44:45], v[2:3], s[70:71], v[44:45] op_sel:[0,1,0] op_sel_hi:[1,1,1]
	v_cvt_scalef32_pk_f32_fp4 v[162:163], v242, 1.0 op_sel:[1,0,0]
	v_pk_fma_f32 v[46:47], v[6:7], s[70:71], v[46:47] op_sel:[0,1,0] op_sel_hi:[1,1,1]
	v_cvt_scalef32_pk_f32_fp4 v[18:19], v242, 1.0 op_sel:[0,1,0]
	v_pk_fma_f32 v[48:49], v[160:161], s[70:71], v[48:49] op_sel:[0,1,0] op_sel_hi:[1,1,1]
	v_cvt_scalef32_pk_f32_fp4 v[20:21], v242, 1.0 op_sel:[1,1,0]
	v_pk_fma_f32 v[50:51], v[162:163], s[70:71], v[50:51] op_sel:[0,1,0] op_sel_hi:[1,1,1]
	v_cvt_scalef32_pk_f32_fp4 v[22:23], v243, 1.0
	v_pk_fma_f32 v[52:53], v[18:19], s[70:71], v[52:53] op_sel:[0,1,0] op_sel_hi:[1,1,1]
	v_cvt_scalef32_pk_f32_fp4 v[30:31], v243, 1.0 op_sel:[1,0,0]
	v_pk_fma_f32 v[54:55], v[20:21], s[70:71], v[54:55] op_sel:[0,1,0] op_sel_hi:[1,1,1]
	v_cvt_scalef32_pk_f32_fp4 v[2:3], v243, 1.0 op_sel:[0,1,0]
	v_pk_fma_f32 v[56:57], v[22:23], s[70:71], v[56:57] op_sel:[0,1,0] op_sel_hi:[1,1,1]
	v_cvt_scalef32_pk_f32_fp4 v[6:7], v243, 1.0 op_sel:[1,1,0]
	v_pk_fma_f32 v[58:59], v[30:31], s[70:71], v[58:59] op_sel:[0,1,0] op_sel_hi:[1,1,1]
	v_pk_fma_f32 v[60:61], v[2:3], s[70:71], v[60:61] op_sel:[0,1,0] op_sel_hi:[1,1,1]
	v_pk_fma_f32 v[62:63], v[6:7], s[70:71], v[62:63] op_sel:[0,1,0] op_sel_hi:[1,1,1]
	v_lshlrev_b32_e32 v2, 4, v0
	s_lshl_b32 s96, s91, 13
	v_add_u32_e32 v3, 0x3000, v2
	v_add_u32_e32 v3, s96, v3
	ds_write_b128 v3, v[32:35] offset:0
	ds_write_b128 v3, v[36:39] offset:1024
	ds_write_b128 v3, v[40:43] offset:2048
	ds_write_b128 v3, v[44:47] offset:3072
	ds_write_b128 v3, v[48:51] offset:4096
	ds_write_b128 v3, v[52:55] offset:5120
	ds_write_b128 v3, v[56:59] offset:6144
	ds_write_b128 v3, v[60:63] offset:7168
	s_waitcnt lgkmcnt(0)
	s_barrier
	s_lshl_b32 s96, s91, 11
	v_add_u32_e32 v3, 0x3000, v2
	v_add_u32_e32 v3, s96, v3
	ds_read_b128 v[64:67], v3 offset:0
	ds_read_b128 v[68:71], v3 offset:1024
	ds_read_b128 v[72:75], v3 offset:8192
	ds_read_b128 v[76:79], v3 offset:9216
	ds_read_b128 v[80:83], v3 offset:16384
	ds_read_b128 v[84:87], v3 offset:17408
	ds_read_b128 v[88:91], v3 offset:24576
	ds_read_b128 v[92:95], v3 offset:25600
	v_lshlrev_b32_e32 v1, 13, v4
	v_lshl_add_u32 v1, v0, 6, v1
	s_lshr_b32 s96, s91, 1
	s_lshl_b32 s96, s96, 12
	s_and_b32 s97, s91, 1
	s_lshl_b32 s97, s97, 5
	s_add_u32 s96, s96, s97
	v_add_u32_e32 v1, s96, v1
	global_load_dwordx4 v[96:99], v1, s[92:93]
	global_load_dwordx4 v[100:103], v1, s[92:93] offset:16
	s_waitcnt lgkmcnt(0)
	v_pk_add_f32 v[64:65], v[64:65], v[72:73]
	v_pk_add_f32 v[66:67], v[66:67], v[74:75]
	v_pk_add_f32 v[68:69], v[68:69], v[76:77]
	v_pk_add_f32 v[70:71], v[70:71], v[78:79]
	v_pk_add_f32 v[64:65], v[64:65], v[80:81]
	v_pk_add_f32 v[66:67], v[66:67], v[82:83]
	v_pk_add_f32 v[68:69], v[68:69], v[84:85]
	v_pk_add_f32 v[70:71], v[70:71], v[86:87]
	v_pk_add_f32 v[64:65], v[64:65], v[88:89]
	v_pk_add_f32 v[66:67], v[66:67], v[90:91]
	v_pk_add_f32 v[68:69], v[68:69], v[92:93]
	v_pk_add_f32 v[70:71], v[70:71], v[94:95]
	s_waitcnt vmcnt(0)
	v_pk_add_f32 v[96:97], v[96:97], v[64:65]
	v_pk_add_f32 v[98:99], v[98:99], v[66:67]
	v_pk_add_f32 v[100:101], v[100:101], v[68:69]
	v_pk_add_f32 v[102:103], v[102:103], v[70:71]
	global_store_dwordx4 v1, v[96:99], s[92:93]
	global_store_dwordx4 v1, v[100:103], s[92:93] offset:16
.Lpb_skip:
	s_load_dwordx4 s[4:7], s[0:1], 0x110
	s_waitcnt lgkmcnt(0)
	s_cmp_lt_i32 s5, 10
	v_readlane_b32 s4, v244, 1
	v_readlane_b32 s5, v244, 2
	s_cselect_b64 s[2:3], -1, 0
	s_xor_b64 s[4:5], s[4:5], -1
	s_or_b64 s[2:3], s[2:3], s[4:5]
	s_and_b64 vcc, exec, s[2:3]
	s_cbranch_vccnz .LBB0_975
	s_waitcnt vmcnt(0)
	s_waitcnt vmcnt(63) expcnt(7) lgkmcnt(15)
	s_barrier
	s_and_saveexec_b64 s[2:3], s[56:57]
	s_cbranch_execz .LBB0_974
	v_readlane_b32 s18, v244, 0
	s_waitcnt vmcnt(0) expcnt(0) lgkmcnt(0)
	s_nop 0
	v_mov_b32_e32 v0, s18
	ds_read_b32 v2, v0
	ds_read_b32 v0, v0 offset:4
	s_waitcnt lgkmcnt(1)
	v_cmp_ne_u32_e32 vcc, 0, v2
	s_cbranch_vccnz .LBB0_945
	s_load_dwordx2 s[6:7], s[0:1], 0x120
	s_load_dword s5, s[0:1], 0x128
	s_add_u32 s0, s58, 0x1000
	s_addc_u32 s1, s59, 0
	s_add_u32 s4, s58, 0x1100
	s_waitcnt lgkmcnt(0)
	s_mul_i32 s16, s7, s6
	s_mul_i32 s16, s16, s5
	s_addc_u32 s5, s59, 0
	s_add_u32 s6, s58, 0x1200
	s_addc_u32 s7, s59, 0
	s_add_u32 s8, s58, 0x1300
	s_addc_u32 s9, s59, 0
	s_mov_b32 s17, 1
	v_mov_b32_e32 v16, 0
	s_branch .LBB0_935
